# counted lgkmcnt waits inside the 24 GEMM MFMA sections: each MFMA waits only for the LDS fragment reads it consumes
# speedup vs baseline: 1.0150x; 1.0112x over previous
; #define PG8_STAGE(bufoff, gbase, voff) do { _Pragma("unroll") for (int _i = 0; _i < 2; ++_i) \
;         __builtin_amdgcn_global_load_lds((const unsigned*)((const char*)(gbase) + (voff)[_i]), (LAS unsigned*)(lds + (bufoff) + ldsw + _i * 8192), 16, 0, 0); } while (0)
; #define PG8_LDA(dst, b, h) do { _Pragma("unroll") for (int m = 0; m < 4; ++m) _Pragma("unroll") for (int k = 0; k < 2; ++k) dst[m][k] = *(const LAS h8*)(lds + PG8_SA(b, h) + aoff + m * 2048 + k * 1024); } while (0)
; #define PG8_LDB(dst, b, h) do { _Pragma("unroll") for (int n = 0; n < 2; ++n) _Pragma("unroll") for (int k = 0; k < 2; ++k) dst[n][k] = *(const LAS h8*)(lds + PG8_SB(b, h) + boff + n * 2048 + k * 1024); } while (0)
; #define PG8_WAIT_L(n) asm volatile("s_waitcnt lgkmcnt(" #n ")" ::: "memory")
; #define PG8_BAR __builtin_amdgcn_s_barrier()
; #define PG8_SCHED __builtin_amdgcn_sched_barrier(0)
; template <class Epi>
; __device__ __forceinline__ void gemm_phase(LAS unsigned char* lds, const Gemm g, const StaticOrder& S, const Epi& E, const int tid) {
;     ...
;         for (int t = 0; t < nt; t += 2) {
;             const bool last = (t == nt - 2);
;             const char* a1 = cA + (size_t)(t + 1) * kstep;
;             const char* a2 = last ? nA : cA + (size_t)(t + 2) * kstep; const char* b2 = last ? nB : cB + (size_t)(t + 2) * kstep;
;             const char* a3 = a2 + kstep; const char* b3 = b2 + kstep;
;             if constexpr (Epi::HAS_MID) { if (t == (nt >> 1)) E.mid(acc, cur, wr, wc, fr, fq); }
;             PG8_LDB(B0, 0, 0); PG8_SCHED; PG8_LDA(At, 0, 0); PG8_STAGE(PG8_SA(1, 1), a1 + hstep, voffA);
;             PG8_WAIT_L(8); PG8_BAR; PG8_WAIT_L(0); PG8_MMA(0, 0, At, B0); PG8_BAR; PG8_SCHED;
;             PG8_LDB(B1, 0, 1); PG8_STAGE(PG8_SB(0, 0), b2, voffB);
;             PG8_BAR; PG8_WAIT_L(0); PG8_MMA(0, 1, At, B1); PG8_BAR;
;             PG8_LDA(At, 0, 1); PG8_STAGE(PG8_SA(0, 0), a2, voffA);
;             PG8_BAR; PG8_WAIT_L(0); PG8_MMA(1, 0, At, B0); PG8_BAR; PG8_SCHED;
.LBB0_332:
	s_add_u32 s18, s14, 0xfff80080
	s_addc_u32 s19, s15, -1
	s_add_i32 s55, 0, 0x10000
	v_add_u32_e32 v157, s55, v140
	ds_read_b128 v[144:147], v157
	ds_read_b128 v[162:165], v157 offset:1024
	ds_read_b128 v[166:169], v157 offset:2048
	ds_read_b128 v[170:173], v157 offset:3072
	s_cmp_eq_u32 s54, 28
	s_cselect_b32 s23, s9, s19
	s_cselect_b32 s22, s50, s18
	s_cselect_b32 s19, s1, s53
	s_cselect_b32 s18, s51, s52
	s_add_i32 m0, s39, 0xc000
	ds_read_b128 v[174:177], v143
	ds_read_b128 v[190:193], v143 offset:1024
	ds_read_b128 v[194:197], v143 offset:2048
	ds_read_b128 v[198:201], v143 offset:3072
	ds_read_b128 v[202:205], v143 offset:4096
	ds_read_b128 v[206:209], v143 offset:5120
	ds_read_b128 v[210:213], v143 offset:6144
	ds_read_b128 v[214:217], v143 offset:7168
	global_load_lds_dwordx4 v136, s[14:15]
	s_add_i32 m0, s39, 0xe000
	s_nop 0
	global_load_lds_dwordx4 v138, s[14:15]
	s_waitcnt lgkmcnt(8)
	s_barrier
	s_waitcnt lgkmcnt(7)
	v_mfma_f32_16x16x32_bf16 v[124:127], v[144:147], v[174:177], v[124:127]
	v_mfma_f32_16x16x32_bf16 v[128:131], v[166:169], v[174:177], v[128:131]
	s_waitcnt lgkmcnt(5)
	v_mfma_f32_16x16x32_bf16 v[108:111], v[144:147], v[194:197], v[108:111]
	v_mfma_f32_16x16x32_bf16 v[112:115], v[166:169], v[194:197], v[112:115]
	s_waitcnt lgkmcnt(3)
	v_mfma_f32_16x16x32_bf16 v[92:95], v[144:147], v[202:205], v[92:95]
	v_mfma_f32_16x16x32_bf16 v[96:99], v[166:169], v[202:205], v[96:99]
	s_waitcnt lgkmcnt(1)
	v_mfma_f32_16x16x32_bf16 v[76:79], v[144:147], v[210:213], v[76:79]
	v_mfma_f32_16x16x32_bf16 v[80:83], v[166:169], v[210:213], v[80:83]
	v_mfma_f32_16x16x32_bf16 v[124:127], v[162:165], v[190:193], v[124:127]
	v_mfma_f32_16x16x32_bf16 v[128:131], v[170:173], v[190:193], v[128:131]
	v_mfma_f32_16x16x32_bf16 v[108:111], v[162:165], v[198:201], v[108:111]
	v_mfma_f32_16x16x32_bf16 v[112:115], v[170:173], v[198:201], v[112:115]
	v_mfma_f32_16x16x32_bf16 v[92:95], v[162:165], v[206:209], v[92:95]
	v_mfma_f32_16x16x32_bf16 v[96:99], v[170:173], v[206:209], v[96:99]
	s_waitcnt lgkmcnt(0)
	v_mfma_f32_16x16x32_bf16 v[76:79], v[162:165], v[214:217], v[76:79]
	v_mfma_f32_16x16x32_bf16 v[80:83], v[170:173], v[214:217], v[80:83]
	s_barrier
	s_add_i32 s58, 0, 0x14000
	s_add_i32 s55, s55, s38
	v_add_u32_e32 v157, s58, v140
	v_lshl_add_u64 v[178:179], s[18:19], 0, v[2:3]
	s_mov_b32 m0, s55
	ds_read_b128 v[218:221], v157
	ds_read_b128 v[222:225], v157 offset:1024
	ds_read_b128 v[226:229], v157 offset:2048
	ds_read_b128 v[230:233], v157 offset:3072
	global_load_lds_dwordx4 v[178:179], off
	v_lshl_add_u64 v[234:235], s[18:19], 0, v[0:1]
	s_add_i32 m0, s55, 0x2000
	s_nop 0
	global_load_lds_dwordx4 v[234:235], off
	s_barrier
	s_waitcnt lgkmcnt(3)
	v_mfma_f32_16x16x32_bf16 v[116:119], v[218:221], v[174:177], v[116:119]
	s_waitcnt lgkmcnt(1)
	v_mfma_f32_16x16x32_bf16 v[120:123], v[226:229], v[174:177], v[120:123]
	v_mfma_f32_16x16x32_bf16 v[100:103], v[218:221], v[194:197], v[100:103]
	v_mfma_f32_16x16x32_bf16 v[104:107], v[226:229], v[194:197], v[104:107]
	v_mfma_f32_16x16x32_bf16 v[84:87], v[218:221], v[202:205], v[84:87]
	v_mfma_f32_16x16x32_bf16 v[88:91], v[226:229], v[202:205], v[88:91]
	v_mfma_f32_16x16x32_bf16 v[68:71], v[218:221], v[210:213], v[68:71]
	v_mfma_f32_16x16x32_bf16 v[72:75], v[226:229], v[210:213], v[72:75]
	v_mfma_f32_16x16x32_bf16 v[116:119], v[222:225], v[190:193], v[116:119]
	s_waitcnt lgkmcnt(0)
	v_mfma_f32_16x16x32_bf16 v[120:123], v[230:233], v[190:193], v[120:123]
	v_mfma_f32_16x16x32_bf16 v[100:103], v[222:225], v[198:201], v[100:103]
	v_mfma_f32_16x16x32_bf16 v[104:107], v[230:233], v[198:201], v[104:107]
	v_mfma_f32_16x16x32_bf16 v[84:87], v[222:225], v[206:209], v[84:87]
	v_mfma_f32_16x16x32_bf16 v[88:91], v[230:233], v[206:209], v[88:91]
	v_mfma_f32_16x16x32_bf16 v[68:71], v[222:225], v[214:217], v[68:71]
	v_mfma_f32_16x16x32_bf16 v[72:75], v[230:233], v[214:217], v[72:75]
	s_mov_b32 m0, s39
	v_lshl_add_u64 v[236:237], s[22:23], 0, v[134:135]
	s_barrier
	ds_read_b128 v[174:177], v143 offset:16384
	ds_read_b128 v[190:193], v143 offset:17408
	ds_read_b128 v[194:197], v143 offset:18432
	ds_read_b128 v[198:201], v143 offset:19456
	ds_read_b128 v[202:205], v143 offset:20480
	ds_read_b128 v[206:209], v143 offset:21504
	ds_read_b128 v[210:213], v143 offset:22528
	ds_read_b128 v[214:217], v143 offset:23552
	global_load_lds_dwordx4 v[236:237], off
	v_lshl_add_u64 v[238:239], s[22:23], 0, v[132:133]
	s_mov_b32 m0, s40
	s_nop 0
	global_load_lds_dwordx4 v[238:239], off
	s_barrier
	s_waitcnt lgkmcnt(7)
	v_mfma_f32_16x16x32_bf16 v[60:63], v[144:147], v[174:177], v[60:63]
	v_mfma_f32_16x16x32_bf16 v[64:67], v[166:169], v[174:177], v[64:67]
	s_waitcnt lgkmcnt(5)
	v_mfma_f32_16x16x32_bf16 v[44:47], v[144:147], v[194:197], v[44:47]
	v_mfma_f32_16x16x32_bf16 v[48:51], v[166:169], v[194:197], v[48:51]
	s_waitcnt lgkmcnt(3)
	v_mfma_f32_16x16x32_bf16 v[28:31], v[144:147], v[202:205], v[28:31]
	v_mfma_f32_16x16x32_bf16 v[32:35], v[166:169], v[202:205], v[32:35]
	s_waitcnt lgkmcnt(1)
	v_mfma_f32_16x16x32_bf16 v[12:15], v[144:147], v[210:213], v[12:15]
	v_mfma_f32_16x16x32_bf16 v[16:19], v[166:169], v[210:213], v[16:19]
	v_mfma_f32_16x16x32_bf16 v[60:63], v[162:165], v[190:193], v[60:63]
	v_mfma_f32_16x16x32_bf16 v[64:67], v[170:173], v[190:193], v[64:67]
	v_mfma_f32_16x16x32_bf16 v[44:47], v[162:165], v[198:201], v[44:47]
	v_mfma_f32_16x16x32_bf16 v[48:51], v[170:173], v[198:201], v[48:51]
	v_mfma_f32_16x16x32_bf16 v[28:31], v[162:165], v[206:209], v[28:31]
	v_mfma_f32_16x16x32_bf16 v[32:35], v[170:173], v[206:209], v[32:35]
	s_waitcnt lgkmcnt(0)
	v_mfma_f32_16x16x32_bf16 v[12:15], v[162:165], v[214:217], v[12:15]
	v_mfma_f32_16x16x32_bf16 v[16:19], v[170:173], v[214:217], v[16:19]
	s_barrier
; #define PG8_STAGE(bufoff, gbase, voff) do { _Pragma("unroll") for (int _i = 0; _i < 2; ++_i) \
;         __builtin_amdgcn_global_load_lds((const unsigned*)((const char*)(gbase) + (voff)[_i]), (LAS unsigned*)(lds + (bufoff) + ldsw + _i * 8192), 16, 0, 0); } while (0)
; #define PG8_LDA(dst, b, h) do { _Pragma("unroll") for (int m = 0; m < 4; ++m) _Pragma("unroll") for (int k = 0; k < 2; ++k) dst[m][k] = *(const LAS h8*)(lds + PG8_SA(b, h) + aoff + m * 2048 + k * 1024); } while (0)
; #define PG8_LDB(dst, b, h) do { _Pragma("unroll") for (int n = 0; n < 2; ++n) _Pragma("unroll") for (int k = 0; k < 2; ++k) dst[n][k] = *(const LAS h8*)(lds + PG8_SB(b, h) + boff + n * 2048 + k * 1024); } while (0)
; #define PG8_WAIT_V(n) asm volatile("s_waitcnt vmcnt(" #n ")" ::: "memory")
; #define PG8_WAIT_L(n) asm volatile("s_waitcnt lgkmcnt(" #n ")" ::: "memory")
; #define PG8_BAR __builtin_amdgcn_s_barrier()
; #define PG8_SCHED __builtin_amdgcn_sched_barrier(0)
; template <class Epi>
; __device__ __forceinline__ void gemm_phase(LAS unsigned char* lds, const Gemm g, const StaticOrder& S, const Epi& E, const int tid) {
;     ...
;             PG8_STAGE(PG8_SB(0, 1), b2 + hstepB, voffB);
;             PG8_WAIT_V(6); PG8_BAR; PG8_MMA(1, 1, At, B1); PG8_BAR;
;             PG8_LDB(B0, 1, 0); PG8_SCHED; PG8_LDA(At, 1, 0); PG8_STAGE(PG8_SA(0, 1), a2 + hstep, voffA);
;             PG8_WAIT_L(8); PG8_BAR; PG8_WAIT_L(0); PG8_MMA(0, 0, At, B0); PG8_BAR; PG8_SCHED;
;             PG8_LDB(B1, 1, 1); PG8_STAGE(PG8_SB(1, 0), b3, voffB);
;             PG8_BAR; PG8_WAIT_L(0); PG8_MMA(0, 1, At, B1); PG8_BAR;
;             PG8_LDA(At, 1, 1); PG8_STAGE(PG8_SA(1, 0), a3, voffA);
	s_add_u32 s56, s18, 0x20000
	s_addc_u32 s57, s19, 0
	s_add_i32 s55, s58, s38
	s_mov_b32 m0, s55
	s_nop 0
	global_load_lds_dwordx4 v2, s[56:57]
	s_add_i32 m0, s55, 0x2000
	s_nop 0
	global_load_lds_dwordx4 v0, s[56:57]
	s_waitcnt vmcnt(6)
	s_barrier
	v_mfma_f32_16x16x32_bf16 v[52:55], v[218:221], v[174:177], v[52:55]
	v_mfma_f32_16x16x32_bf16 v[56:59], v[226:229], v[174:177], v[56:59]
	v_mfma_f32_16x16x32_bf16 v[36:39], v[218:221], v[194:197], v[36:39]
	v_mfma_f32_16x16x32_bf16 v[40:43], v[226:229], v[194:197], v[40:43]
	v_mfma_f32_16x16x32_bf16 v[20:23], v[218:221], v[202:205], v[20:23]
	v_mfma_f32_16x16x32_bf16 v[24:27], v[226:229], v[202:205], v[24:27]
	v_mfma_f32_16x16x32_bf16 v[8:11], v[218:221], v[210:213], v[8:11]
	v_mfma_f32_16x16x32_bf16 v[4:7], v[226:229], v[210:213], v[4:7]
	v_mfma_f32_16x16x32_bf16 v[52:55], v[222:225], v[190:193], v[52:55]
	v_mfma_f32_16x16x32_bf16 v[56:59], v[230:233], v[190:193], v[56:59]
	v_mfma_f32_16x16x32_bf16 v[36:39], v[222:225], v[198:201], v[36:39]
	v_mfma_f32_16x16x32_bf16 v[40:43], v[230:233], v[198:201], v[40:43]
	v_mfma_f32_16x16x32_bf16 v[20:23], v[222:225], v[206:209], v[20:23]
	v_mfma_f32_16x16x32_bf16 v[24:27], v[230:233], v[206:209], v[24:27]
	v_mfma_f32_16x16x32_bf16 v[8:11], v[222:225], v[214:217], v[8:11]
	v_mfma_f32_16x16x32_bf16 v[4:7], v[230:233], v[214:217], v[4:7]
	s_add_i32 s55, 0, 0x18000
	v_add_u32_e32 v157, s55, v140
	s_barrier
	ds_read_b128 v[144:147], v157
	ds_read_b128 v[162:165], v157 offset:1024
	ds_read_b128 v[166:169], v157 offset:2048
	ds_read_b128 v[170:173], v157 offset:3072
	s_add_u32 s22, s22, 0x80000
	s_addc_u32 s23, s23, 0
	s_mov_b32 m0, s41
	ds_read_b128 v[174:177], v143 offset:32768
	ds_read_b128 v[190:193], v143 offset:33792
	ds_read_b128 v[194:197], v143 offset:34816
	ds_read_b128 v[198:201], v143 offset:35840
	ds_read_b128 v[202:205], v143 offset:36864
	ds_read_b128 v[206:209], v143 offset:37888
	ds_read_b128 v[210:213], v143 offset:38912
	ds_read_b128 v[214:217], v143 offset:39936
	global_load_lds_dwordx4 v134, s[22:23]
	s_mov_b32 m0, s42
	s_nop 0
	global_load_lds_dwordx4 v132, s[22:23]
	s_waitcnt lgkmcnt(8)
	s_barrier
	s_waitcnt lgkmcnt(7)
	v_mfma_f32_16x16x32_bf16 v[124:127], v[144:147], v[174:177], v[124:127]
	v_mfma_f32_16x16x32_bf16 v[128:131], v[166:169], v[174:177], v[128:131]
	s_waitcnt lgkmcnt(5)
	v_mfma_f32_16x16x32_bf16 v[108:111], v[144:147], v[194:197], v[108:111]
	v_mfma_f32_16x16x32_bf16 v[112:115], v[166:169], v[194:197], v[112:115]
	s_waitcnt lgkmcnt(3)
	v_mfma_f32_16x16x32_bf16 v[92:95], v[144:147], v[202:205], v[92:95]
	v_mfma_f32_16x16x32_bf16 v[96:99], v[166:169], v[202:205], v[96:99]
	s_waitcnt lgkmcnt(1)
	v_mfma_f32_16x16x32_bf16 v[76:79], v[144:147], v[210:213], v[76:79]
	v_mfma_f32_16x16x32_bf16 v[80:83], v[166:169], v[210:213], v[80:83]
	v_mfma_f32_16x16x32_bf16 v[124:127], v[162:165], v[190:193], v[124:127]
	v_mfma_f32_16x16x32_bf16 v[128:131], v[170:173], v[190:193], v[128:131]
	v_mfma_f32_16x16x32_bf16 v[108:111], v[162:165], v[198:201], v[108:111]
	v_mfma_f32_16x16x32_bf16 v[112:115], v[170:173], v[198:201], v[112:115]
	v_mfma_f32_16x16x32_bf16 v[92:95], v[162:165], v[206:209], v[92:95]
	v_mfma_f32_16x16x32_bf16 v[96:99], v[170:173], v[206:209], v[96:99]
	s_waitcnt lgkmcnt(0)
	v_mfma_f32_16x16x32_bf16 v[76:79], v[162:165], v[214:217], v[76:79]
	v_mfma_f32_16x16x32_bf16 v[80:83], v[170:173], v[214:217], v[80:83]
	s_barrier
	s_add_i32 s22, 0, 0x1c000
	s_add_i32 s23, s55, s38
	v_add_u32_e32 v157, s22, v140
	v_lshl_add_u64 v[178:179], v[178:179], 0, s[30:31]
	s_mov_b32 m0, s23
	ds_read_b128 v[218:221], v157
	ds_read_b128 v[222:225], v157 offset:1024
	ds_read_b128 v[226:229], v157 offset:2048
	ds_read_b128 v[230:233], v157 offset:3072
	global_load_lds_dwordx4 v[178:179], off
	v_lshl_add_u64 v[178:179], v[234:235], 0, s[30:31]
	s_add_i32 m0, s23, 0x2000
	s_nop 0
	global_load_lds_dwordx4 v[178:179], off
	s_barrier
	s_waitcnt lgkmcnt(3)
	v_mfma_f32_16x16x32_bf16 v[116:119], v[218:221], v[174:177], v[116:119]
	s_waitcnt lgkmcnt(1)
	v_mfma_f32_16x16x32_bf16 v[120:123], v[226:229], v[174:177], v[120:123]
	v_mfma_f32_16x16x32_bf16 v[100:103], v[218:221], v[194:197], v[100:103]
	v_mfma_f32_16x16x32_bf16 v[104:107], v[226:229], v[194:197], v[104:107]
	v_mfma_f32_16x16x32_bf16 v[84:87], v[218:221], v[202:205], v[84:87]
	v_mfma_f32_16x16x32_bf16 v[88:91], v[226:229], v[202:205], v[88:91]
	v_mfma_f32_16x16x32_bf16 v[68:71], v[218:221], v[210:213], v[68:71]
	v_mfma_f32_16x16x32_bf16 v[72:75], v[226:229], v[210:213], v[72:75]
	v_mfma_f32_16x16x32_bf16 v[116:119], v[222:225], v[190:193], v[116:119]
	s_waitcnt lgkmcnt(0)
	v_mfma_f32_16x16x32_bf16 v[120:123], v[230:233], v[190:193], v[120:123]
	v_mfma_f32_16x16x32_bf16 v[100:103], v[222:225], v[198:201], v[100:103]
	v_mfma_f32_16x16x32_bf16 v[104:107], v[230:233], v[198:201], v[104:107]
	v_mfma_f32_16x16x32_bf16 v[84:87], v[222:225], v[206:209], v[84:87]
	v_mfma_f32_16x16x32_bf16 v[88:91], v[230:233], v[206:209], v[88:91]
	v_mfma_f32_16x16x32_bf16 v[68:71], v[222:225], v[214:217], v[68:71]
	v_mfma_f32_16x16x32_bf16 v[72:75], v[230:233], v[214:217], v[72:75]
	s_mov_b32 m0, s43
	v_lshl_add_u64 v[178:179], v[236:237], 0, s[30:31]
	s_barrier
	ds_read_b128 v[174:177], v143 offset:49152
	ds_read_b128 v[190:193], v143 offset:50176
	ds_read_b128 v[194:197], v143 offset:51200
	ds_read_b128 v[198:201], v143 offset:52224
	ds_read_b128 v[202:205], v143 offset:53248
	ds_read_b128 v[206:209], v143 offset:54272
	ds_read_b128 v[210:213], v143 offset:55296
	ds_read_b128 v[214:217], v143 offset:56320
	global_load_lds_dwordx4 v[178:179], off
	v_lshl_add_u64 v[178:179], v[238:239], 0, s[30:31]
	s_mov_b32 m0, s46
	s_nop 0
	global_load_lds_dwordx4 v[178:179], off
	s_barrier
; #define PG8_STAGE(bufoff, gbase, voff) do { _Pragma("unroll") for (int _i = 0; _i < 2; ++_i) \
;         __builtin_amdgcn_global_load_lds((const unsigned*)((const char*)(gbase) + (voff)[_i]), (LAS unsigned*)(lds + (bufoff) + ldsw + _i * 8192), 16, 0, 0); } while (0)
; #define PG8_LDA(dst, b, h) do { _Pragma("unroll") for (int m = 0; m < 4; ++m) _Pragma("unroll") for (int k = 0; k < 2; ++k) dst[m][k] = *(const LAS h8*)(lds + PG8_SA(b, h) + aoff + m * 2048 + k * 1024); } while (0)
; #define PG8_WAIT_V(n) asm volatile("s_waitcnt vmcnt(" #n ")" ::: "memory")
; #define PG8_WAIT_L(n) asm volatile("s_waitcnt lgkmcnt(" #n ")" ::: "memory")
; #define PG8_BAR __builtin_amdgcn_s_barrier()
; #define PG8_SCHED __builtin_amdgcn_sched_barrier(0)
; template <class Epi>
; __device__ __forceinline__ void gemm_phase(LAS unsigned char* lds, const Gemm g, const StaticOrder& S, const Epi& E, const int tid) {
;     ...
;             PG8_LDA(At, 1, 1); PG8_STAGE(PG8_SA(1, 0), a3, voffA);
;             PG8_BAR; PG8_WAIT_L(0); PG8_MMA(1, 0, At, B0); PG8_BAR; PG8_SCHED;
;             PG8_STAGE(PG8_SB(1, 1), b3 + hstepB, voffB);
;             PG8_WAIT_V(6); PG8_BAR; PG8_MMA(1, 1, At, B1); PG8_BAR;
;         }
;     __device__ __forceinline__ void operator()(f32x4 (&acc)[2][2][4][2], const pg8::Unit& u, int wr, int wc, int fr, int fq) const {
;         const bool hi = fr >= 8;
;         const int row0 = u.pm * 256 + wr * 64 + (fr & 7), col = u.pn * 256 + wc * 64 + fq * 8 + (hi ? 32 : 0);
; #pragma unroll
;         for (int ai = 0; ai < 2; ++ai)
; #pragma unroll
;             for (int m = 0; m < 4; ++m) {
;                 const h8 x0 = pack8(acc[ai][0][m][0], acc[ai][0][m][1]), x1 = pack8(acc[ai][1][m][0], acc[ai][1][m][1]);
;                 const i32x4 snd = hi ? __builtin_bit_cast(i32x4, x0) : __builtin_bit_cast(i32x4, x1);
;                 i32x4 rcv;
; #pragma unroll
;                 for (int d = 0; d < 4; ++d) rcv[d] = __builtin_amdgcn_update_dpp(0, snd[d], 0x128  , 0xF, 0xF, false);
;                 const h8 rv = __builtin_bit_cast(h8, rcv);
;                 const h8 vA = hi ? rv : x0;
;                 const h8 vB = hi ? x1 : rv;
;                 half_t* rowp = O + (size_t)(row0 + ai * 128 + m * 16) * NIN + col;
;                 __builtin_nontemporal_store(vA, (h8*)rowp); __builtin_nontemporal_store(vB, (h8*)(rowp + (size_t)8 * NIN)); }
	s_waitcnt lgkmcnt(7)
	v_mfma_f32_16x16x32_bf16 v[60:63], v[144:147], v[174:177], v[60:63]
	v_mfma_f32_16x16x32_bf16 v[64:67], v[166:169], v[174:177], v[64:67]
	s_waitcnt lgkmcnt(5)
	v_mfma_f32_16x16x32_bf16 v[44:47], v[144:147], v[194:197], v[44:47]
	v_mfma_f32_16x16x32_bf16 v[48:51], v[166:169], v[194:197], v[48:51]
	s_waitcnt lgkmcnt(3)
	v_mfma_f32_16x16x32_bf16 v[28:31], v[144:147], v[202:205], v[28:31]
	v_mfma_f32_16x16x32_bf16 v[32:35], v[166:169], v[202:205], v[32:35]
	s_waitcnt lgkmcnt(1)
	v_mfma_f32_16x16x32_bf16 v[12:15], v[144:147], v[210:213], v[12:15]
	v_mfma_f32_16x16x32_bf16 v[16:19], v[166:169], v[210:213], v[16:19]
	v_mfma_f32_16x16x32_bf16 v[60:63], v[162:165], v[190:193], v[60:63]
	v_mfma_f32_16x16x32_bf16 v[64:67], v[170:173], v[190:193], v[64:67]
	v_mfma_f32_16x16x32_bf16 v[44:47], v[162:165], v[198:201], v[44:47]
	v_mfma_f32_16x16x32_bf16 v[48:51], v[170:173], v[198:201], v[48:51]
	v_mfma_f32_16x16x32_bf16 v[28:31], v[162:165], v[206:209], v[28:31]
	v_mfma_f32_16x16x32_bf16 v[32:35], v[170:173], v[206:209], v[32:35]
	s_waitcnt lgkmcnt(0)
	v_mfma_f32_16x16x32_bf16 v[12:15], v[162:165], v[214:217], v[12:15]
	v_mfma_f32_16x16x32_bf16 v[16:19], v[170:173], v[214:217], v[16:19]
	s_barrier
	s_add_u32 s18, s18, 0x20080
	s_addc_u32 s19, s19, 0
	s_add_i32 s22, s22, s38
	s_mov_b32 m0, s22
	s_nop 0
	global_load_lds_dwordx4 v2, s[18:19]
	v_lshl_add_u64 v[144:145], s[18:19], 0, v[0:1]
	s_add_i32 m0, s22, 0x2000
	s_nop 0
	global_load_lds_dwordx4 v[144:145], off
	s_waitcnt vmcnt(6)
	s_barrier
	v_mfma_f32_16x16x32_bf16 v[52:55], v[218:221], v[174:177], v[52:55]
	v_mfma_f32_16x16x32_bf16 v[56:59], v[226:229], v[174:177], v[56:59]
	v_mfma_f32_16x16x32_bf16 v[36:39], v[218:221], v[194:197], v[36:39]
	v_mfma_f32_16x16x32_bf16 v[40:43], v[226:229], v[194:197], v[40:43]
	v_mfma_f32_16x16x32_bf16 v[20:23], v[218:221], v[202:205], v[20:23]
	v_mfma_f32_16x16x32_bf16 v[24:27], v[226:229], v[202:205], v[24:27]
	v_mfma_f32_16x16x32_bf16 v[8:11], v[218:221], v[210:213], v[8:11]
	v_mfma_f32_16x16x32_bf16 v[4:7], v[226:229], v[210:213], v[4:7]
	v_mfma_f32_16x16x32_bf16 v[52:55], v[222:225], v[190:193], v[52:55]
	v_mfma_f32_16x16x32_bf16 v[56:59], v[230:233], v[190:193], v[56:59]
	v_mfma_f32_16x16x32_bf16 v[36:39], v[222:225], v[198:201], v[36:39]
	v_mfma_f32_16x16x32_bf16 v[40:43], v[230:233], v[198:201], v[40:43]
	v_mfma_f32_16x16x32_bf16 v[20:23], v[222:225], v[206:209], v[20:23]
	v_mfma_f32_16x16x32_bf16 v[24:27], v[230:233], v[206:209], v[24:27]
	v_mfma_f32_16x16x32_bf16 v[8:11], v[222:225], v[214:217], v[8:11]
	v_mfma_f32_16x16x32_bf16 v[4:7], v[230:233], v[214:217], v[4:7]
	s_add_i32 s54, s54, 2
	s_add_u32 s14, s14, 0x100
	s_addc_u32 s15, s15, 0
	s_add_u32 s52, s52, 0x100
	s_addc_u32 s53, s53, 0
	s_cmp_gt_u32 s54, 29
	s_barrier
	s_cbranch_scc0 .LBB0_332
	v_cvt_pk_f16_f32 v124, v124, v125
	v_cvt_pk_f16_f32 v116, v116, v117
	v_cvt_pk_f16_f32 v130, v130, v131
	v_cvt_pk_f16_f32 v131, v122, v123
	v_cvt_pk_f16_f32 v128, v128, v129
	v_cvt_pk_f16_f32 v129, v120, v121
	v_cvt_pk_f16_f32 v121, v126, v127
	v_cvt_pk_f16_f32 v118, v118, v119
	v_cndmask_b32_e64 v117, v116, v124, s[4:5]
	v_mov_b32_e32 v147, v3
	v_cndmask_b32_e64 v122, v131, v130, s[4:5]
	v_cndmask_b32_e64 v119, v118, v121, s[4:5]
	v_mov_b32_dpp v147, v117 row_ror:8 row_mask:0xf bank_mask:0xf
	v_mov_b32_e32 v117, v3
	v_mov_b32_e32 v125, v3
	v_lshl_or_b32 v144, s48, 8, v142
	v_cndmask_b32_e64 v120, v129, v128, s[4:5]
	v_mov_b32_dpp v117, v119 row_ror:8 row_mask:0xf bank_mask:0xf
	v_mov_b32_e32 v119, v3
	v_mov_b32_dpp v125, v122 row_ror:8 row_mask:0xf bank_mask:0xf
	v_lshl_add_u32 v146, s49, 8, v141
	v_ashrrev_i32_e32 v145, 31, v144
	v_mov_b32_dpp v119, v120 row_ror:8 row_mask:0xf bank_mask:0xf
	v_cndmask_b32_e64 v123, v130, v125, s[4:5]
	v_cndmask_b32_e64 v121, v121, v117, s[4:5]
	v_cndmask_b32_e64 v120, v124, v147, s[4:5]
	v_cndmask_b32_e64 v127, v125, v131, s[4:5]
	v_cndmask_b32_e64 v125, v117, v118, s[4:5]
	v_cndmask_b32_e64 v124, v147, v116, s[4:5]
	v_mov_b64_e32 v[116:117], s[36:37]
	v_cndmask_b32_e64 v122, v128, v119, s[4:5]
	v_cndmask_b32_e64 v126, v119, v129, s[4:5]
	v_mad_i64_i32 v[128:129], s[14:15], v146, s35, v[116:117]
	v_lshlrev_b64 v[118:119], 1, v[144:145]
	v_lshl_add_u64 v[128:129], v[128:129], 0, v[118:119]
	s_mov_b32 s1, 0x3c000
	global_store_dwordx4 v[128:129], v[120:123], off nt
	v_cvt_pk_f16_f32 v112, v112, v113
	v_cvt_pk_f16_f32 v104, v104, v105
	v_add_co_u32_e32 v120, vcc, s1, v128
	v_cvt_pk_f16_f32 v108, v108, v109
	s_nop 0
	v_addc_co_u32_e32 v121, vcc, 0, v129, vcc
	v_cvt_pk_f16_f32 v109, v100, v101
	global_store_dwordx4 v[120:121], v[124:127], off nt
	v_cvt_pk_f16_f32 v114, v114, v115
	v_cvt_pk_f16_f32 v106, v106, v107
	v_cndmask_b32_e64 v105, v104, v112, s[4:5]
	v_cndmask_b32_e64 v100, v109, v108, s[4:5]
	v_mov_b32_e32 v113, v3
	v_mov_b32_e32 v120, v3
	v_cndmask_b32_e64 v107, v106, v114, s[4:5]
	v_cvt_pk_f16_f32 v110, v110, v111
	v_cvt_pk_f16_f32 v111, v102, v103
	v_mov_b32_dpp v113, v100 row_ror:8 row_mask:0xf bank_mask:0xf
	v_mov_b32_dpp v120, v105 row_ror:8 row_mask:0xf bank_mask:0xf
	v_mov_b32_e32 v105, v3
	v_cndmask_b32_e64 v102, v111, v110, s[4:5]
	v_mov_b32_e32 v115, v3
	v_mov_b32_dpp v105, v107 row_ror:8 row_mask:0xf bank_mask:0xf
	v_cndmask_b32_e64 v100, v108, v113, s[4:5]
	v_or_b32_e32 v108, 16, v146
	v_mov_b32_dpp v115, v102 row_ror:8 row_mask:0xf bank_mask:0xf
	v_cndmask_b32_e64 v107, v105, v106, s[4:5]
	v_cndmask_b32_e64 v106, v120, v104, s[4:5]
	v_cndmask_b32_e64 v104, v113, v109, s[4:5]
	v_mad_i64_i32 v[108:109], s[14:15], v108, s35, v[116:117]
	v_cndmask_b32_e64 v103, v114, v105, s[4:5]
	v_cndmask_b32_e64 v102, v112, v120, s[4:5]
;     __device__ __forceinline__ void operator()(f32x4 (&acc)[2][2][4][2], const pg8::Unit& u, int wr, int wc, int fr, int fq) const {
;         const bool hi = fr >= 8;
;         const int row0 = u.pm * 256 + wr * 64 + (fr & 7), col = u.pn * 256 + wc * 64 + fq * 8 + (hi ? 32 : 0);
; #pragma unroll
;         for (int ai = 0; ai < 2; ++ai)
; #pragma unroll
;             for (int m = 0; m < 4; ++m) {
;                 const h8 x0 = pack8(acc[ai][0][m][0], acc[ai][0][m][1]), x1 = pack8(acc[ai][1][m][0], acc[ai][1][m][1]);
;                 const i32x4 snd = hi ? __builtin_bit_cast(i32x4, x0) : __builtin_bit_cast(i32x4, x1);
;                 i32x4 rcv;
; #pragma unroll
;                 for (int d = 0; d < 4; ++d) rcv[d] = __builtin_amdgcn_update_dpp(0, snd[d], 0x128  , 0xF, 0xF, false);
;                 const h8 rv = __builtin_bit_cast(h8, rcv);
;                 const h8 vA = hi ? rv : x0;
;                 const h8 vB = hi ? x1 : rv;
;                 half_t* rowp = O + (size_t)(row0 + ai * 128 + m * 16) * NIN + col;
;                 __builtin_nontemporal_store(vA, (h8*)rowp); __builtin_nontemporal_store(vB, (h8*)(rowp + (size_t)8 * NIN)); }
	v_cndmask_b32_e64 v101, v110, v115, s[4:5]
	v_lshl_add_u64 v[108:109], v[108:109], 0, v[118:119]
	global_store_dwordx4 v[108:109], v[100:103], off nt
	v_cndmask_b32_e64 v105, v115, v111, s[4:5]
	v_cvt_pk_f16_f32 v96, v96, v97
	v_add_co_u32_e32 v100, vcc, s1, v108
	v_cvt_pk_f16_f32 v88, v88, v89
	s_nop 0
	v_addc_co_u32_e32 v101, vcc, 0, v109, vcc
	v_cvt_pk_f16_f32 v92, v92, v93
	v_cvt_pk_f16_f32 v93, v84, v85
	global_store_dwordx4 v[100:101], v[104:107], off nt
	v_cvt_pk_f16_f32 v98, v98, v99
	v_cvt_pk_f16_f32 v90, v90, v91
	v_cndmask_b32_e64 v89, v88, v96, s[4:5]
	v_cndmask_b32_e64 v84, v93, v92, s[4:5]
	v_mov_b32_e32 v97, v3
	v_mov_b32_e32 v100, v3
	v_cndmask_b32_e64 v91, v90, v98, s[4:5]
	v_cvt_pk_f16_f32 v94, v94, v95
	v_cvt_pk_f16_f32 v95, v86, v87
	v_mov_b32_dpp v97, v84 row_ror:8 row_mask:0xf bank_mask:0xf
	v_mov_b32_dpp v100, v89 row_ror:8 row_mask:0xf bank_mask:0xf
	v_mov_b32_e32 v89, v3
	v_cndmask_b32_e64 v86, v95, v94, s[4:5]
	v_mov_b32_e32 v99, v3
	v_mov_b32_dpp v89, v91 row_ror:8 row_mask:0xf bank_mask:0xf
	v_cndmask_b32_e64 v84, v92, v97, s[4:5]
	v_or_b32_e32 v92, 32, v146
	v_mov_b32_dpp v99, v86 row_ror:8 row_mask:0xf bank_mask:0xf
	v_cndmask_b32_e64 v91, v89, v90, s[4:5]
	v_cndmask_b32_e64 v90, v100, v88, s[4:5]
	v_cndmask_b32_e64 v88, v97, v93, s[4:5]
	v_mad_i64_i32 v[92:93], s[14:15], v92, s35, v[116:117]
	v_cndmask_b32_e64 v87, v98, v89, s[4:5]
	v_cndmask_b32_e64 v86, v96, v100, s[4:5]
	v_cndmask_b32_e64 v85, v94, v99, s[4:5]
	v_lshl_add_u64 v[92:93], v[92:93], 0, v[118:119]
	global_store_dwordx4 v[92:93], v[84:87], off nt
	v_cndmask_b32_e64 v89, v99, v95, s[4:5]
	v_cvt_pk_f16_f32 v80, v80, v81
	v_add_co_u32_e32 v84, vcc, s1, v92
	v_cvt_pk_f16_f32 v72, v72, v73
	s_nop 0
	v_addc_co_u32_e32 v85, vcc, 0, v93, vcc
	v_cvt_pk_f16_f32 v76, v76, v77
	v_cvt_pk_f16_f32 v77, v68, v69
	global_store_dwordx4 v[84:85], v[88:91], off nt
	v_cvt_pk_f16_f32 v82, v82, v83
	v_cvt_pk_f16_f32 v74, v74, v75
	v_cndmask_b32_e64 v73, v72, v80, s[4:5]
	v_cndmask_b32_e64 v68, v77, v76, s[4:5]
	v_mov_b32_e32 v81, v3
	v_mov_b32_e32 v84, v3
	v_cndmask_b32_e64 v75, v74, v82, s[4:5]
	v_cvt_pk_f16_f32 v78, v78, v79
	v_cvt_pk_f16_f32 v79, v70, v71
	v_mov_b32_dpp v81, v68 row_ror:8 row_mask:0xf bank_mask:0xf
	v_mov_b32_dpp v84, v73 row_ror:8 row_mask:0xf bank_mask:0xf
	v_mov_b32_e32 v73, v3
	v_cndmask_b32_e64 v70, v79, v78, s[4:5]
	v_mov_b32_e32 v83, v3
	v_mov_b32_dpp v73, v75 row_ror:8 row_mask:0xf bank_mask:0xf
	v_cndmask_b32_e64 v68, v76, v81, s[4:5]
	v_or_b32_e32 v76, 48, v146
	v_mov_b32_dpp v83, v70 row_ror:8 row_mask:0xf bank_mask:0xf
	v_cndmask_b32_e64 v75, v73, v74, s[4:5]
	v_cndmask_b32_e64 v74, v84, v72, s[4:5]
	v_cndmask_b32_e64 v72, v81, v77, s[4:5]
	v_mad_i64_i32 v[76:77], s[14:15], v76, s35, v[116:117]
	v_cndmask_b32_e64 v71, v82, v73, s[4:5]
	v_cndmask_b32_e64 v70, v80, v84, s[4:5]
	v_cndmask_b32_e64 v69, v78, v83, s[4:5]
	v_lshl_add_u64 v[76:77], v[76:77], 0, v[118:119]
	global_store_dwordx4 v[76:77], v[68:71], off nt
	v_cndmask_b32_e64 v73, v83, v79, s[4:5]
	v_cvt_pk_f16_f32 v64, v64, v65
	v_add_co_u32_e32 v68, vcc, s1, v76
	v_cvt_pk_f16_f32 v56, v56, v57
	s_nop 0
	v_addc_co_u32_e32 v69, vcc, 0, v77, vcc
	global_store_dwordx4 v[68:69], v[72:75], off nt
	v_cvt_pk_f16_f32 v66, v66, v67
	v_cvt_pk_f16_f32 v58, v58, v59
	v_cndmask_b32_e64 v57, v56, v64, s[4:5]
	v_cvt_pk_f16_f32 v60, v60, v61
	v_cvt_pk_f16_f32 v61, v52, v53
	v_mov_b32_e32 v69, v3
	v_cndmask_b32_e64 v59, v58, v66, s[4:5]
	v_cvt_pk_f16_f32 v62, v62, v63
	v_cvt_pk_f16_f32 v63, v54, v55
	v_cndmask_b32_e64 v52, v61, v60, s[4:5]
	v_mov_b32_e32 v65, v3
	v_mov_b32_dpp v69, v57 row_ror:8 row_mask:0xf bank_mask:0xf
	v_mov_b32_e32 v57, v3
	v_add_u32_e32 v68, 0x80, v146
	v_cndmask_b32_e64 v54, v63, v62, s[4:5]
	v_mov_b32_dpp v65, v52 row_ror:8 row_mask:0xf bank_mask:0xf
	v_mov_b32_e32 v67, v3
	v_mov_b32_dpp v57, v59 row_ror:8 row_mask:0xf bank_mask:0xf
	v_cndmask_b32_e64 v52, v60, v65, s[4:5]
	v_mov_b32_dpp v67, v54 row_ror:8 row_mask:0xf bank_mask:0xf
	v_cndmask_b32_e64 v59, v57, v58, s[4:5]
	v_cndmask_b32_e64 v58, v69, v56, s[4:5]
	v_cndmask_b32_e64 v56, v65, v61, s[4:5]
	v_mad_i64_i32 v[60:61], s[14:15], v68, s35, v[116:117]
	v_cndmask_b32_e64 v55, v66, v57, s[4:5]
	v_cndmask_b32_e64 v54, v64, v69, s[4:5]
	v_cndmask_b32_e64 v53, v62, v67, s[4:5]
	v_lshl_add_u64 v[60:61], v[60:61], 0, v[118:119]
	global_store_dwordx4 v[60:61], v[52:55], off nt
	v_cndmask_b32_e64 v57, v67, v63, s[4:5]
	v_cvt_pk_f16_f32 v48, v48, v49
	v_add_co_u32_e32 v52, vcc, s1, v60
	v_cvt_pk_f16_f32 v40, v40, v41
	s_nop 0
	v_addc_co_u32_e32 v53, vcc, 0, v61, vcc
; #define PG8_WAIT_V(n) asm volatile("s_waitcnt vmcnt(" #n ")" ::: "memory")
; #define PG8_BAR __builtin_amdgcn_s_barrier()
; template <class Epi>
; __device__ __forceinline__ void gemm_phase(LAS unsigned char* lds, const Gemm g, const StaticOrder& S, const Epi& E, const int tid) {
;     ...
;     PG8_WAIT_V(0);
;     if (wr == 0) PG8_BAR;
;     PG8_BAR;
;     __device__ __forceinline__ void operator()(f32x4 (&acc)[2][2][4][2], const pg8::Unit& u, int wr, int wc, int fr, int fq) const {
;     ...
;                 const h8 x0 = pack8(acc[ai][0][m][0], acc[ai][0][m][1]), x1 = pack8(acc[ai][1][m][0], acc[ai][1][m][1]);
;                 const i32x4 snd = hi ? __builtin_bit_cast(i32x4, x0) : __builtin_bit_cast(i32x4, x1);
;                 i32x4 rcv;
; #pragma unroll
;                 for (int d = 0; d < 4; ++d) rcv[d] = __builtin_amdgcn_update_dpp(0, snd[d], 0x128  , 0xF, 0xF, false);
;                 const h8 rv = __builtin_bit_cast(h8, rcv);
;                 const h8 vA = hi ? rv : x0;
;                 const h8 vB = hi ? x1 : rv;
;                 half_t* rowp = O + (size_t)(row0 + ai * 128 + m * 16) * NIN + col;
;                 __builtin_nontemporal_store(vA, (h8*)rowp); __builtin_nontemporal_store(vB, (h8*)(rowp + (size_t)8 * NIN)); }
	v_cvt_pk_f16_f32 v44, v44, v45
	v_cvt_pk_f16_f32 v45, v36, v37
	global_store_dwordx4 v[52:53], v[56:59], off nt
	v_cvt_pk_f16_f32 v50, v50, v51
	v_cvt_pk_f16_f32 v42, v42, v43
	v_cndmask_b32_e64 v41, v40, v48, s[4:5]
	v_cndmask_b32_e64 v36, v45, v44, s[4:5]
	v_mov_b32_e32 v49, v3
	v_mov_b32_e32 v52, v3
	v_cndmask_b32_e64 v43, v42, v50, s[4:5]
	v_cvt_pk_f16_f32 v46, v46, v47
	v_cvt_pk_f16_f32 v47, v38, v39
	v_mov_b32_dpp v49, v36 row_ror:8 row_mask:0xf bank_mask:0xf
	v_mov_b32_dpp v52, v41 row_ror:8 row_mask:0xf bank_mask:0xf
	v_mov_b32_e32 v41, v3
	v_cndmask_b32_e64 v38, v47, v46, s[4:5]
	v_mov_b32_e32 v51, v3
	v_mov_b32_dpp v41, v43 row_ror:8 row_mask:0xf bank_mask:0xf
	v_cndmask_b32_e64 v36, v44, v49, s[4:5]
	v_add_u32_e32 v44, 0x90, v146
	v_mov_b32_dpp v51, v38 row_ror:8 row_mask:0xf bank_mask:0xf
	v_cndmask_b32_e64 v43, v41, v42, s[4:5]
	v_cndmask_b32_e64 v42, v52, v40, s[4:5]
	v_cndmask_b32_e64 v40, v49, v45, s[4:5]
	v_mad_i64_i32 v[44:45], s[14:15], v44, s35, v[116:117]
	v_cndmask_b32_e64 v39, v50, v41, s[4:5]
	v_cndmask_b32_e64 v38, v48, v52, s[4:5]
	v_cndmask_b32_e64 v37, v46, v51, s[4:5]
	v_lshl_add_u64 v[44:45], v[44:45], 0, v[118:119]
	global_store_dwordx4 v[44:45], v[36:39], off nt
	v_cndmask_b32_e64 v41, v51, v47, s[4:5]
	v_cvt_pk_f16_f32 v32, v32, v33
	v_add_co_u32_e32 v36, vcc, s1, v44
	v_cvt_pk_f16_f32 v24, v24, v25
	s_nop 0
	v_addc_co_u32_e32 v37, vcc, 0, v45, vcc
	v_cvt_pk_f16_f32 v28, v28, v29
	v_cvt_pk_f16_f32 v29, v20, v21
	global_store_dwordx4 v[36:37], v[40:43], off nt
	v_cvt_pk_f16_f32 v34, v34, v35
	v_cvt_pk_f16_f32 v26, v26, v27
	v_cndmask_b32_e64 v25, v24, v32, s[4:5]
	v_cndmask_b32_e64 v20, v29, v28, s[4:5]
	v_mov_b32_e32 v33, v3
	v_mov_b32_e32 v36, v3
	v_cndmask_b32_e64 v27, v26, v34, s[4:5]
	v_cvt_pk_f16_f32 v30, v30, v31
	v_cvt_pk_f16_f32 v31, v22, v23
	v_mov_b32_dpp v33, v20 row_ror:8 row_mask:0xf bank_mask:0xf
	v_mov_b32_dpp v36, v25 row_ror:8 row_mask:0xf bank_mask:0xf
	v_mov_b32_e32 v25, v3
	v_cvt_pk_f16_f32 v16, v16, v17
	v_cvt_pk_f16_f32 v17, v4, v5
	v_cvt_pk_f16_f32 v5, v14, v15
	v_cvt_pk_f16_f32 v14, v10, v11
	v_cvt_pk_f16_f32 v10, v12, v13
	v_cvt_pk_f16_f32 v8, v8, v9
	v_cndmask_b32_e64 v22, v31, v30, s[4:5]
	v_mov_b32_e32 v35, v3
	v_mov_b32_dpp v25, v27 row_ror:8 row_mask:0xf bank_mask:0xf
	v_cndmask_b32_e64 v20, v28, v33, s[4:5]
	v_add_u32_e32 v28, 0xa0, v146
	v_cndmask_b32_e64 v9, v8, v10, s[4:5]
	v_mov_b32_e32 v12, v3
	v_mov_b32_dpp v35, v22 row_ror:8 row_mask:0xf bank_mask:0xf
	v_cndmask_b32_e64 v27, v25, v26, s[4:5]
	v_cndmask_b32_e64 v26, v36, v24, s[4:5]
	v_cndmask_b32_e64 v24, v33, v29, s[4:5]
	v_mad_i64_i32 v[28:29], s[14:15], v28, s35, v[116:117]
	v_cvt_pk_f16_f32 v18, v18, v19
	v_cvt_pk_f16_f32 v19, v6, v7
	v_cndmask_b32_e64 v4, v17, v16, s[4:5]
	v_mov_b32_dpp v12, v9 row_ror:8 row_mask:0xf bank_mask:0xf
	v_mov_b32_e32 v13, v3
	v_cndmask_b32_e64 v23, v34, v25, s[4:5]
	v_cndmask_b32_e64 v22, v32, v36, s[4:5]
	v_cndmask_b32_e64 v21, v30, v35, s[4:5]
	v_lshl_add_u64 v[28:29], v[28:29], 0, v[118:119]
	v_cndmask_b32_e64 v6, v19, v18, s[4:5]
	v_cndmask_b32_e64 v7, v14, v5, s[4:5]
	v_mov_b32_e32 v9, v3
	v_mov_b32_dpp v13, v4 row_ror:8 row_mask:0xf bank_mask:0xf
	v_mov_b32_e32 v11, v3
	v_cndmask_b32_e64 v4, v10, v12, s[4:5]
	v_cndmask_b32_e64 v8, v12, v8, s[4:5]
	v_add_u32_e32 v12, 0xb0, v146
	global_store_dwordx4 v[28:29], v[20:23], off nt
	v_mov_b32_dpp v9, v7 row_ror:8 row_mask:0xf bank_mask:0xf
	v_mov_b32_dpp v11, v6 row_ror:8 row_mask:0xf bank_mask:0xf
	v_add_co_u32_e32 v20, vcc, s1, v28
	v_cndmask_b32_e64 v6, v16, v13, s[4:5]
	v_cndmask_b32_e64 v10, v13, v17, s[4:5]
	v_mad_i64_i32 v[12:13], s[14:15], v12, s35, v[116:117]
	v_addc_co_u32_e32 v21, vcc, 0, v29, vcc
	v_cndmask_b32_e64 v7, v18, v11, s[4:5]
	v_cndmask_b32_e64 v5, v5, v9, s[4:5]
	v_lshl_add_u64 v[12:13], v[12:13], 0, v[118:119]
	global_store_dwordx4 v[12:13], v[4:7], off nt
	v_cndmask_b32_e64 v25, v35, v31, s[4:5]
	v_cndmask_b32_e64 v11, v11, v19, s[4:5]
	v_add_co_u32_e32 v4, vcc, 0x3c000, v12
	v_cndmask_b32_e64 v9, v9, v14, s[4:5]
	s_nop 0
	v_addc_co_u32_e32 v5, vcc, 0, v13, vcc
	s_and_b64 vcc, exec, s[6:7]
	s_mov_b32 s48, s0
	s_mov_b32 s49, s8
	s_mov_b64 s[18:19], s[12:13]
	s_mov_b64 s[14:15], s[10:11]
	global_store_dwordx4 v[20:21], v[24:27], off nt
	global_store_dwordx4 v[4:5], v[8:11], off nt
	s_cbranch_vccz .LBB0_329
	s_waitcnt vmcnt(0)
	v_readlane_b32 s42, v251, 7
	v_readlane_b32 s46, v251, 9
	v_readlane_b32 s48, v251, 13
	s_cmpk_gt_u32 s20, 0xff
	v_readlane_b32 s43, v251, 8
	v_readlane_b32 s47, v251, 10
	v_readlane_b32 s49, v251, 14
	s_cbranch_scc1 .LBB0_336
	s_barrier

; #define PG8_STAGE(bufoff, gbase, voff) do { _Pragma("unroll") for (int _i = 0; _i < 2; ++_i) \
;         __builtin_amdgcn_global_load_lds((const unsigned*)((const char*)(gbase) + (voff)[_i]), (LAS unsigned*)(lds + (bufoff) + ldsw + _i * 8192), 16, 0, 0); } while (0)
; #define PG8_LDA(dst, b, h) do { _Pragma("unroll") for (int m = 0; m < 4; ++m) _Pragma("unroll") for (int k = 0; k < 2; ++k) dst[m][k] = *(const LAS h8*)(lds + PG8_SA(b, h) + aoff + m * 2048 + k * 1024); } while (0)
; #define PG8_LDB(dst, b, h) do { _Pragma("unroll") for (int n = 0; n < 2; ++n) _Pragma("unroll") for (int k = 0; k < 2; ++k) dst[n][k] = *(const LAS h8*)(lds + PG8_SB(b, h) + boff + n * 2048 + k * 1024); } while (0)
; #define PG8_WAIT_L(n) asm volatile("s_waitcnt lgkmcnt(" #n ")" ::: "memory")
; #define PG8_BAR __builtin_amdgcn_s_barrier()
; #define PG8_SCHED __builtin_amdgcn_sched_barrier(0)
; template <class Epi>
; __device__ __forceinline__ void gemm_phase(LAS unsigned char* lds, const Gemm g, const StaticOrder& S, const Epi& E, const int tid) {
;     ...
;         for (int t = 0; t < nt; t += 2) {
;             const bool last = (t == nt - 2);
;             const char* a1 = cA + (size_t)(t + 1) * kstep;
;             const char* a2 = last ? nA : cA + (size_t)(t + 2) * kstep; const char* b2 = last ? nB : cB + (size_t)(t + 2) * kstep;
;             const char* a3 = a2 + kstep; const char* b3 = b2 + kstep;
;             if constexpr (Epi::HAS_MID) { if (t == (nt >> 1)) E.mid(acc, cur, wr, wc, fr, fq); }
;             PG8_LDB(B0, 0, 0); PG8_SCHED; PG8_LDA(At, 0, 0); PG8_STAGE(PG8_SA(1, 1), a1 + hstep, voffA);
;             PG8_WAIT_L(8); PG8_BAR; PG8_WAIT_L(0); PG8_MMA(0, 0, At, B0); PG8_BAR; PG8_SCHED;
;             PG8_LDB(B1, 0, 1); PG8_STAGE(PG8_SB(0, 0), b2, voffB);
;             PG8_BAR; PG8_WAIT_L(0); PG8_MMA(0, 1, At, B1); PG8_BAR;
;             PG8_LDA(At, 0, 1); PG8_STAGE(PG8_SA(0, 0), a2, voffA);
;             PG8_BAR; PG8_WAIT_L(0); PG8_MMA(1, 0, At, B0); PG8_BAR; PG8_SCHED;
.LBB0_594:
	s_add_u32 s14, s10, s12
	s_addc_u32 s15, s11, s13
	s_add_u32 s14, s14, 0x100
	s_addc_u32 s15, s15, 0
	s_add_u32 s55, s52, s12
	s_addc_u32 s56, s53, s13
	s_cmpk_eq_i32 s12, 0x1f00
	s_cselect_b32 s19, s5, s15
	s_cselect_b32 s18, s50, s14
	s_cselect_b32 s15, s1, s56
	s_cselect_b32 s14, s51, s55
	s_add_i32 s55, 0, 0x10000
	v_add_u32_e32 v0, s55, v189
	ds_read_b128 v[132:135], v0
	ds_read_b128 v[136:139], v0 offset:1024
	ds_read_b128 v[176:179], v0 offset:2048
	ds_read_b128 v[192:195], v0 offset:3072
	v_lshl_add_u64 v[0:1], v[172:173], 0, s[12:13]
	s_add_i32 m0, s25, 0xc000
	ds_read_b128 v[196:199], v191
	ds_read_b128 v[200:203], v191 offset:1024
	ds_read_b128 v[204:207], v191 offset:2048
	ds_read_b128 v[208:211], v191 offset:3072
	ds_read_b128 v[212:215], v191 offset:4096
	ds_read_b128 v[216:219], v191 offset:5120
	ds_read_b128 v[220:223], v191 offset:6144
	ds_read_b128 v[224:227], v191 offset:7168
	global_load_lds_dwordx4 v[0:1], off
	v_lshl_add_u64 v[0:1], v[174:175], 0, s[12:13]
	s_add_i32 m0, s25, 0xe000
	s_nop 0
	global_load_lds_dwordx4 v[0:1], off
	s_waitcnt lgkmcnt(8)
	s_barrier
	s_waitcnt lgkmcnt(7)
	v_mfma_f32_16x16x32_bf16 v[128:131], v[132:135], v[196:199], v[128:131]
	v_mfma_f32_16x16x32_bf16 v[124:127], v[176:179], v[196:199], v[124:127]
	s_waitcnt lgkmcnt(5)
	v_mfma_f32_16x16x32_bf16 v[112:115], v[132:135], v[204:207], v[112:115]
	v_mfma_f32_16x16x32_bf16 v[108:111], v[176:179], v[204:207], v[108:111]
	s_waitcnt lgkmcnt(3)
	v_mfma_f32_16x16x32_bf16 v[96:99], v[132:135], v[212:215], v[96:99]
	v_mfma_f32_16x16x32_bf16 v[92:95], v[176:179], v[212:215], v[92:95]
	s_waitcnt lgkmcnt(1)
	v_mfma_f32_16x16x32_bf16 v[80:83], v[132:135], v[220:223], v[80:83]
	v_mfma_f32_16x16x32_bf16 v[76:79], v[176:179], v[220:223], v[76:79]
	v_mfma_f32_16x16x32_bf16 v[128:131], v[136:139], v[200:203], v[128:131]
	v_mfma_f32_16x16x32_bf16 v[124:127], v[192:195], v[200:203], v[124:127]
	v_mfma_f32_16x16x32_bf16 v[112:115], v[136:139], v[208:211], v[112:115]
	v_mfma_f32_16x16x32_bf16 v[108:111], v[192:195], v[208:211], v[108:111]
	v_mfma_f32_16x16x32_bf16 v[96:99], v[136:139], v[216:219], v[96:99]
	v_mfma_f32_16x16x32_bf16 v[92:95], v[192:195], v[216:219], v[92:95]
	s_waitcnt lgkmcnt(0)
	v_mfma_f32_16x16x32_bf16 v[80:83], v[136:139], v[224:227], v[80:83]
	v_mfma_f32_16x16x32_bf16 v[76:79], v[192:195], v[224:227], v[76:79]
	s_barrier
	s_add_i32 s58, 0, 0x14000
	v_add_u32_e32 v0, s58, v189
	s_add_i32 s55, s55, s24
	ds_read_b128 v[228:231], v0
	ds_read_b128 v[232:235], v0 offset:1024
	ds_read_b128 v[236:239], v0 offset:2048
	ds_read_b128 v[240:243], v0 offset:3072
	v_lshl_add_u64 v[0:1], s[14:15], 0, v[144:145]
	s_mov_b32 m0, s55
	v_lshl_add_u64 v[244:245], s[14:15], 0, v[140:141]
	global_load_lds_dwordx4 v[0:1], off
	s_add_i32 m0, s55, 0x2000
	s_nop 0
	global_load_lds_dwordx4 v[244:245], off
	s_barrier
	s_waitcnt lgkmcnt(3)
	v_mfma_f32_16x16x32_bf16 v[120:123], v[228:231], v[196:199], v[120:123]
	s_waitcnt lgkmcnt(1)
	v_mfma_f32_16x16x32_bf16 v[116:119], v[236:239], v[196:199], v[116:119]
	v_mfma_f32_16x16x32_bf16 v[104:107], v[228:231], v[204:207], v[104:107]
	v_mfma_f32_16x16x32_bf16 v[100:103], v[236:239], v[204:207], v[100:103]
	v_mfma_f32_16x16x32_bf16 v[88:91], v[228:231], v[212:215], v[88:91]
	v_mfma_f32_16x16x32_bf16 v[84:87], v[236:239], v[212:215], v[84:87]
	v_mfma_f32_16x16x32_bf16 v[72:75], v[228:231], v[220:223], v[72:75]
	v_mfma_f32_16x16x32_bf16 v[68:71], v[236:239], v[220:223], v[68:71]
	v_mfma_f32_16x16x32_bf16 v[120:123], v[232:235], v[200:203], v[120:123]
	s_waitcnt lgkmcnt(0)
	v_mfma_f32_16x16x32_bf16 v[116:119], v[240:243], v[200:203], v[116:119]
	v_mfma_f32_16x16x32_bf16 v[104:107], v[232:235], v[208:211], v[104:107]
	v_mfma_f32_16x16x32_bf16 v[100:103], v[240:243], v[208:211], v[100:103]
	v_mfma_f32_16x16x32_bf16 v[88:91], v[232:235], v[216:219], v[88:91]
	v_mfma_f32_16x16x32_bf16 v[84:87], v[240:243], v[216:219], v[84:87]
	v_mfma_f32_16x16x32_bf16 v[72:75], v[232:235], v[224:227], v[72:75]
	v_mfma_f32_16x16x32_bf16 v[68:71], v[240:243], v[224:227], v[68:71]
	s_mov_b32 m0, s25
	v_lshl_add_u64 v[246:247], s[18:19], 0, v[146:147]
	s_barrier
	ds_read_b128 v[196:199], v191 offset:16384
	ds_read_b128 v[200:203], v191 offset:17408
	ds_read_b128 v[204:207], v191 offset:18432
	ds_read_b128 v[208:211], v191 offset:19456
	ds_read_b128 v[212:215], v191 offset:20480
	ds_read_b128 v[216:219], v191 offset:21504
	ds_read_b128 v[220:223], v191 offset:22528
	ds_read_b128 v[224:227], v191 offset:23552
	global_load_lds_dwordx4 v[246:247], off
	v_lshl_add_u64 v[248:249], s[18:19], 0, v[142:143]
	s_mov_b32 m0, s42
	s_nop 0
	global_load_lds_dwordx4 v[248:249], off
	s_barrier
	s_waitcnt lgkmcnt(7)
	v_mfma_f32_16x16x32_bf16 v[64:67], v[132:135], v[196:199], v[64:67]
	v_mfma_f32_16x16x32_bf16 v[60:63], v[176:179], v[196:199], v[60:63]
	s_waitcnt lgkmcnt(5)
	v_mfma_f32_16x16x32_bf16 v[48:51], v[132:135], v[204:207], v[48:51]
	v_mfma_f32_16x16x32_bf16 v[44:47], v[176:179], v[204:207], v[44:47]
	s_waitcnt lgkmcnt(3)
	v_mfma_f32_16x16x32_bf16 v[32:35], v[132:135], v[212:215], v[32:35]
	v_mfma_f32_16x16x32_bf16 v[28:31], v[176:179], v[212:215], v[28:31]
	s_waitcnt lgkmcnt(1)
	v_mfma_f32_16x16x32_bf16 v[16:19], v[132:135], v[220:223], v[16:19]
	v_mfma_f32_16x16x32_bf16 v[12:15], v[176:179], v[220:223], v[12:15]
	v_mfma_f32_16x16x32_bf16 v[64:67], v[136:139], v[200:203], v[64:67]
	v_mfma_f32_16x16x32_bf16 v[60:63], v[192:195], v[200:203], v[60:63]
	v_mfma_f32_16x16x32_bf16 v[48:51], v[136:139], v[208:211], v[48:51]
	v_mfma_f32_16x16x32_bf16 v[44:47], v[192:195], v[208:211], v[44:47]
	v_mfma_f32_16x16x32_bf16 v[32:35], v[136:139], v[216:219], v[32:35]
	v_mfma_f32_16x16x32_bf16 v[28:31], v[192:195], v[216:219], v[28:31]
	s_waitcnt lgkmcnt(0)
	v_mfma_f32_16x16x32_bf16 v[16:19], v[136:139], v[224:227], v[16:19]
	v_mfma_f32_16x16x32_bf16 v[12:15], v[192:195], v[224:227], v[12:15]
	s_barrier
; #define PG8_STAGE(bufoff, gbase, voff) do { _Pragma("unroll") for (int _i = 0; _i < 2; ++_i) \
;         __builtin_amdgcn_global_load_lds((const unsigned*)((const char*)(gbase) + (voff)[_i]), (LAS unsigned*)(lds + (bufoff) + ldsw + _i * 8192), 16, 0, 0); } while (0)
; #define PG8_LDA(dst, b, h) do { _Pragma("unroll") for (int m = 0; m < 4; ++m) _Pragma("unroll") for (int k = 0; k < 2; ++k) dst[m][k] = *(const LAS h8*)(lds + PG8_SA(b, h) + aoff + m * 2048 + k * 1024); } while (0)
; #define PG8_LDB(dst, b, h) do { _Pragma("unroll") for (int n = 0; n < 2; ++n) _Pragma("unroll") for (int k = 0; k < 2; ++k) dst[n][k] = *(const LAS h8*)(lds + PG8_SB(b, h) + boff + n * 2048 + k * 1024); } while (0)
; #define PG8_WAIT_V(n) asm volatile("s_waitcnt vmcnt(" #n ")" ::: "memory")
; #define PG8_WAIT_L(n) asm volatile("s_waitcnt lgkmcnt(" #n ")" ::: "memory")
; #define PG8_BAR __builtin_amdgcn_s_barrier()
; #define PG8_SCHED __builtin_amdgcn_sched_barrier(0)
; template <class Epi>
; __device__ __forceinline__ void gemm_phase(LAS unsigned char* lds, const Gemm g, const StaticOrder& S, const Epi& E, const int tid) {
;     ...
;             PG8_STAGE(PG8_SB(0, 1), b2 + hstepB, voffB);
;             PG8_WAIT_V(6); PG8_BAR; PG8_MMA(1, 1, At, B1); PG8_BAR;
;             PG8_LDB(B0, 1, 0); PG8_SCHED; PG8_LDA(At, 1, 0); PG8_STAGE(PG8_SA(0, 1), a2 + hstep, voffA);
;             PG8_WAIT_L(8); PG8_BAR; PG8_WAIT_L(0); PG8_MMA(0, 0, At, B0); PG8_BAR; PG8_SCHED;
;             PG8_LDB(B1, 1, 1); PG8_STAGE(PG8_SB(1, 0), b3, voffB);
;             PG8_BAR; PG8_WAIT_L(0); PG8_MMA(0, 1, At, B1); PG8_BAR;
;             PG8_LDA(At, 1, 1); PG8_STAGE(PG8_SA(1, 0), a3, voffA);
	s_add_u32 s56, s14, 0x100000
	s_addc_u32 s57, s15, 0
	s_add_i32 s55, s58, s24
	s_mov_b32 m0, s55
	s_nop 0
	global_load_lds_dwordx4 v144, s[56:57]
	s_add_i32 m0, s55, 0x2000
	s_nop 0
	global_load_lds_dwordx4 v140, s[56:57]
	s_waitcnt vmcnt(6)
	s_barrier
	v_mfma_f32_16x16x32_bf16 v[56:59], v[228:231], v[196:199], v[56:59]
	v_mfma_f32_16x16x32_bf16 v[52:55], v[236:239], v[196:199], v[52:55]
	v_mfma_f32_16x16x32_bf16 v[40:43], v[228:231], v[204:207], v[40:43]
	v_mfma_f32_16x16x32_bf16 v[36:39], v[236:239], v[204:207], v[36:39]
	v_mfma_f32_16x16x32_bf16 v[24:27], v[228:231], v[212:215], v[24:27]
	v_mfma_f32_16x16x32_bf16 v[20:23], v[236:239], v[212:215], v[20:23]
	v_mfma_f32_16x16x32_bf16 v[8:11], v[228:231], v[220:223], v[8:11]
	v_mfma_f32_16x16x32_bf16 v[4:7], v[236:239], v[220:223], v[4:7]
	v_mfma_f32_16x16x32_bf16 v[56:59], v[232:235], v[200:203], v[56:59]
	v_mfma_f32_16x16x32_bf16 v[52:55], v[240:243], v[200:203], v[52:55]
	v_mfma_f32_16x16x32_bf16 v[40:43], v[232:235], v[208:211], v[40:43]
	v_mfma_f32_16x16x32_bf16 v[36:39], v[240:243], v[208:211], v[36:39]
	v_mfma_f32_16x16x32_bf16 v[24:27], v[232:235], v[216:219], v[24:27]
	v_mfma_f32_16x16x32_bf16 v[20:23], v[240:243], v[216:219], v[20:23]
	v_mfma_f32_16x16x32_bf16 v[8:11], v[232:235], v[224:227], v[8:11]
	v_mfma_f32_16x16x32_bf16 v[4:7], v[240:243], v[224:227], v[4:7]
	s_add_i32 s55, 0, 0x18000
	v_add_u32_e32 v2, s55, v189
	s_barrier
	ds_read_b128 v[132:135], v2
	ds_read_b128 v[136:139], v2 offset:1024
	ds_read_b128 v[176:179], v2 offset:2048
	ds_read_b128 v[192:195], v2 offset:3072
	s_add_u32 s18, s18, 0x100000
	s_addc_u32 s19, s19, 0
	s_mov_b32 m0, s43
	ds_read_b128 v[196:199], v191 offset:32768
	ds_read_b128 v[200:203], v191 offset:33792
	ds_read_b128 v[204:207], v191 offset:34816
	ds_read_b128 v[208:211], v191 offset:35840
	ds_read_b128 v[212:215], v191 offset:36864
	ds_read_b128 v[216:219], v191 offset:37888
	ds_read_b128 v[220:223], v191 offset:38912
	ds_read_b128 v[224:227], v191 offset:39936
	global_load_lds_dwordx4 v146, s[18:19]
	s_mov_b32 m0, s46
	s_nop 0
	global_load_lds_dwordx4 v142, s[18:19]
	s_waitcnt lgkmcnt(8)
	s_barrier
	s_waitcnt lgkmcnt(7)
	v_mfma_f32_16x16x32_bf16 v[128:131], v[132:135], v[196:199], v[128:131]
	v_mfma_f32_16x16x32_bf16 v[124:127], v[176:179], v[196:199], v[124:127]
	s_waitcnt lgkmcnt(5)
	v_mfma_f32_16x16x32_bf16 v[112:115], v[132:135], v[204:207], v[112:115]
	v_mfma_f32_16x16x32_bf16 v[108:111], v[176:179], v[204:207], v[108:111]
	s_waitcnt lgkmcnt(3)
	v_mfma_f32_16x16x32_bf16 v[96:99], v[132:135], v[212:215], v[96:99]
	v_mfma_f32_16x16x32_bf16 v[92:95], v[176:179], v[212:215], v[92:95]
	s_waitcnt lgkmcnt(1)
	v_mfma_f32_16x16x32_bf16 v[80:83], v[132:135], v[220:223], v[80:83]
	v_mfma_f32_16x16x32_bf16 v[76:79], v[176:179], v[220:223], v[76:79]
	v_mfma_f32_16x16x32_bf16 v[128:131], v[136:139], v[200:203], v[128:131]
	v_mfma_f32_16x16x32_bf16 v[124:127], v[192:195], v[200:203], v[124:127]
	v_mfma_f32_16x16x32_bf16 v[112:115], v[136:139], v[208:211], v[112:115]
	v_mfma_f32_16x16x32_bf16 v[108:111], v[192:195], v[208:211], v[108:111]
	v_mfma_f32_16x16x32_bf16 v[96:99], v[136:139], v[216:219], v[96:99]
	v_mfma_f32_16x16x32_bf16 v[92:95], v[192:195], v[216:219], v[92:95]
	s_waitcnt lgkmcnt(0)
	v_mfma_f32_16x16x32_bf16 v[80:83], v[136:139], v[224:227], v[80:83]
	v_mfma_f32_16x16x32_bf16 v[76:79], v[192:195], v[224:227], v[76:79]
	s_barrier
	s_add_i32 s18, 0, 0x1c000
	s_add_i32 s19, s55, s24
	v_add_u32_e32 v2, s18, v189
	v_lshl_add_u64 v[0:1], v[0:1], 0, s[30:31]
	s_mov_b32 m0, s19
	ds_read_b128 v[228:231], v2
	ds_read_b128 v[232:235], v2 offset:1024
	ds_read_b128 v[236:239], v2 offset:2048
	ds_read_b128 v[240:243], v2 offset:3072
	global_load_lds_dwordx4 v[0:1], off
	v_lshl_add_u64 v[0:1], v[244:245], 0, s[30:31]
	s_add_i32 m0, s19, 0x2000
	s_nop 0
	global_load_lds_dwordx4 v[0:1], off
	s_barrier
; #define PG8_STAGE(bufoff, gbase, voff) do { _Pragma("unroll") for (int _i = 0; _i < 2; ++_i) \
;         __builtin_amdgcn_global_load_lds((const unsigned*)((const char*)(gbase) + (voff)[_i]), (LAS unsigned*)(lds + (bufoff) + ldsw + _i * 8192), 16, 0, 0); } while (0)
; #define PG8_LDA(dst, b, h) do { _Pragma("unroll") for (int m = 0; m < 4; ++m) _Pragma("unroll") for (int k = 0; k < 2; ++k) dst[m][k] = *(const LAS h8*)(lds + PG8_SA(b, h) + aoff + m * 2048 + k * 1024); } while (0)
; #define PG8_WAIT_V(n) asm volatile("s_waitcnt vmcnt(" #n ")" ::: "memory")
; #define PG8_WAIT_L(n) asm volatile("s_waitcnt lgkmcnt(" #n ")" ::: "memory")
; #define PG8_BAR __builtin_amdgcn_s_barrier()
; #define PG8_SCHED __builtin_amdgcn_sched_barrier(0)
; template <class Epi>
; __device__ __forceinline__ void gemm_phase(LAS unsigned char* lds, const Gemm g, const StaticOrder& S, const Epi& E, const int tid) {
;     ...
;             PG8_BAR; PG8_WAIT_L(0); PG8_MMA(0, 1, At, B1); PG8_BAR;
;             PG8_LDA(At, 1, 1); PG8_STAGE(PG8_SA(1, 0), a3, voffA);
;             PG8_BAR; PG8_WAIT_L(0); PG8_MMA(1, 0, At, B0); PG8_BAR; PG8_SCHED;
;             PG8_STAGE(PG8_SB(1, 1), b3 + hstepB, voffB);
;             PG8_WAIT_V(6); PG8_BAR; PG8_MMA(1, 1, At, B1); PG8_BAR;
;         }
	s_waitcnt lgkmcnt(3)
	v_mfma_f32_16x16x32_bf16 v[120:123], v[228:231], v[196:199], v[120:123]
	s_waitcnt lgkmcnt(1)
	v_mfma_f32_16x16x32_bf16 v[116:119], v[236:239], v[196:199], v[116:119]
	v_mfma_f32_16x16x32_bf16 v[104:107], v[228:231], v[204:207], v[104:107]
	v_mfma_f32_16x16x32_bf16 v[100:103], v[236:239], v[204:207], v[100:103]
	v_mfma_f32_16x16x32_bf16 v[88:91], v[228:231], v[212:215], v[88:91]
	v_mfma_f32_16x16x32_bf16 v[84:87], v[236:239], v[212:215], v[84:87]
	v_mfma_f32_16x16x32_bf16 v[72:75], v[228:231], v[220:223], v[72:75]
	v_mfma_f32_16x16x32_bf16 v[68:71], v[236:239], v[220:223], v[68:71]
	v_mfma_f32_16x16x32_bf16 v[120:123], v[232:235], v[200:203], v[120:123]
	s_waitcnt lgkmcnt(0)
	v_mfma_f32_16x16x32_bf16 v[116:119], v[240:243], v[200:203], v[116:119]
	v_mfma_f32_16x16x32_bf16 v[104:107], v[232:235], v[208:211], v[104:107]
	v_mfma_f32_16x16x32_bf16 v[100:103], v[240:243], v[208:211], v[100:103]
	v_mfma_f32_16x16x32_bf16 v[88:91], v[232:235], v[216:219], v[88:91]
	v_mfma_f32_16x16x32_bf16 v[84:87], v[240:243], v[216:219], v[84:87]
	v_mfma_f32_16x16x32_bf16 v[72:75], v[232:235], v[224:227], v[72:75]
	v_mfma_f32_16x16x32_bf16 v[68:71], v[240:243], v[224:227], v[68:71]
	s_mov_b32 m0, s47
	v_lshl_add_u64 v[0:1], v[246:247], 0, s[30:31]
	s_barrier
	ds_read_b128 v[196:199], v191 offset:49152
	ds_read_b128 v[200:203], v191 offset:50176
	ds_read_b128 v[204:207], v191 offset:51200
	ds_read_b128 v[208:211], v191 offset:52224
	ds_read_b128 v[212:215], v191 offset:53248
	ds_read_b128 v[216:219], v191 offset:54272
	ds_read_b128 v[220:223], v191 offset:55296
	ds_read_b128 v[224:227], v191 offset:56320
	global_load_lds_dwordx4 v[0:1], off
	v_lshl_add_u64 v[0:1], v[248:249], 0, s[30:31]
	s_mov_b32 m0, s48
	s_nop 0
	global_load_lds_dwordx4 v[0:1], off
	s_barrier
	s_waitcnt lgkmcnt(7)
	v_mfma_f32_16x16x32_bf16 v[64:67], v[132:135], v[196:199], v[64:67]
	v_mfma_f32_16x16x32_bf16 v[60:63], v[176:179], v[196:199], v[60:63]
	s_waitcnt lgkmcnt(5)
	v_mfma_f32_16x16x32_bf16 v[48:51], v[132:135], v[204:207], v[48:51]
	v_mfma_f32_16x16x32_bf16 v[44:47], v[176:179], v[204:207], v[44:47]
	s_waitcnt lgkmcnt(3)
	v_mfma_f32_16x16x32_bf16 v[32:35], v[132:135], v[212:215], v[32:35]
	v_mfma_f32_16x16x32_bf16 v[28:31], v[176:179], v[212:215], v[28:31]
	s_waitcnt lgkmcnt(1)
	v_mfma_f32_16x16x32_bf16 v[16:19], v[132:135], v[220:223], v[16:19]
	v_mfma_f32_16x16x32_bf16 v[12:15], v[176:179], v[220:223], v[12:15]
	v_mfma_f32_16x16x32_bf16 v[64:67], v[136:139], v[200:203], v[64:67]
	v_mfma_f32_16x16x32_bf16 v[60:63], v[192:195], v[200:203], v[60:63]
	v_mfma_f32_16x16x32_bf16 v[48:51], v[136:139], v[208:211], v[48:51]
	v_mfma_f32_16x16x32_bf16 v[44:47], v[192:195], v[208:211], v[44:47]
	v_mfma_f32_16x16x32_bf16 v[32:35], v[136:139], v[216:219], v[32:35]
	v_mfma_f32_16x16x32_bf16 v[28:31], v[192:195], v[216:219], v[28:31]
	s_waitcnt lgkmcnt(0)
	v_mfma_f32_16x16x32_bf16 v[16:19], v[136:139], v[224:227], v[16:19]
	v_mfma_f32_16x16x32_bf16 v[12:15], v[192:195], v[224:227], v[12:15]
	s_barrier
	s_add_u32 s14, s14, 0x100080
	s_addc_u32 s15, s15, 0
	s_add_i32 s18, s18, s24
	s_mov_b32 m0, s18
	s_nop 0
	global_load_lds_dwordx4 v144, s[14:15]
	s_add_i32 m0, s18, 0x2000
	s_nop 0
	global_load_lds_dwordx4 v140, s[14:15]
	s_waitcnt vmcnt(6)
	s_barrier
	v_mfma_f32_16x16x32_bf16 v[56:59], v[228:231], v[196:199], v[56:59]
	v_mfma_f32_16x16x32_bf16 v[52:55], v[236:239], v[196:199], v[52:55]
	v_mfma_f32_16x16x32_bf16 v[40:43], v[228:231], v[204:207], v[40:43]
	v_mfma_f32_16x16x32_bf16 v[36:39], v[236:239], v[204:207], v[36:39]
	v_mfma_f32_16x16x32_bf16 v[24:27], v[228:231], v[212:215], v[24:27]
	v_mfma_f32_16x16x32_bf16 v[20:23], v[236:239], v[212:215], v[20:23]
	v_mfma_f32_16x16x32_bf16 v[8:11], v[228:231], v[220:223], v[8:11]
	v_mfma_f32_16x16x32_bf16 v[4:7], v[236:239], v[220:223], v[4:7]
	v_mfma_f32_16x16x32_bf16 v[56:59], v[232:235], v[200:203], v[56:59]
	v_mfma_f32_16x16x32_bf16 v[52:55], v[240:243], v[200:203], v[52:55]
	v_mfma_f32_16x16x32_bf16 v[40:43], v[232:235], v[208:211], v[40:43]
	v_mfma_f32_16x16x32_bf16 v[36:39], v[240:243], v[208:211], v[36:39]
	v_mfma_f32_16x16x32_bf16 v[24:27], v[232:235], v[216:219], v[24:27]
	v_mfma_f32_16x16x32_bf16 v[20:23], v[240:243], v[216:219], v[20:23]
	v_mfma_f32_16x16x32_bf16 v[8:11], v[232:235], v[224:227], v[8:11]
	v_mfma_f32_16x16x32_bf16 v[4:7], v[240:243], v[224:227], v[4:7]
	s_add_i32 s54, s54, 2
	s_add_u32 s12, s12, 0x100
	s_addc_u32 s13, s13, 0
	s_cmp_gt_u32 s54, 61
	s_barrier
	s_cbranch_scc1 .LBB0_586

; #define PG8_STAGE(bufoff, gbase, voff) do { _Pragma("unroll") for (int _i = 0; _i < 2; ++_i) \
;         __builtin_amdgcn_global_load_lds((const unsigned*)((const char*)(gbase) + (voff)[_i]), (LAS unsigned*)(lds + (bufoff) + ldsw + _i * 8192), 16, 0, 0); } while (0)
; #define PG8_LDA(dst, b, h) do { _Pragma("unroll") for (int m = 0; m < 4; ++m) _Pragma("unroll") for (int k = 0; k < 2; ++k) dst[m][k] = *(const LAS h8*)(lds + PG8_SA(b, h) + aoff + m * 2048 + k * 1024); } while (0)
; #define PG8_LDB(dst, b, h) do { _Pragma("unroll") for (int n = 0; n < 2; ++n) _Pragma("unroll") for (int k = 0; k < 2; ++k) dst[n][k] = *(const LAS h8*)(lds + PG8_SB(b, h) + boff + n * 2048 + k * 1024); } while (0)
; #define PG8_WAIT_L(n) asm volatile("s_waitcnt lgkmcnt(" #n ")" ::: "memory")
; #define PG8_BAR __builtin_amdgcn_s_barrier()
; #define PG8_SCHED __builtin_amdgcn_sched_barrier(0)
; template <class Epi>
; __device__ __forceinline__ void gemm_phase(LAS unsigned char* lds, const Gemm g, const StaticOrder& S, const Epi& E, const int tid) {
;     ...
;         for (int t = 0; t < nt; t += 2) {
;             const bool last = (t == nt - 2);
;             const char* a1 = cA + (size_t)(t + 1) * kstep;
;             const char* a2 = last ? nA : cA + (size_t)(t + 2) * kstep; const char* b2 = last ? nB : cB + (size_t)(t + 2) * kstep;
;             const char* a3 = a2 + kstep; const char* b3 = b2 + kstep;
;             if constexpr (Epi::HAS_MID) { if (t == (nt >> 1)) E.mid(acc, cur, wr, wc, fr, fq); }
;             PG8_LDB(B0, 0, 0); PG8_SCHED; PG8_LDA(At, 0, 0); PG8_STAGE(PG8_SA(1, 1), a1 + hstep, voffA);
;             PG8_WAIT_L(8); PG8_BAR; PG8_WAIT_L(0); PG8_MMA(0, 0, At, B0); PG8_BAR; PG8_SCHED;
;             PG8_LDB(B1, 0, 1); PG8_STAGE(PG8_SB(0, 0), b2, voffB);
;             PG8_BAR; PG8_WAIT_L(0); PG8_MMA(0, 1, At, B1); PG8_BAR;
;             PG8_LDA(At, 0, 1); PG8_STAGE(PG8_SA(0, 0), a2, voffA);
;             PG8_BAR; PG8_WAIT_L(0); PG8_MMA(1, 0, At, B0); PG8_BAR; PG8_SCHED;
.LBB0_660:
	s_add_u32 s14, s12, 0xfff80080
	s_addc_u32 s15, s13, -1
	s_add_i32 s57, 0, 0x10000
	v_add_u32_e32 v64, s57, v190
	ds_read_b128 v[28:31], v64
	ds_read_b128 v[32:35], v64 offset:1024
	ds_read_b128 v[60:63], v64 offset:2048
	ds_read_b128 v[64:67], v64 offset:3072
	s_cmp_eq_u32 s56, 28
	s_cselect_b32 s19, s7, s15
	s_cselect_b32 s18, s52, s14
	s_cselect_b32 s15, s1, s55
	s_cselect_b32 s14, s53, s54
	s_add_i32 m0, s41, 0xc000
	ds_read_b128 v[170:173], v192
	ds_read_b128 v[194:197], v192 offset:1024
	ds_read_b128 v[198:201], v192 offset:2048
	ds_read_b128 v[202:205], v192 offset:3072
	ds_read_b128 v[206:209], v192 offset:4096
	ds_read_b128 v[210:213], v192 offset:5120
	ds_read_b128 v[214:217], v192 offset:6144
	ds_read_b128 v[218:221], v192 offset:7168
	global_load_lds_dwordx4 v166, s[12:13]
	v_lshl_add_u64 v[174:175], s[12:13], 0, v[168:169]
	s_add_i32 m0, s41, 0xe000
	s_nop 0
	global_load_lds_dwordx4 v[174:175], off
	s_waitcnt lgkmcnt(8)
	s_barrier
	s_waitcnt lgkmcnt(7)
	v_mfma_f32_16x16x32_bf16 v[144:147], v[28:31], v[170:173], v[144:147]
	v_mfma_f32_16x16x32_bf16 v[140:143], v[60:63], v[170:173], v[140:143]
	s_waitcnt lgkmcnt(5)
	v_mfma_f32_16x16x32_bf16 v[128:131], v[28:31], v[198:201], v[128:131]
	v_mfma_f32_16x16x32_bf16 v[124:127], v[60:63], v[198:201], v[124:127]
	s_waitcnt lgkmcnt(3)
	v_mfma_f32_16x16x32_bf16 v[112:115], v[28:31], v[206:209], v[112:115]
	v_mfma_f32_16x16x32_bf16 v[108:111], v[60:63], v[206:209], v[108:111]
	s_waitcnt lgkmcnt(1)
	v_mfma_f32_16x16x32_bf16 v[96:99], v[28:31], v[214:217], v[96:99]
	v_mfma_f32_16x16x32_bf16 v[92:95], v[60:63], v[214:217], v[92:95]
	v_mfma_f32_16x16x32_bf16 v[144:147], v[32:35], v[194:197], v[144:147]
	v_mfma_f32_16x16x32_bf16 v[140:143], v[64:67], v[194:197], v[140:143]
	v_mfma_f32_16x16x32_bf16 v[128:131], v[32:35], v[202:205], v[128:131]
	v_mfma_f32_16x16x32_bf16 v[124:127], v[64:67], v[202:205], v[124:127]
	v_mfma_f32_16x16x32_bf16 v[112:115], v[32:35], v[210:213], v[112:115]
	v_mfma_f32_16x16x32_bf16 v[108:111], v[64:67], v[210:213], v[108:111]
	s_waitcnt lgkmcnt(0)
	v_mfma_f32_16x16x32_bf16 v[96:99], v[32:35], v[218:221], v[96:99]
	v_mfma_f32_16x16x32_bf16 v[92:95], v[64:67], v[218:221], v[92:95]
	s_barrier
	s_add_i32 s60, 0, 0x14000
	v_add_u32_e32 v174, s60, v190
	s_add_i32 s57, s57, s40
	ds_read_b128 v[222:225], v174
	ds_read_b128 v[226:229], v174 offset:1024
	ds_read_b128 v[230:233], v174 offset:2048
	ds_read_b128 v[234:237], v174 offset:3072
	v_lshl_add_u64 v[174:175], s[14:15], 0, v[2:3]
	s_mov_b32 m0, s57
	v_lshl_add_u64 v[238:239], s[14:15], 0, v[0:1]
	global_load_lds_dwordx4 v[174:175], off
	s_add_i32 m0, s57, 0x2000
	s_nop 0
	global_load_lds_dwordx4 v[238:239], off
	s_barrier
	s_waitcnt lgkmcnt(3)
	v_mfma_f32_16x16x32_bf16 v[136:139], v[222:225], v[170:173], v[136:139]
	s_waitcnt lgkmcnt(1)
	v_mfma_f32_16x16x32_bf16 v[132:135], v[230:233], v[170:173], v[132:135]
	v_mfma_f32_16x16x32_bf16 v[120:123], v[222:225], v[198:201], v[120:123]
	v_mfma_f32_16x16x32_bf16 v[116:119], v[230:233], v[198:201], v[116:119]
	v_mfma_f32_16x16x32_bf16 v[104:107], v[222:225], v[206:209], v[104:107]
	v_mfma_f32_16x16x32_bf16 v[100:103], v[230:233], v[206:209], v[100:103]
	v_mfma_f32_16x16x32_bf16 v[88:91], v[222:225], v[214:217], v[88:91]
	v_mfma_f32_16x16x32_bf16 v[84:87], v[230:233], v[214:217], v[84:87]
	v_mfma_f32_16x16x32_bf16 v[136:139], v[226:229], v[194:197], v[136:139]
	s_waitcnt lgkmcnt(0)
	v_mfma_f32_16x16x32_bf16 v[132:135], v[234:237], v[194:197], v[132:135]
	v_mfma_f32_16x16x32_bf16 v[120:123], v[226:229], v[202:205], v[120:123]
	v_mfma_f32_16x16x32_bf16 v[116:119], v[234:237], v[202:205], v[116:119]
	v_mfma_f32_16x16x32_bf16 v[104:107], v[226:229], v[210:213], v[104:107]
	v_mfma_f32_16x16x32_bf16 v[100:103], v[234:237], v[210:213], v[100:103]
	v_mfma_f32_16x16x32_bf16 v[88:91], v[226:229], v[218:221], v[88:91]
	v_mfma_f32_16x16x32_bf16 v[84:87], v[234:237], v[218:221], v[84:87]
	s_mov_b32 m0, s41
	v_lshl_add_u64 v[240:241], s[18:19], 0, v[164:165]
	s_barrier
	ds_read_b128 v[170:173], v192 offset:16384
	ds_read_b128 v[194:197], v192 offset:17408
	ds_read_b128 v[198:201], v192 offset:18432
	ds_read_b128 v[202:205], v192 offset:19456
	ds_read_b128 v[206:209], v192 offset:20480
	ds_read_b128 v[210:213], v192 offset:21504
	ds_read_b128 v[214:217], v192 offset:22528
	ds_read_b128 v[218:221], v192 offset:23552
	global_load_lds_dwordx4 v[240:241], off
	v_lshl_add_u64 v[242:243], s[18:19], 0, v[162:163]
	s_mov_b32 m0, s42
	s_nop 0
	global_load_lds_dwordx4 v[242:243], off
	s_barrier
	s_waitcnt lgkmcnt(7)
	v_mfma_f32_16x16x32_bf16 v[80:83], v[28:31], v[170:173], v[80:83]
	v_mfma_f32_16x16x32_bf16 v[76:79], v[60:63], v[170:173], v[76:79]
	s_waitcnt lgkmcnt(5)
	v_mfma_f32_16x16x32_bf16 v[56:59], v[28:31], v[198:201], v[56:59]
	v_mfma_f32_16x16x32_bf16 v[52:55], v[60:63], v[198:201], v[52:55]
	s_waitcnt lgkmcnt(3)
	v_mfma_f32_16x16x32_bf16 v[40:43], v[28:31], v[206:209], v[40:43]
	v_mfma_f32_16x16x32_bf16 v[36:39], v[60:63], v[206:209], v[36:39]
	s_waitcnt lgkmcnt(1)
	v_mfma_f32_16x16x32_bf16 v[16:19], v[28:31], v[214:217], v[16:19]
	v_mfma_f32_16x16x32_bf16 v[12:15], v[60:63], v[214:217], v[12:15]
	v_mfma_f32_16x16x32_bf16 v[80:83], v[32:35], v[194:197], v[80:83]
	v_mfma_f32_16x16x32_bf16 v[76:79], v[64:67], v[194:197], v[76:79]
	v_mfma_f32_16x16x32_bf16 v[56:59], v[32:35], v[202:205], v[56:59]
	v_mfma_f32_16x16x32_bf16 v[52:55], v[64:67], v[202:205], v[52:55]
	v_mfma_f32_16x16x32_bf16 v[40:43], v[32:35], v[210:213], v[40:43]
	v_mfma_f32_16x16x32_bf16 v[36:39], v[64:67], v[210:213], v[36:39]
	s_waitcnt lgkmcnt(0)
	v_mfma_f32_16x16x32_bf16 v[16:19], v[32:35], v[218:221], v[16:19]
	v_mfma_f32_16x16x32_bf16 v[12:15], v[64:67], v[218:221], v[12:15]
	s_barrier
; #define PG8_STAGE(bufoff, gbase, voff) do { _Pragma("unroll") for (int _i = 0; _i < 2; ++_i) \
;         __builtin_amdgcn_global_load_lds((const unsigned*)((const char*)(gbase) + (voff)[_i]), (LAS unsigned*)(lds + (bufoff) + ldsw + _i * 8192), 16, 0, 0); } while (0)
; #define PG8_LDA(dst, b, h) do { _Pragma("unroll") for (int m = 0; m < 4; ++m) _Pragma("unroll") for (int k = 0; k < 2; ++k) dst[m][k] = *(const LAS h8*)(lds + PG8_SA(b, h) + aoff + m * 2048 + k * 1024); } while (0)
; #define PG8_LDB(dst, b, h) do { _Pragma("unroll") for (int n = 0; n < 2; ++n) _Pragma("unroll") for (int k = 0; k < 2; ++k) dst[n][k] = *(const LAS h8*)(lds + PG8_SB(b, h) + boff + n * 2048 + k * 1024); } while (0)
; #define PG8_WAIT_V(n) asm volatile("s_waitcnt vmcnt(" #n ")" ::: "memory")
; #define PG8_WAIT_L(n) asm volatile("s_waitcnt lgkmcnt(" #n ")" ::: "memory")
; #define PG8_BAR __builtin_amdgcn_s_barrier()
; #define PG8_SCHED __builtin_amdgcn_sched_barrier(0)
; template <class Epi>
; __device__ __forceinline__ void gemm_phase(LAS unsigned char* lds, const Gemm g, const StaticOrder& S, const Epi& E, const int tid) {
;     ...
;             PG8_STAGE(PG8_SB(0, 1), b2 + hstepB, voffB);
;             PG8_WAIT_V(6); PG8_BAR; PG8_MMA(1, 1, At, B1); PG8_BAR;
;             PG8_LDB(B0, 1, 0); PG8_SCHED; PG8_LDA(At, 1, 0); PG8_STAGE(PG8_SA(0, 1), a2 + hstep, voffA);
;             PG8_WAIT_L(8); PG8_BAR; PG8_WAIT_L(0); PG8_MMA(0, 0, At, B0); PG8_BAR; PG8_SCHED;
;             PG8_LDB(B1, 1, 1); PG8_STAGE(PG8_SB(1, 0), b3, voffB);
;             PG8_BAR; PG8_WAIT_L(0); PG8_MMA(0, 1, At, B1); PG8_BAR;
;             PG8_LDA(At, 1, 1); PG8_STAGE(PG8_SA(1, 0), a3, voffA);
	s_add_u32 s58, s14, 0x80000
	s_addc_u32 s59, s15, 0
	s_add_i32 s57, s60, s40
	s_mov_b32 m0, s57
	s_nop 0
	global_load_lds_dwordx4 v2, s[58:59]
	v_lshl_add_u64 v[28:29], s[58:59], 0, v[0:1]
	s_add_i32 m0, s57, 0x2000
	s_nop 0
	global_load_lds_dwordx4 v[28:29], off
	s_waitcnt vmcnt(6)
	s_barrier
	v_mfma_f32_16x16x32_bf16 v[48:51], v[222:225], v[198:201], v[48:51]
	v_mfma_f32_16x16x32_bf16 v[44:47], v[230:233], v[198:201], v[44:47]
	v_mfma_f32_16x16x32_bf16 v[24:27], v[222:225], v[206:209], v[24:27]
	v_mfma_f32_16x16x32_bf16 v[20:23], v[230:233], v[206:209], v[20:23]
	v_mfma_f32_16x16x32_bf16 v[8:11], v[222:225], v[214:217], v[8:11]
	v_mfma_f32_16x16x32_bf16 v[4:7], v[230:233], v[214:217], v[4:7]
	v_mfma_f32_16x16x32_bf16 v[28:31], v[222:225], v[170:173], v[72:75]
	v_mfma_f32_16x16x32_bf16 v[32:35], v[230:233], v[170:173], v[68:71]
	v_mfma_f32_16x16x32_bf16 v[48:51], v[226:229], v[202:205], v[48:51]
	v_mfma_f32_16x16x32_bf16 v[44:47], v[234:237], v[202:205], v[44:47]
	v_mfma_f32_16x16x32_bf16 v[24:27], v[226:229], v[210:213], v[24:27]
	v_mfma_f32_16x16x32_bf16 v[20:23], v[234:237], v[210:213], v[20:23]
	v_mfma_f32_16x16x32_bf16 v[8:11], v[226:229], v[218:221], v[8:11]
	v_mfma_f32_16x16x32_bf16 v[4:7], v[234:237], v[218:221], v[4:7]
	v_mfma_f32_16x16x32_bf16 v[28:31], v[226:229], v[194:197], v[28:31]
	v_mfma_f32_16x16x32_bf16 v[32:35], v[234:237], v[194:197], v[32:35]
	s_add_i32 s57, 0, 0x18000
	v_add_u32_e32 v72, s57, v190
	s_barrier
	ds_read_b128 v[60:63], v72
	ds_read_b128 v[64:67], v72 offset:1024
	ds_read_b128 v[68:71], v72 offset:2048
	ds_read_b128 v[72:75], v72 offset:3072
	s_add_u32 s18, s18, 0x80000
	s_addc_u32 s19, s19, 0
	s_mov_b32 m0, s43
	ds_read_b128 v[170:173], v192 offset:32768
	ds_read_b128 v[194:197], v192 offset:33792
	ds_read_b128 v[198:201], v192 offset:34816
	ds_read_b128 v[202:205], v192 offset:35840
	ds_read_b128 v[206:209], v192 offset:36864
	ds_read_b128 v[210:213], v192 offset:37888
	ds_read_b128 v[214:217], v192 offset:38912
	ds_read_b128 v[218:221], v192 offset:39936
	global_load_lds_dwordx4 v164, s[18:19]
	s_mov_b32 m0, s46
	s_nop 0
	global_load_lds_dwordx4 v162, s[18:19]
	s_waitcnt lgkmcnt(8)
	s_barrier
	s_waitcnt lgkmcnt(7)
	v_mfma_f32_16x16x32_bf16 v[144:147], v[60:63], v[170:173], v[144:147]
	v_mfma_f32_16x16x32_bf16 v[140:143], v[68:71], v[170:173], v[140:143]
	s_waitcnt lgkmcnt(5)
	v_mfma_f32_16x16x32_bf16 v[128:131], v[60:63], v[198:201], v[128:131]
	v_mfma_f32_16x16x32_bf16 v[124:127], v[68:71], v[198:201], v[124:127]
	s_waitcnt lgkmcnt(3)
	v_mfma_f32_16x16x32_bf16 v[112:115], v[60:63], v[206:209], v[112:115]
	v_mfma_f32_16x16x32_bf16 v[108:111], v[68:71], v[206:209], v[108:111]
	s_waitcnt lgkmcnt(1)
	v_mfma_f32_16x16x32_bf16 v[96:99], v[60:63], v[214:217], v[96:99]
	v_mfma_f32_16x16x32_bf16 v[92:95], v[68:71], v[214:217], v[92:95]
	v_mfma_f32_16x16x32_bf16 v[144:147], v[64:67], v[194:197], v[144:147]
	v_mfma_f32_16x16x32_bf16 v[140:143], v[72:75], v[194:197], v[140:143]
	v_mfma_f32_16x16x32_bf16 v[128:131], v[64:67], v[202:205], v[128:131]
	v_mfma_f32_16x16x32_bf16 v[124:127], v[72:75], v[202:205], v[124:127]
	v_mfma_f32_16x16x32_bf16 v[112:115], v[64:67], v[210:213], v[112:115]
	v_mfma_f32_16x16x32_bf16 v[108:111], v[72:75], v[210:213], v[108:111]
	s_waitcnt lgkmcnt(0)
	v_mfma_f32_16x16x32_bf16 v[96:99], v[64:67], v[218:221], v[96:99]
	v_mfma_f32_16x16x32_bf16 v[92:95], v[72:75], v[218:221], v[92:95]
	s_barrier
	s_add_i32 s18, 0, 0x1c000
	s_add_i32 s19, s57, s40
	v_add_u32_e32 v193, s18, v190
	v_lshl_add_u64 v[174:175], v[174:175], 0, s[30:31]
	s_mov_b32 m0, s19
	ds_read_b128 v[222:225], v193
	ds_read_b128 v[226:229], v193 offset:1024
	ds_read_b128 v[230:233], v193 offset:2048
	ds_read_b128 v[234:237], v193 offset:3072
	global_load_lds_dwordx4 v[174:175], off
	v_lshl_add_u64 v[174:175], v[238:239], 0, s[30:31]
	s_add_i32 m0, s19, 0x2000
	s_nop 0
	global_load_lds_dwordx4 v[174:175], off
	s_barrier
	s_waitcnt lgkmcnt(3)
	v_mfma_f32_16x16x32_bf16 v[136:139], v[222:225], v[170:173], v[136:139]
	s_waitcnt lgkmcnt(1)
	v_mfma_f32_16x16x32_bf16 v[132:135], v[230:233], v[170:173], v[132:135]
	v_mfma_f32_16x16x32_bf16 v[120:123], v[222:225], v[198:201], v[120:123]
	v_mfma_f32_16x16x32_bf16 v[116:119], v[230:233], v[198:201], v[116:119]
	v_mfma_f32_16x16x32_bf16 v[104:107], v[222:225], v[206:209], v[104:107]
	v_mfma_f32_16x16x32_bf16 v[100:103], v[230:233], v[206:209], v[100:103]
	v_mfma_f32_16x16x32_bf16 v[88:91], v[222:225], v[214:217], v[88:91]
	v_mfma_f32_16x16x32_bf16 v[84:87], v[230:233], v[214:217], v[84:87]
	v_mfma_f32_16x16x32_bf16 v[136:139], v[226:229], v[194:197], v[136:139]
	s_waitcnt lgkmcnt(0)
	v_mfma_f32_16x16x32_bf16 v[132:135], v[234:237], v[194:197], v[132:135]
	v_mfma_f32_16x16x32_bf16 v[120:123], v[226:229], v[202:205], v[120:123]
	v_mfma_f32_16x16x32_bf16 v[116:119], v[234:237], v[202:205], v[116:119]
	v_mfma_f32_16x16x32_bf16 v[104:107], v[226:229], v[210:213], v[104:107]
	v_mfma_f32_16x16x32_bf16 v[100:103], v[234:237], v[210:213], v[100:103]
	v_mfma_f32_16x16x32_bf16 v[88:91], v[226:229], v[218:221], v[88:91]
	v_mfma_f32_16x16x32_bf16 v[84:87], v[234:237], v[218:221], v[84:87]
	s_mov_b32 m0, s47
	v_lshl_add_u64 v[174:175], v[240:241], 0, s[30:31]
	s_barrier
	ds_read_b128 v[170:173], v192 offset:49152
	ds_read_b128 v[194:197], v192 offset:50176
	ds_read_b128 v[198:201], v192 offset:51200
	ds_read_b128 v[202:205], v192 offset:52224
	ds_read_b128 v[206:209], v192 offset:53248
	ds_read_b128 v[210:213], v192 offset:54272
	ds_read_b128 v[214:217], v192 offset:55296
	ds_read_b128 v[218:221], v192 offset:56320
	global_load_lds_dwordx4 v[174:175], off
	v_lshl_add_u64 v[174:175], v[242:243], 0, s[30:31]
	s_mov_b32 m0, s48
	s_nop 0
	global_load_lds_dwordx4 v[174:175], off
	s_barrier
; #define PG8_STAGE(bufoff, gbase, voff) do { _Pragma("unroll") for (int _i = 0; _i < 2; ++_i) \
;         __builtin_amdgcn_global_load_lds((const unsigned*)((const char*)(gbase) + (voff)[_i]), (LAS unsigned*)(lds + (bufoff) + ldsw + _i * 8192), 16, 0, 0); } while (0)
; #define PG8_LDA(dst, b, h) do { _Pragma("unroll") for (int m = 0; m < 4; ++m) _Pragma("unroll") for (int k = 0; k < 2; ++k) dst[m][k] = *(const LAS h8*)(lds + PG8_SA(b, h) + aoff + m * 2048 + k * 1024); } while (0)
; #define PG8_WAIT_V(n) asm volatile("s_waitcnt vmcnt(" #n ")" ::: "memory")
; #define PG8_WAIT_L(n) asm volatile("s_waitcnt lgkmcnt(" #n ")" ::: "memory")
; #define PG8_BAR __builtin_amdgcn_s_barrier()
; #define PG8_SCHED __builtin_amdgcn_sched_barrier(0)
; template <class Epi>
; __device__ __forceinline__ void gemm_phase(LAS unsigned char* lds, const Gemm g, const StaticOrder& S, const Epi& E, const int tid) {
;     ...
;             PG8_LDA(At, 1, 1); PG8_STAGE(PG8_SA(1, 0), a3, voffA);
;             PG8_BAR; PG8_WAIT_L(0); PG8_MMA(1, 0, At, B0); PG8_BAR; PG8_SCHED;
;             PG8_STAGE(PG8_SB(1, 1), b3 + hstepB, voffB);
;             PG8_WAIT_V(6); PG8_BAR; PG8_MMA(1, 1, At, B1); PG8_BAR;
;         }
;     __device__ __forceinline__ void operator()(const f32x4 (&acc)[2][2][4][2], const pg8::Unit& u, int wr, int wc, int fr, int fq) const {
;         const int row0 = u.pm * 256 + wr * 64 + fr, col0 = u.pn * 256 + wc * 32 + 8 * fq;
;         const float* gp = gate + (size_t)((u.pm * 256) >> 12) * 6144 + col0;
;         f32x4 gv[2][2];
; #pragma unroll
;         for (int bj = 0; bj < 2; ++bj)
; #pragma unroll
;             for (int n = 0; n < 2; ++n) gv[bj][n] = *(const f32x4*)(gp + bj * 128 + 4 * n);
; #pragma unroll
;         for (int ai = 0; ai < 2; ++ai)
; #pragma unroll
;             for (int m = 0; m < 4; ++m) { const size_t ro = (size_t)(row0 + ai * 128 + m * 16) * DM + col0;
; #pragma unroll
;                 for (int bj = 0; bj < 2; ++bj) {
;                     f32x4 x0, x1;
;                     if (XF32) { x0 = *(const f32x4*)(xin + ro + bj * 128); x1 = *(const f32x4*)(xin + ro + bj * 128 + 4); }
;                     else { const h8 xh = *(const h8*)(H + ro + bj * 128); x0 = (f32x4){(float)xh[0], (float)xh[1], (float)xh[2], (float)xh[3]}; x1 = (f32x4){(float)xh[4], (float)xh[5], (float)xh[6], (float)xh[7]}; }
	s_waitcnt lgkmcnt(7)
	v_mfma_f32_16x16x32_bf16 v[80:83], v[60:63], v[170:173], v[80:83]
	v_mfma_f32_16x16x32_bf16 v[76:79], v[68:71], v[170:173], v[76:79]
	s_waitcnt lgkmcnt(5)
	v_mfma_f32_16x16x32_bf16 v[56:59], v[60:63], v[198:201], v[56:59]
	v_mfma_f32_16x16x32_bf16 v[52:55], v[68:71], v[198:201], v[52:55]
	s_waitcnt lgkmcnt(3)
	v_mfma_f32_16x16x32_bf16 v[40:43], v[60:63], v[206:209], v[40:43]
	v_mfma_f32_16x16x32_bf16 v[36:39], v[68:71], v[206:209], v[36:39]
	s_waitcnt lgkmcnt(1)
	v_mfma_f32_16x16x32_bf16 v[16:19], v[60:63], v[214:217], v[16:19]
	v_mfma_f32_16x16x32_bf16 v[12:15], v[68:71], v[214:217], v[12:15]
	v_mfma_f32_16x16x32_bf16 v[80:83], v[64:67], v[194:197], v[80:83]
	v_mfma_f32_16x16x32_bf16 v[76:79], v[72:75], v[194:197], v[76:79]
	v_mfma_f32_16x16x32_bf16 v[56:59], v[64:67], v[202:205], v[56:59]
	v_mfma_f32_16x16x32_bf16 v[52:55], v[72:75], v[202:205], v[52:55]
	v_mfma_f32_16x16x32_bf16 v[40:43], v[64:67], v[210:213], v[40:43]
	v_mfma_f32_16x16x32_bf16 v[36:39], v[72:75], v[210:213], v[36:39]
	s_waitcnt lgkmcnt(0)
	v_mfma_f32_16x16x32_bf16 v[16:19], v[64:67], v[218:221], v[16:19]
	v_mfma_f32_16x16x32_bf16 v[12:15], v[72:75], v[218:221], v[12:15]
	s_barrier
	s_add_u32 s14, s14, 0x80080
	s_addc_u32 s15, s15, 0
	s_add_i32 s18, s18, s40
	s_mov_b32 m0, s18
	s_nop 0
	global_load_lds_dwordx4 v2, s[14:15]
	v_lshl_add_u64 v[60:61], s[14:15], 0, v[0:1]
	s_add_i32 m0, s18, 0x2000
	s_nop 0
	global_load_lds_dwordx4 v[60:61], off
	s_waitcnt vmcnt(6)
	s_barrier
	v_mfma_f32_16x16x32_bf16 v[28:31], v[222:225], v[170:173], v[28:31]
	v_mfma_f32_16x16x32_bf16 v[72:75], v[226:229], v[194:197], v[28:31]
	v_mfma_f32_16x16x32_bf16 v[28:31], v[230:233], v[170:173], v[32:35]
	v_mfma_f32_16x16x32_bf16 v[68:71], v[234:237], v[194:197], v[28:31]
	v_mfma_f32_16x16x32_bf16 v[28:31], v[222:225], v[198:201], v[48:51]
	v_mfma_f32_16x16x32_bf16 v[48:51], v[226:229], v[202:205], v[28:31]
	v_mfma_f32_16x16x32_bf16 v[28:31], v[230:233], v[198:201], v[44:47]
	v_mfma_f32_16x16x32_bf16 v[24:27], v[222:225], v[206:209], v[24:27]
	v_mfma_f32_16x16x32_bf16 v[20:23], v[230:233], v[206:209], v[20:23]
	v_mfma_f32_16x16x32_bf16 v[8:11], v[222:225], v[214:217], v[8:11]
	v_mfma_f32_16x16x32_bf16 v[4:7], v[230:233], v[214:217], v[4:7]
	v_mfma_f32_16x16x32_bf16 v[44:47], v[234:237], v[202:205], v[28:31]
	v_mfma_f32_16x16x32_bf16 v[24:27], v[226:229], v[210:213], v[24:27]
	v_mfma_f32_16x16x32_bf16 v[20:23], v[234:237], v[210:213], v[20:23]
	v_mfma_f32_16x16x32_bf16 v[8:11], v[226:229], v[218:221], v[8:11]
	v_mfma_f32_16x16x32_bf16 v[4:7], v[234:237], v[218:221], v[4:7]
	s_add_i32 s56, s56, 2
	s_add_u32 s12, s12, 0x100
	s_addc_u32 s13, s13, 0
	s_add_u32 s54, s54, 0x100
	s_addc_u32 s55, s55, 0
	s_cmp_gt_u32 s56, 29
	s_barrier
	s_cbranch_scc0 .LBB0_660
	s_ashr_i32 s1, s50, 4
	v_lshl_add_u32 v172, s50, 8, v189
	v_lshl_or_b32 v170, s51, 8, v191
	s_mul_hi_i32 s7, s1, 0x6000
	s_mulk_i32 s1, 0x6000
	v_ashrrev_i32_e32 v173, 31, v172
	s_add_u32 s12, s23, s1
	v_ashrrev_i32_e32 v171, 31, v170
	v_lshlrev_b64 v[174:175], 12, v[172:173]
	s_addc_u32 s13, s24, s7
	v_lshl_add_u64 v[194:195], s[16:17], 0, v[174:175]
	v_lshlrev_b64 v[174:175], 1, v[170:171]
	v_lshl_add_u64 v[32:33], v[170:171], 2, s[12:13]
	v_lshl_add_u64 v[170:171], v[194:195], 0, v[174:175]
	global_load_dwordx4 v[60:63], v[32:33], off offset:16
	global_load_dwordx4 v[64:67], v[32:33], off
	global_load_dwordx4 v[28:31], v[32:33], off offset:528
	s_nop 0
	global_load_dwordx4 v[32:35], v[32:33], off offset:512
	v_add_co_u32_e32 v242, vcc, 0, v170
	s_nop 1
	v_addc_co_u32_e32 v243, vcc, 0, v171, vcc
	global_load_dwordx4 v[202:205], v[242:243], off
	v_add_co_u32_e32 v242, vcc, 0, v170
	s_nop 1
	v_addc_co_u32_e32 v243, vcc, 0, v171, vcc
	global_load_dwordx4 v[206:209], v[242:243], off offset:256
	v_add_co_u32_e32 v242, vcc, 0x10000, v170
	s_nop 1
	v_addc_co_u32_e32 v243, vcc, 0, v171, vcc
	global_load_dwordx4 v[210:213], v[242:243], off
	v_add_co_u32_e32 v242, vcc, 0x10000, v170
	s_nop 1
	v_addc_co_u32_e32 v243, vcc, 0, v171, vcc
	global_load_dwordx4 v[214:217], v[242:243], off offset:256
	v_add_co_u32_e32 v242, vcc, 0x20000, v170
	s_nop 1
	v_addc_co_u32_e32 v243, vcc, 0, v171, vcc
	global_load_dwordx4 v[218:221], v[242:243], off
	v_add_co_u32_e32 v242, vcc, 0x20000, v170
	s_nop 1
	v_addc_co_u32_e32 v243, vcc, 0, v171, vcc
	global_load_dwordx4 v[222:225], v[242:243], off offset:256
	v_add_co_u32_e32 v242, vcc, 0x30000, v170
	s_nop 1
	v_addc_co_u32_e32 v243, vcc, 0, v171, vcc
	global_load_dwordx4 v[226:229], v[242:243], off
	v_add_co_u32_e32 v242, vcc, 0x30000, v170
	s_nop 1
	v_addc_co_u32_e32 v243, vcc, 0, v171, vcc
	global_load_dwordx4 v[230:233], v[242:243], off offset:256
	v_add_co_u32_e32 v242, vcc, 0x80000, v170
	s_nop 1
	v_addc_co_u32_e32 v243, vcc, 0, v171, vcc
	global_load_dwordx4 v[234:237], v[242:243], off
	v_add_co_u32_e32 v242, vcc, 0x80000, v170
	s_nop 1
	v_addc_co_u32_e32 v243, vcc, 0, v171, vcc
	global_load_dwordx4 v[238:241], v[242:243], off offset:256
	v_add_co_u32_e32 v242, vcc, 0x90000, v170
	s_nop 1
	v_addc_co_u32_e32 v243, vcc, 0, v171, vcc
	global_load_dwordx4 v[244:247], v[242:243], off
	s_mov_b32 s1, 0x80000
	s_nop 1
	s_waitcnt vmcnt(10)
;     __device__ __forceinline__ void operator()(const f32x4 (&acc)[2][2][4][2], const pg8::Unit& u, int wr, int wc, int fr, int fq) const {
;     ...
;             for (int m = 0; m < 4; ++m) { const size_t ro = (size_t)(row0 + ai * 128 + m * 16) * DM + col0;
; #pragma unroll
;                 for (int bj = 0; bj < 2; ++bj) {
;                     f32x4 x0, x1;
;                     if (XF32) { x0 = *(const f32x4*)(xin + ro + bj * 128); x1 = *(const f32x4*)(xin + ro + bj * 128 + 4); }
;                     else { const h8 xh = *(const h8*)(H + ro + bj * 128); x0 = (f32x4){(float)xh[0], (float)xh[1], (float)xh[2], (float)xh[3]}; x1 = (f32x4){(float)xh[4], (float)xh[5], (float)xh[6], (float)xh[7]}; }
;                     const f32x4 y0 = x0 + gv[bj][0] * acc[ai][bj][m][0], y1 = x1 + gv[bj][1] * acc[ai][bj][m][1];
;                     h8 o; o[0] = (half_t)y0[0]; o[1] = (half_t)y0[1]; o[2] = (half_t)y0[2]; o[3] = (half_t)y0[3]; o[4] = (half_t)y1[0]; o[5] = (half_t)y1[1]; o[6] = (half_t)y1[2]; o[7] = (half_t)y1[3];
;                     *(h8*)(H + ro + bj * 128) = o; } }
	v_mov_b32_e32 v194, v202
	v_mov_b32_e32 v195, v203
	v_mov_b32_e32 v196, v204
	v_mov_b32_e32 v197, v205
	v_add_co_u32_e32 v242, vcc, 0x90000, v170
	s_nop 1
	v_addc_co_u32_e32 v243, vcc, 0, v171, vcc
	global_load_dwordx4 v[202:205], v[242:243], off offset:256
	s_mov_b64 s[12:13], 0x80000
	s_mov_b32 s51, s0
	s_mov_b32 s50, s6
	s_mov_b64 s[14:15], s[10:11]
	v_readlane_b32 s59, v251, 43
	s_nop 0
	v_cvt_f32_f16_e32 v198, v194
	v_cvt_f32_f16_sdwa v199, v194 dst_sel:DWORD dst_unused:UNUSED_PAD src0_sel:WORD_1
	v_cvt_f32_f16_e32 v194, v195
	v_cvt_f32_f16_sdwa v195, v195 dst_sel:DWORD dst_unused:UNUSED_PAD src0_sel:WORD_1
	v_cvt_f32_f16_e32 v200, v196
	v_cvt_f32_f16_sdwa v201, v196 dst_sel:DWORD dst_unused:UNUSED_PAD src0_sel:WORD_1
	v_cvt_f32_f16_e32 v196, v197
	v_cvt_f32_f16_sdwa v197, v197 dst_sel:DWORD dst_unused:UNUSED_PAD src0_sel:WORD_1
	v_pk_fma_f32 v[146:147], v[146:147], v[66:67], v[194:195]
	v_pk_fma_f32 v[144:145], v[144:145], v[64:65], v[198:199]
	v_pk_fma_f32 v[140:141], v[140:141], v[60:61], v[200:201]
	v_pk_fma_f32 v[142:143], v[142:143], v[62:63], v[196:197]
	s_nop 0
	v_cvt_pk_f16_f32 v143, v142, v143
	v_cvt_pk_f16_f32 v142, v140, v141
	v_cvt_pk_f16_f32 v141, v146, v147
	v_cvt_pk_f16_f32 v140, v144, v145
	global_store_dwordx4 v[170:171], v[140:143], off
	s_nop 1
	s_waitcnt vmcnt(10)
	v_mov_b32_e32 v140, v206
	v_mov_b32_e32 v141, v207
	v_mov_b32_e32 v142, v208
	v_mov_b32_e32 v143, v209
	v_add_co_u32_e32 v242, vcc, 0xa0000, v170
	s_nop 1
	v_addc_co_u32_e32 v243, vcc, 0, v171, vcc
	global_load_dwordx4 v[206:209], v[242:243], off
	s_nop 0
	v_cvt_f32_f16_e32 v144, v140
	v_cvt_f32_f16_sdwa v145, v140 dst_sel:DWORD dst_unused:UNUSED_PAD src0_sel:WORD_1
	v_cvt_f32_f16_e32 v140, v141
	v_cvt_f32_f16_sdwa v141, v141 dst_sel:DWORD dst_unused:UNUSED_PAD src0_sel:WORD_1
	v_cvt_f32_f16_e32 v146, v142
	v_cvt_f32_f16_sdwa v147, v142 dst_sel:DWORD dst_unused:UNUSED_PAD src0_sel:WORD_1
	v_cvt_f32_f16_e32 v142, v143
	v_cvt_f32_f16_sdwa v143, v143 dst_sel:DWORD dst_unused:UNUSED_PAD src0_sel:WORD_1
	v_pk_fma_f32 v[138:139], v[138:139], v[34:35], v[140:141]
	v_pk_fma_f32 v[136:137], v[136:137], v[32:33], v[144:145]
	v_pk_fma_f32 v[132:133], v[132:133], v[28:29], v[146:147]
	v_pk_fma_f32 v[134:135], v[134:135], v[30:31], v[142:143]
	s_nop 0
	v_cvt_pk_f16_f32 v135, v134, v135
	v_cvt_pk_f16_f32 v134, v132, v133
	v_cvt_pk_f16_f32 v133, v138, v139
	v_cvt_pk_f16_f32 v132, v136, v137
	global_store_dwordx4 v[170:171], v[132:135], off offset:256
	s_nop 1
	v_or_b32_e32 v132, 16, v172
	v_ashrrev_i32_e32 v133, 31, v132
	v_lshlrev_b64 v[132:133], 12, v[132:133]
	v_lshl_add_u64 v[132:133], s[16:17], 0, v[132:133]
	v_lshl_add_u64 v[136:137], v[132:133], 0, v[174:175]
	s_nop 1
	s_waitcnt vmcnt(10)
	v_mov_b32_e32 v132, v210
	v_mov_b32_e32 v133, v211
	v_mov_b32_e32 v134, v212
	v_mov_b32_e32 v135, v213
	v_add_co_u32_e32 v242, vcc, 0xa0000, v170
	s_nop 1
	v_addc_co_u32_e32 v243, vcc, 0, v171, vcc
	global_load_dwordx4 v[210:213], v[242:243], off offset:256
	s_nop 0
	v_cvt_f32_f16_e32 v138, v132
	v_cvt_f32_f16_sdwa v139, v132 dst_sel:DWORD dst_unused:UNUSED_PAD src0_sel:WORD_1
	v_cvt_f32_f16_e32 v132, v133
	v_cvt_f32_f16_sdwa v133, v133 dst_sel:DWORD dst_unused:UNUSED_PAD src0_sel:WORD_1
	v_cvt_f32_f16_e32 v140, v134
	v_cvt_f32_f16_sdwa v141, v134 dst_sel:DWORD dst_unused:UNUSED_PAD src0_sel:WORD_1
	v_cvt_f32_f16_e32 v134, v135
	v_cvt_f32_f16_sdwa v135, v135 dst_sel:DWORD dst_unused:UNUSED_PAD src0_sel:WORD_1
	v_pk_fma_f32 v[130:131], v[130:131], v[66:67], v[132:133]
	v_pk_fma_f32 v[128:129], v[128:129], v[64:65], v[138:139]
	v_pk_fma_f32 v[124:125], v[124:125], v[60:61], v[140:141]
	v_pk_fma_f32 v[126:127], v[126:127], v[62:63], v[134:135]
	s_nop 0
	v_cvt_pk_f16_f32 v127, v126, v127
	v_cvt_pk_f16_f32 v126, v124, v125
	v_cvt_pk_f16_f32 v125, v130, v131
	v_cvt_pk_f16_f32 v124, v128, v129
	global_store_dwordx4 v[136:137], v[124:127], off
	s_nop 1
	s_waitcnt vmcnt(10)
	v_mov_b32_e32 v124, v214
	v_mov_b32_e32 v125, v215
	v_mov_b32_e32 v126, v216
	v_mov_b32_e32 v127, v217
	v_add_co_u32_e32 v242, vcc, 0xb0000, v170
	s_nop 1
	v_addc_co_u32_e32 v243, vcc, 0, v171, vcc
	global_load_dwordx4 v[214:217], v[242:243], off
	s_nop 0
	v_cvt_f32_f16_e32 v128, v124
	v_cvt_f32_f16_sdwa v129, v124 dst_sel:DWORD dst_unused:UNUSED_PAD src0_sel:WORD_1
	v_cvt_f32_f16_e32 v124, v125
	v_cvt_f32_f16_sdwa v125, v125 dst_sel:DWORD dst_unused:UNUSED_PAD src0_sel:WORD_1
	v_cvt_f32_f16_e32 v130, v126
	v_cvt_f32_f16_sdwa v131, v126 dst_sel:DWORD dst_unused:UNUSED_PAD src0_sel:WORD_1
	v_cvt_f32_f16_e32 v126, v127
	v_cvt_f32_f16_sdwa v127, v127 dst_sel:DWORD dst_unused:UNUSED_PAD src0_sel:WORD_1
	v_pk_fma_f32 v[122:123], v[122:123], v[34:35], v[124:125]
	v_pk_fma_f32 v[120:121], v[120:121], v[32:33], v[128:129]
	v_pk_fma_f32 v[116:117], v[116:117], v[28:29], v[130:131]
	v_pk_fma_f32 v[118:119], v[118:119], v[30:31], v[126:127]
	s_nop 0
	v_cvt_pk_f16_f32 v119, v118, v119
	v_cvt_pk_f16_f32 v118, v116, v117
	v_cvt_pk_f16_f32 v117, v122, v123
	v_cvt_pk_f16_f32 v116, v120, v121
	global_store_dwordx4 v[136:137], v[116:119], off offset:256
	s_nop 1
	v_or_b32_e32 v116, 32, v172
	v_ashrrev_i32_e32 v117, 31, v116
	v_lshlrev_b64 v[116:117], 12, v[116:117]
	v_lshl_add_u64 v[116:117], s[16:17], 0, v[116:117]
	v_lshl_add_u64 v[120:121], v[116:117], 0, v[174:175]
	s_nop 1
	s_waitcnt vmcnt(10)
;     __device__ __forceinline__ void operator()(const f32x4 (&acc)[2][2][4][2], const pg8::Unit& u, int wr, int wc, int fr, int fq) const {
;     ...
;             for (int m = 0; m < 4; ++m) { const size_t ro = (size_t)(row0 + ai * 128 + m * 16) * DM + col0;
; #pragma unroll
;                 for (int bj = 0; bj < 2; ++bj) {
;                     f32x4 x0, x1;
;                     if (XF32) { x0 = *(const f32x4*)(xin + ro + bj * 128); x1 = *(const f32x4*)(xin + ro + bj * 128 + 4); }
;                     else { const h8 xh = *(const h8*)(H + ro + bj * 128); x0 = (f32x4){(float)xh[0], (float)xh[1], (float)xh[2], (float)xh[3]}; x1 = (f32x4){(float)xh[4], (float)xh[5], (float)xh[6], (float)xh[7]}; }
;                     const f32x4 y0 = x0 + gv[bj][0] * acc[ai][bj][m][0], y1 = x1 + gv[bj][1] * acc[ai][bj][m][1];
;                     h8 o; o[0] = (half_t)y0[0]; o[1] = (half_t)y0[1]; o[2] = (half_t)y0[2]; o[3] = (half_t)y0[3]; o[4] = (half_t)y1[0]; o[5] = (half_t)y1[1]; o[6] = (half_t)y1[2]; o[7] = (half_t)y1[3];
;                     *(h8*)(H + ro + bj * 128) = o; } }
	v_mov_b32_e32 v116, v218
	v_mov_b32_e32 v117, v219
	v_mov_b32_e32 v118, v220
	v_mov_b32_e32 v119, v221
	v_add_co_u32_e32 v242, vcc, 0xb0000, v170
	s_nop 1
	v_addc_co_u32_e32 v243, vcc, 0, v171, vcc
	global_load_dwordx4 v[218:221], v[242:243], off offset:256
	s_nop 0
	v_cvt_f32_f16_e32 v122, v116
	v_cvt_f32_f16_sdwa v123, v116 dst_sel:DWORD dst_unused:UNUSED_PAD src0_sel:WORD_1
	v_cvt_f32_f16_e32 v116, v117
	v_cvt_f32_f16_sdwa v117, v117 dst_sel:DWORD dst_unused:UNUSED_PAD src0_sel:WORD_1
	v_cvt_f32_f16_e32 v124, v118
	v_cvt_f32_f16_sdwa v125, v118 dst_sel:DWORD dst_unused:UNUSED_PAD src0_sel:WORD_1
	v_cvt_f32_f16_e32 v118, v119
	v_cvt_f32_f16_sdwa v119, v119 dst_sel:DWORD dst_unused:UNUSED_PAD src0_sel:WORD_1
	v_pk_fma_f32 v[114:115], v[114:115], v[66:67], v[116:117]
	v_pk_fma_f32 v[112:113], v[112:113], v[64:65], v[122:123]
	v_pk_fma_f32 v[108:109], v[108:109], v[60:61], v[124:125]
	v_pk_fma_f32 v[110:111], v[110:111], v[62:63], v[118:119]
	s_nop 0
	v_cvt_pk_f16_f32 v111, v110, v111
	v_cvt_pk_f16_f32 v110, v108, v109
	v_cvt_pk_f16_f32 v109, v114, v115
	v_cvt_pk_f16_f32 v108, v112, v113
	global_store_dwordx4 v[120:121], v[108:111], off
	s_nop 1
	s_waitcnt vmcnt(10)
	v_mov_b32_e32 v108, v222
	v_mov_b32_e32 v109, v223
	v_mov_b32_e32 v110, v224
	v_mov_b32_e32 v111, v225
	s_nop 0
	v_cvt_f32_f16_e32 v112, v108
	v_cvt_f32_f16_sdwa v113, v108 dst_sel:DWORD dst_unused:UNUSED_PAD src0_sel:WORD_1
	v_cvt_f32_f16_e32 v108, v109
	v_cvt_f32_f16_sdwa v109, v109 dst_sel:DWORD dst_unused:UNUSED_PAD src0_sel:WORD_1
	v_cvt_f32_f16_e32 v114, v110
	v_cvt_f32_f16_sdwa v115, v110 dst_sel:DWORD dst_unused:UNUSED_PAD src0_sel:WORD_1
	v_cvt_f32_f16_e32 v110, v111
	v_cvt_f32_f16_sdwa v111, v111 dst_sel:DWORD dst_unused:UNUSED_PAD src0_sel:WORD_1
	v_pk_fma_f32 v[106:107], v[106:107], v[34:35], v[108:109]
	v_pk_fma_f32 v[104:105], v[104:105], v[32:33], v[112:113]
	v_pk_fma_f32 v[100:101], v[100:101], v[28:29], v[114:115]
	v_pk_fma_f32 v[102:103], v[102:103], v[30:31], v[110:111]
	s_nop 0
	v_cvt_pk_f16_f32 v103, v102, v103
	v_cvt_pk_f16_f32 v102, v100, v101
	v_cvt_pk_f16_f32 v101, v106, v107
	v_cvt_pk_f16_f32 v100, v104, v105
	global_store_dwordx4 v[120:121], v[100:103], off offset:256
	s_nop 1
	v_or_b32_e32 v100, 48, v172
	v_ashrrev_i32_e32 v101, 31, v100
	v_lshlrev_b64 v[100:101], 12, v[100:101]
	v_lshl_add_u64 v[100:101], s[16:17], 0, v[100:101]
	v_lshl_add_u64 v[104:105], v[100:101], 0, v[174:175]
	s_nop 1
	s_waitcnt vmcnt(9)
	v_mov_b32_e32 v100, v226
	v_mov_b32_e32 v101, v227
	v_mov_b32_e32 v102, v228
	v_mov_b32_e32 v103, v229
	s_nop 0
	v_cvt_f32_f16_e32 v106, v100
	v_cvt_f32_f16_sdwa v107, v100 dst_sel:DWORD dst_unused:UNUSED_PAD src0_sel:WORD_1
	v_cvt_f32_f16_e32 v100, v101
	v_cvt_f32_f16_sdwa v101, v101 dst_sel:DWORD dst_unused:UNUSED_PAD src0_sel:WORD_1
	v_cvt_f32_f16_e32 v108, v102
	v_cvt_f32_f16_sdwa v109, v102 dst_sel:DWORD dst_unused:UNUSED_PAD src0_sel:WORD_1
	v_cvt_f32_f16_e32 v102, v103
	v_cvt_f32_f16_sdwa v103, v103 dst_sel:DWORD dst_unused:UNUSED_PAD src0_sel:WORD_1
	v_pk_fma_f32 v[98:99], v[98:99], v[66:67], v[100:101]
	v_pk_fma_f32 v[96:97], v[96:97], v[64:65], v[106:107]
	v_pk_fma_f32 v[92:93], v[92:93], v[60:61], v[108:109]
	v_pk_fma_f32 v[94:95], v[94:95], v[62:63], v[102:103]
	s_nop 0
	v_cvt_pk_f16_f32 v95, v94, v95
	v_cvt_pk_f16_f32 v94, v92, v93
	v_cvt_pk_f16_f32 v93, v98, v99
	v_cvt_pk_f16_f32 v92, v96, v97
	global_store_dwordx4 v[104:105], v[92:95], off
	s_nop 1
	s_waitcnt vmcnt(8)
	v_mov_b32_e32 v92, v230
	v_mov_b32_e32 v93, v231
	v_mov_b32_e32 v94, v232
	v_mov_b32_e32 v95, v233
	s_nop 0
	v_cvt_f32_f16_e32 v96, v92
	v_cvt_f32_f16_sdwa v97, v92 dst_sel:DWORD dst_unused:UNUSED_PAD src0_sel:WORD_1
	v_cvt_f32_f16_e32 v92, v93
	v_cvt_f32_f16_sdwa v93, v93 dst_sel:DWORD dst_unused:UNUSED_PAD src0_sel:WORD_1
	v_cvt_f32_f16_e32 v98, v94
	v_cvt_f32_f16_sdwa v99, v94 dst_sel:DWORD dst_unused:UNUSED_PAD src0_sel:WORD_1
	v_cvt_f32_f16_e32 v94, v95
	v_cvt_f32_f16_sdwa v95, v95 dst_sel:DWORD dst_unused:UNUSED_PAD src0_sel:WORD_1
	v_pk_fma_f32 v[90:91], v[90:91], v[34:35], v[92:93]
	v_pk_fma_f32 v[84:85], v[84:85], v[28:29], v[98:99]
	v_pk_fma_f32 v[88:89], v[88:89], v[32:33], v[96:97]
	v_pk_fma_f32 v[86:87], v[86:87], v[30:31], v[94:95]
	s_nop 0
	v_cvt_pk_f16_f32 v87, v86, v87
	v_cvt_pk_f16_f32 v86, v84, v85
	v_cvt_pk_f16_f32 v85, v90, v91
	v_add_co_u32_e32 v90, vcc, s1, v170
	v_cvt_pk_f16_f32 v84, v88, v89
	s_nop 0
	v_addc_co_u32_e32 v91, vcc, 0, v171, vcc
	global_store_dwordx4 v[104:105], v[84:87], off offset:256
	s_nop 1
	s_waitcnt vmcnt(7)
	v_mov_b32_e32 v86, v234
	v_mov_b32_e32 v87, v235
	v_mov_b32_e32 v88, v236
	v_mov_b32_e32 v89, v237
	s_mov_b32 s1, 0x90000
	v_lshl_add_u64 v[84:85], v[170:171], 0, s[12:13]
	s_mov_b64 s[12:13], 0x90000
	s_nop 0
	v_cvt_f32_f16_e32 v92, v86
	v_cvt_f32_f16_sdwa v93, v86 dst_sel:DWORD dst_unused:UNUSED_PAD src0_sel:WORD_1
	v_cvt_f32_f16_e32 v86, v87
	v_cvt_f32_f16_sdwa v87, v87 dst_sel:DWORD dst_unused:UNUSED_PAD src0_sel:WORD_1
	v_cvt_f32_f16_e32 v94, v88
	v_cvt_f32_f16_sdwa v95, v88 dst_sel:DWORD dst_unused:UNUSED_PAD src0_sel:WORD_1
	v_cvt_f32_f16_e32 v88, v89
	v_cvt_f32_f16_sdwa v89, v89 dst_sel:DWORD dst_unused:UNUSED_PAD src0_sel:WORD_1
	v_pk_fma_f32 v[82:83], v[82:83], v[66:67], v[86:87]
	v_pk_fma_f32 v[80:81], v[80:81], v[64:65], v[92:93]
	v_pk_fma_f32 v[76:77], v[76:77], v[60:61], v[94:95]
	v_pk_fma_f32 v[78:79], v[78:79], v[62:63], v[88:89]
	s_nop 0
	v_cvt_pk_f16_f32 v79, v78, v79
	v_cvt_pk_f16_f32 v78, v76, v77
	v_cvt_pk_f16_f32 v77, v82, v83
	v_cvt_pk_f16_f32 v76, v80, v81
	global_store_dwordx4 v[90:91], v[76:79], off
	s_nop 1
	s_waitcnt vmcnt(6)
;     __device__ __forceinline__ void operator()(const f32x4 (&acc)[2][2][4][2], const pg8::Unit& u, int wr, int wc, int fr, int fq) const {
;     ...
;             for (int m = 0; m < 4; ++m) { const size_t ro = (size_t)(row0 + ai * 128 + m * 16) * DM + col0;
; #pragma unroll
;                 for (int bj = 0; bj < 2; ++bj) {
;                     f32x4 x0, x1;
;                     if (XF32) { x0 = *(const f32x4*)(xin + ro + bj * 128); x1 = *(const f32x4*)(xin + ro + bj * 128 + 4); }
;                     else { const h8 xh = *(const h8*)(H + ro + bj * 128); x0 = (f32x4){(float)xh[0], (float)xh[1], (float)xh[2], (float)xh[3]}; x1 = (f32x4){(float)xh[4], (float)xh[5], (float)xh[6], (float)xh[7]}; }
;                     const f32x4 y0 = x0 + gv[bj][0] * acc[ai][bj][m][0], y1 = x1 + gv[bj][1] * acc[ai][bj][m][1];
;                     h8 o; o[0] = (half_t)y0[0]; o[1] = (half_t)y0[1]; o[2] = (half_t)y0[2]; o[3] = (half_t)y0[3]; o[4] = (half_t)y1[0]; o[5] = (half_t)y1[1]; o[6] = (half_t)y1[2]; o[7] = (half_t)y1[3];
;                     *(h8*)(H + ro + bj * 128) = o; } }
	v_mov_b32_e32 v76, v238
	v_mov_b32_e32 v77, v239
	v_mov_b32_e32 v78, v240
	v_mov_b32_e32 v79, v241
	s_nop 0
	v_cvt_f32_f16_e32 v80, v76
	v_cvt_f32_f16_sdwa v81, v76 dst_sel:DWORD dst_unused:UNUSED_PAD src0_sel:WORD_1
	v_cvt_f32_f16_e32 v76, v77
	v_cvt_f32_f16_sdwa v77, v77 dst_sel:DWORD dst_unused:UNUSED_PAD src0_sel:WORD_1
	v_cvt_f32_f16_e32 v82, v78
	v_cvt_f32_f16_sdwa v83, v78 dst_sel:DWORD dst_unused:UNUSED_PAD src0_sel:WORD_1
	v_cvt_f32_f16_e32 v78, v79
	v_cvt_f32_f16_sdwa v79, v79 dst_sel:DWORD dst_unused:UNUSED_PAD src0_sel:WORD_1
	v_pk_fma_f32 v[74:75], v[74:75], v[34:35], v[76:77]
	v_pk_fma_f32 v[68:69], v[68:69], v[28:29], v[82:83]
	v_pk_fma_f32 v[72:73], v[72:73], v[32:33], v[80:81]
	v_pk_fma_f32 v[70:71], v[70:71], v[30:31], v[78:79]
	s_nop 0
	v_cvt_pk_f16_f32 v71, v70, v71
	v_cvt_pk_f16_f32 v70, v68, v69
	v_cvt_pk_f16_f32 v69, v74, v75
	v_add_co_u32_e32 v74, vcc, s1, v170
	v_cvt_pk_f16_f32 v68, v72, v73
	s_nop 0
	v_addc_co_u32_e32 v75, vcc, 0, v171, vcc
	global_store_dwordx4 v[84:85], v[68:71], off offset:256
	s_nop 1
	s_waitcnt vmcnt(5)
	v_mov_b32_e32 v70, v244
	v_mov_b32_e32 v71, v245
	v_mov_b32_e32 v72, v246
	v_mov_b32_e32 v73, v247
	s_mov_b32 s1, 0xa0000
	v_lshl_add_u64 v[68:69], v[170:171], 0, s[12:13]
	s_mov_b64 s[12:13], 0xa0000
	s_nop 0
	v_cvt_f32_f16_e32 v76, v70
	v_cvt_f32_f16_sdwa v77, v70 dst_sel:DWORD dst_unused:UNUSED_PAD src0_sel:WORD_1
	v_cvt_f32_f16_e32 v70, v71
	v_cvt_f32_f16_sdwa v71, v71 dst_sel:DWORD dst_unused:UNUSED_PAD src0_sel:WORD_1
	v_cvt_f32_f16_e32 v78, v72
	v_cvt_f32_f16_sdwa v79, v72 dst_sel:DWORD dst_unused:UNUSED_PAD src0_sel:WORD_1
	v_cvt_f32_f16_e32 v72, v73
	v_cvt_f32_f16_sdwa v73, v73 dst_sel:DWORD dst_unused:UNUSED_PAD src0_sel:WORD_1
	v_pk_fma_f32 v[58:59], v[58:59], v[66:67], v[70:71]
	v_pk_fma_f32 v[56:57], v[56:57], v[64:65], v[76:77]
	v_pk_fma_f32 v[52:53], v[52:53], v[60:61], v[78:79]
	v_pk_fma_f32 v[54:55], v[54:55], v[62:63], v[72:73]
	s_nop 0
	v_cvt_pk_f16_f32 v55, v54, v55
	v_cvt_pk_f16_f32 v54, v52, v53
	v_cvt_pk_f16_f32 v53, v58, v59
	v_cvt_pk_f16_f32 v52, v56, v57
	global_store_dwordx4 v[74:75], v[52:55], off
	s_nop 1
	s_waitcnt vmcnt(4)
	v_mov_b32_e32 v52, v202
	v_mov_b32_e32 v53, v203
	v_mov_b32_e32 v54, v204
	v_mov_b32_e32 v55, v205
	s_nop 0
	v_cvt_f32_f16_e32 v56, v52
	v_cvt_f32_f16_sdwa v57, v52 dst_sel:DWORD dst_unused:UNUSED_PAD src0_sel:WORD_1
	v_cvt_f32_f16_e32 v52, v53
	v_cvt_f32_f16_sdwa v53, v53 dst_sel:DWORD dst_unused:UNUSED_PAD src0_sel:WORD_1
	v_cvt_f32_f16_e32 v58, v54
	v_cvt_f32_f16_sdwa v59, v54 dst_sel:DWORD dst_unused:UNUSED_PAD src0_sel:WORD_1
	v_cvt_f32_f16_e32 v54, v55
	v_cvt_f32_f16_sdwa v55, v55 dst_sel:DWORD dst_unused:UNUSED_PAD src0_sel:WORD_1
	v_pk_fma_f32 v[50:51], v[50:51], v[34:35], v[52:53]
	v_pk_fma_f32 v[44:45], v[44:45], v[28:29], v[58:59]
	v_pk_fma_f32 v[48:49], v[48:49], v[32:33], v[56:57]
	v_pk_fma_f32 v[46:47], v[46:47], v[30:31], v[54:55]
	s_nop 0
	v_cvt_pk_f16_f32 v47, v46, v47
	v_cvt_pk_f16_f32 v46, v44, v45
	v_cvt_pk_f16_f32 v45, v50, v51
	v_add_co_u32_e32 v50, vcc, s1, v170
	v_cvt_pk_f16_f32 v44, v48, v49
	s_nop 0
	v_addc_co_u32_e32 v51, vcc, 0, v171, vcc
	global_store_dwordx4 v[68:69], v[44:47], off offset:256
	s_nop 1
	s_waitcnt vmcnt(3)
	v_mov_b32_e32 v46, v206
	v_mov_b32_e32 v47, v207
	v_mov_b32_e32 v48, v208
	v_mov_b32_e32 v49, v209
	s_mov_b32 s1, 0xb0000
	v_lshl_add_u64 v[44:45], v[170:171], 0, s[12:13]
	s_mov_b64 s[12:13], 0xb0000
	s_nop 0
	v_cvt_f32_f16_e32 v52, v46
	v_cvt_f32_f16_sdwa v53, v46 dst_sel:DWORD dst_unused:UNUSED_PAD src0_sel:WORD_1
	v_cvt_f32_f16_e32 v46, v47
	v_cvt_f32_f16_sdwa v47, v47 dst_sel:DWORD dst_unused:UNUSED_PAD src0_sel:WORD_1
	v_cvt_f32_f16_e32 v54, v48
	v_cvt_f32_f16_sdwa v55, v48 dst_sel:DWORD dst_unused:UNUSED_PAD src0_sel:WORD_1
	v_cvt_f32_f16_e32 v48, v49
	v_cvt_f32_f16_sdwa v49, v49 dst_sel:DWORD dst_unused:UNUSED_PAD src0_sel:WORD_1
	v_pk_fma_f32 v[42:43], v[42:43], v[66:67], v[46:47]
	v_pk_fma_f32 v[40:41], v[40:41], v[64:65], v[52:53]
	v_pk_fma_f32 v[36:37], v[36:37], v[60:61], v[54:55]
	v_pk_fma_f32 v[38:39], v[38:39], v[62:63], v[48:49]
	s_nop 0
	v_cvt_pk_f16_f32 v39, v38, v39
	v_cvt_pk_f16_f32 v38, v36, v37
	v_cvt_pk_f16_f32 v37, v42, v43
	v_cvt_pk_f16_f32 v36, v40, v41
	global_store_dwordx4 v[50:51], v[36:39], off
	s_nop 1
	s_waitcnt vmcnt(2)
; #define PG8_WAIT_V(n) asm volatile("s_waitcnt vmcnt(" #n ")" ::: "memory")
; #define PG8_BAR __builtin_amdgcn_s_barrier()
; template <class Epi>
; __device__ __forceinline__ void gemm_phase(LAS unsigned char* lds, const Gemm g, const StaticOrder& S, const Epi& E, const int tid) {
;     ...
;     PG8_WAIT_V(0);
;     if (wr == 0) PG8_BAR;
;     PG8_BAR;
;     __device__ __forceinline__ void operator()(const f32x4 (&acc)[2][2][4][2], const pg8::Unit& u, int wr, int wc, int fr, int fq) const {
;     ...
;             for (int m = 0; m < 4; ++m) { const size_t ro = (size_t)(row0 + ai * 128 + m * 16) * DM + col0;
; #pragma unroll
;                 for (int bj = 0; bj < 2; ++bj) {
;                     f32x4 x0, x1;
;                     if (XF32) { x0 = *(const f32x4*)(xin + ro + bj * 128); x1 = *(const f32x4*)(xin + ro + bj * 128 + 4); }
;                     else { const h8 xh = *(const h8*)(H + ro + bj * 128); x0 = (f32x4){(float)xh[0], (float)xh[1], (float)xh[2], (float)xh[3]}; x1 = (f32x4){(float)xh[4], (float)xh[5], (float)xh[6], (float)xh[7]}; }
;                     const f32x4 y0 = x0 + gv[bj][0] * acc[ai][bj][m][0], y1 = x1 + gv[bj][1] * acc[ai][bj][m][1];
;                     h8 o; o[0] = (half_t)y0[0]; o[1] = (half_t)y0[1]; o[2] = (half_t)y0[2]; o[3] = (half_t)y0[3]; o[4] = (half_t)y1[0]; o[5] = (half_t)y1[1]; o[6] = (half_t)y1[2]; o[7] = (half_t)y1[3];
;                     *(h8*)(H + ro + bj * 128) = o; } }
	v_mov_b32_e32 v36, v210
	v_mov_b32_e32 v37, v211
	v_mov_b32_e32 v38, v212
	v_mov_b32_e32 v39, v213
	s_nop 0
	v_cvt_f32_f16_e32 v40, v36
	v_cvt_f32_f16_sdwa v41, v36 dst_sel:DWORD dst_unused:UNUSED_PAD src0_sel:WORD_1
	v_cvt_f32_f16_e32 v36, v37
	v_cvt_f32_f16_sdwa v37, v37 dst_sel:DWORD dst_unused:UNUSED_PAD src0_sel:WORD_1
	v_cvt_f32_f16_e32 v42, v38
	v_cvt_f32_f16_sdwa v43, v38 dst_sel:DWORD dst_unused:UNUSED_PAD src0_sel:WORD_1
	v_cvt_f32_f16_e32 v38, v39
	v_cvt_f32_f16_sdwa v39, v39 dst_sel:DWORD dst_unused:UNUSED_PAD src0_sel:WORD_1
	v_pk_fma_f32 v[26:27], v[26:27], v[34:35], v[36:37]
	v_pk_fma_f32 v[20:21], v[20:21], v[28:29], v[42:43]
	v_pk_fma_f32 v[24:25], v[24:25], v[32:33], v[40:41]
	v_pk_fma_f32 v[22:23], v[22:23], v[30:31], v[38:39]
	s_nop 0
	v_cvt_pk_f16_f32 v23, v22, v23
	v_cvt_pk_f16_f32 v22, v20, v21
	v_cvt_pk_f16_f32 v21, v26, v27
	v_add_co_u32_e32 v26, vcc, s1, v170
	v_cvt_pk_f16_f32 v20, v24, v25
	s_nop 0
	v_addc_co_u32_e32 v27, vcc, 0, v171, vcc
	global_store_dwordx4 v[44:45], v[20:23], off offset:256
	s_nop 1
	s_waitcnt vmcnt(1)
	v_mov_b32_e32 v22, v214
	v_mov_b32_e32 v23, v215
	v_mov_b32_e32 v24, v216
	v_mov_b32_e32 v25, v217
	s_and_b64 vcc, exec, s[4:5]
	v_lshl_add_u64 v[20:21], v[170:171], 0, s[12:13]
	s_mov_b64 s[12:13], s[8:9]
	s_nop 0
	v_cvt_f32_f16_e32 v36, v22
	v_cvt_f32_f16_sdwa v37, v22 dst_sel:DWORD dst_unused:UNUSED_PAD src0_sel:WORD_1
	v_cvt_f32_f16_e32 v22, v23
	v_cvt_f32_f16_sdwa v23, v23 dst_sel:DWORD dst_unused:UNUSED_PAD src0_sel:WORD_1
	v_cvt_f32_f16_e32 v38, v24
	v_cvt_f32_f16_sdwa v39, v24 dst_sel:DWORD dst_unused:UNUSED_PAD src0_sel:WORD_1
	v_cvt_f32_f16_e32 v24, v25
	v_cvt_f32_f16_sdwa v25, v25 dst_sel:DWORD dst_unused:UNUSED_PAD src0_sel:WORD_1
	v_pk_fma_f32 v[18:19], v[18:19], v[66:67], v[22:23]
	v_pk_fma_f32 v[16:17], v[16:17], v[64:65], v[36:37]
	v_pk_fma_f32 v[12:13], v[12:13], v[60:61], v[38:39]
	v_pk_fma_f32 v[14:15], v[14:15], v[62:63], v[24:25]
	s_nop 0
	v_cvt_pk_f16_f32 v15, v14, v15
	v_cvt_pk_f16_f32 v14, v12, v13
	v_cvt_pk_f16_f32 v13, v18, v19
	v_cvt_pk_f16_f32 v12, v16, v17
	global_store_dwordx4 v[26:27], v[12:15], off
	s_nop 1
	s_waitcnt vmcnt(0)
	v_mov_b32_e32 v12, v218
	v_mov_b32_e32 v13, v219
	v_mov_b32_e32 v14, v220
	v_mov_b32_e32 v15, v221
	s_nop 0
	v_cvt_f32_f16_e32 v16, v12
	v_cvt_f32_f16_sdwa v17, v12 dst_sel:DWORD dst_unused:UNUSED_PAD src0_sel:WORD_1
	v_cvt_f32_f16_e32 v12, v13
	v_cvt_f32_f16_sdwa v13, v13 dst_sel:DWORD dst_unused:UNUSED_PAD src0_sel:WORD_1
	v_cvt_f32_f16_e32 v18, v14
	v_cvt_f32_f16_sdwa v19, v14 dst_sel:DWORD dst_unused:UNUSED_PAD src0_sel:WORD_1
	v_cvt_f32_f16_e32 v14, v15
	v_cvt_f32_f16_sdwa v15, v15 dst_sel:DWORD dst_unused:UNUSED_PAD src0_sel:WORD_1
	v_pk_fma_f32 v[10:11], v[10:11], v[34:35], v[12:13]
	v_pk_fma_f32 v[8:9], v[8:9], v[32:33], v[16:17]
	v_pk_fma_f32 v[4:5], v[4:5], v[28:29], v[18:19]
	v_pk_fma_f32 v[6:7], v[6:7], v[30:31], v[14:15]
	s_nop 0
	v_cvt_pk_f16_f32 v7, v6, v7
	v_cvt_pk_f16_f32 v6, v4, v5
	v_cvt_pk_f16_f32 v5, v10, v11
	v_cvt_pk_f16_f32 v4, v8, v9
	global_store_dwordx4 v[20:21], v[4:7], off offset:256
	s_cbranch_vccz .LBB0_653
	s_waitcnt vmcnt(0)
	v_readlane_b32 s48, v251, 13
	s_cmpk_gt_u32 s25, 0xff
	v_readlane_b32 s49, v251, 14
	s_cbranch_scc1 .LBB0_664
	s_barrier

; #define PG8_STAGE(bufoff, gbase, voff) do { _Pragma("unroll") for (int _i = 0; _i < 2; ++_i) \
;         __builtin_amdgcn_global_load_lds((const unsigned*)((const char*)(gbase) + (voff)[_i]), (LAS unsigned*)(lds + (bufoff) + ldsw + _i * 8192), 16, 0, 0); } while (0)
; #define PG8_LDA(dst, b, h) do { _Pragma("unroll") for (int m = 0; m < 4; ++m) _Pragma("unroll") for (int k = 0; k < 2; ++k) dst[m][k] = *(const LAS h8*)(lds + PG8_SA(b, h) + aoff + m * 2048 + k * 1024); } while (0)
; #define PG8_LDB(dst, b, h) do { _Pragma("unroll") for (int n = 0; n < 2; ++n) _Pragma("unroll") for (int k = 0; k < 2; ++k) dst[n][k] = *(const LAS h8*)(lds + PG8_SB(b, h) + boff + n * 2048 + k * 1024); } while (0)
; #define PG8_WAIT_L(n) asm volatile("s_waitcnt lgkmcnt(" #n ")" ::: "memory")
; #define PG8_BAR __builtin_amdgcn_s_barrier()
; #define PG8_SCHED __builtin_amdgcn_sched_barrier(0)
; template <class Epi>
; __device__ __forceinline__ void gemm_phase(LAS unsigned char* lds, const Gemm g, const StaticOrder& S, const Epi& E, const int tid) {
;     ...
;         for (int t = 0; t < nt; t += 2) {
;             const bool last = (t == nt - 2);
;             const char* a1 = cA + (size_t)(t + 1) * kstep;
;             const char* a2 = last ? nA : cA + (size_t)(t + 2) * kstep; const char* b2 = last ? nB : cB + (size_t)(t + 2) * kstep;
;             const char* a3 = a2 + kstep; const char* b3 = b2 + kstep;
;             if constexpr (Epi::HAS_MID) { if (t == (nt >> 1)) E.mid(acc, cur, wr, wc, fr, fq); }
;             PG8_LDB(B0, 0, 0); PG8_SCHED; PG8_LDA(At, 0, 0); PG8_STAGE(PG8_SA(1, 1), a1 + hstep, voffA);
;             PG8_WAIT_L(8); PG8_BAR; PG8_WAIT_L(0); PG8_MMA(0, 0, At, B0); PG8_BAR; PG8_SCHED;
;             PG8_LDB(B1, 0, 1); PG8_STAGE(PG8_SB(0, 0), b2, voffB);
;             PG8_BAR; PG8_WAIT_L(0); PG8_MMA(0, 1, At, B1); PG8_BAR;
;             PG8_LDA(At, 0, 1); PG8_STAGE(PG8_SA(0, 0), a2, voffA);
;             PG8_BAR; PG8_WAIT_L(0); PG8_MMA(1, 0, At, B0); PG8_BAR; PG8_SCHED;
.LBB0_678:
	s_add_u32 s14, s12, 0xfff80080
	s_addc_u32 s15, s13, -1
	s_add_i32 s55, 0, 0x10000
	v_add_u32_e32 v88, s55, v176
	ds_read_b128 v[68:71], v88
	ds_read_b128 v[72:75], v88 offset:1024
	ds_read_b128 v[84:87], v88 offset:2048
	ds_read_b128 v[88:91], v88 offset:3072
	s_cmp_eq_u32 s54, 28
	s_cselect_b32 s19, s7, s15
	s_cselect_b32 s18, s50, s14
	s_cselect_b32 s15, s1, s53
	s_cselect_b32 s14, s51, s52
	s_add_i32 m0, s39, 0xc000
	ds_read_b128 v[170:173], v177
	ds_read_b128 v[190:193], v177 offset:1024
	ds_read_b128 v[194:197], v177 offset:2048
	ds_read_b128 v[198:201], v177 offset:3072
	ds_read_b128 v[202:205], v177 offset:4096
	ds_read_b128 v[206:209], v177 offset:5120
	ds_read_b128 v[210:213], v177 offset:6144
	ds_read_b128 v[214:217], v177 offset:7168
	global_load_lds_dwordx4 v166, s[12:13]
	v_lshl_add_u64 v[174:175], s[12:13], 0, v[168:169]
	s_add_i32 m0, s39, 0xe000
	s_nop 0
	global_load_lds_dwordx4 v[174:175], off
	s_waitcnt lgkmcnt(8)
	s_barrier
	s_waitcnt lgkmcnt(7)
	v_mfma_f32_16x16x32_bf16 v[144:147], v[68:71], v[170:173], v[144:147]
	v_mfma_f32_16x16x32_bf16 v[140:143], v[84:87], v[170:173], v[140:143]
	s_waitcnt lgkmcnt(5)
	v_mfma_f32_16x16x32_bf16 v[128:131], v[68:71], v[194:197], v[128:131]
	v_mfma_f32_16x16x32_bf16 v[124:127], v[84:87], v[194:197], v[124:127]
	s_waitcnt lgkmcnt(3)
	v_mfma_f32_16x16x32_bf16 v[112:115], v[68:71], v[202:205], v[112:115]
	v_mfma_f32_16x16x32_bf16 v[108:111], v[84:87], v[202:205], v[108:111]
	s_waitcnt lgkmcnt(1)
	v_mfma_f32_16x16x32_bf16 v[96:99], v[68:71], v[210:213], v[96:99]
	v_mfma_f32_16x16x32_bf16 v[92:95], v[84:87], v[210:213], v[92:95]
	v_mfma_f32_16x16x32_bf16 v[144:147], v[72:75], v[190:193], v[144:147]
	v_mfma_f32_16x16x32_bf16 v[140:143], v[88:91], v[190:193], v[140:143]
	v_mfma_f32_16x16x32_bf16 v[128:131], v[72:75], v[198:201], v[128:131]
	v_mfma_f32_16x16x32_bf16 v[124:127], v[88:91], v[198:201], v[124:127]
	v_mfma_f32_16x16x32_bf16 v[112:115], v[72:75], v[206:209], v[112:115]
	v_mfma_f32_16x16x32_bf16 v[108:111], v[88:91], v[206:209], v[108:111]
	s_waitcnt lgkmcnt(0)
	v_mfma_f32_16x16x32_bf16 v[96:99], v[72:75], v[214:217], v[96:99]
	v_mfma_f32_16x16x32_bf16 v[92:95], v[88:91], v[214:217], v[92:95]
	s_barrier
	s_add_i32 s58, 0, 0x14000
	v_add_u32_e32 v174, s58, v176
	s_add_i32 s55, s55, s38
	ds_read_b128 v[218:221], v174
	ds_read_b128 v[222:225], v174 offset:1024
	ds_read_b128 v[226:229], v174 offset:2048
	ds_read_b128 v[230:233], v174 offset:3072
	v_lshl_add_u64 v[174:175], s[14:15], 0, v[2:3]
	s_mov_b32 m0, s55
	v_lshl_add_u64 v[234:235], s[14:15], 0, v[0:1]
	global_load_lds_dwordx4 v[174:175], off
	s_add_i32 m0, s55, 0x2000
	s_nop 0
	global_load_lds_dwordx4 v[234:235], off
	s_barrier
	s_waitcnt lgkmcnt(3)
	v_mfma_f32_16x16x32_bf16 v[136:139], v[218:221], v[170:173], v[136:139]
	s_waitcnt lgkmcnt(1)
	v_mfma_f32_16x16x32_bf16 v[132:135], v[226:229], v[170:173], v[132:135]
	v_mfma_f32_16x16x32_bf16 v[120:123], v[218:221], v[194:197], v[120:123]
	v_mfma_f32_16x16x32_bf16 v[116:119], v[226:229], v[194:197], v[116:119]
	v_mfma_f32_16x16x32_bf16 v[104:107], v[218:221], v[202:205], v[104:107]
	v_mfma_f32_16x16x32_bf16 v[100:103], v[226:229], v[202:205], v[100:103]
	v_mfma_f32_16x16x32_bf16 v[80:83], v[218:221], v[210:213], v[80:83]
	v_mfma_f32_16x16x32_bf16 v[76:79], v[226:229], v[210:213], v[76:79]
	v_mfma_f32_16x16x32_bf16 v[136:139], v[222:225], v[190:193], v[136:139]
	s_waitcnt lgkmcnt(0)
	v_mfma_f32_16x16x32_bf16 v[132:135], v[230:233], v[190:193], v[132:135]
	v_mfma_f32_16x16x32_bf16 v[120:123], v[222:225], v[198:201], v[120:123]
	v_mfma_f32_16x16x32_bf16 v[116:119], v[230:233], v[198:201], v[116:119]
	v_mfma_f32_16x16x32_bf16 v[104:107], v[222:225], v[206:209], v[104:107]
	v_mfma_f32_16x16x32_bf16 v[100:103], v[230:233], v[206:209], v[100:103]
	v_mfma_f32_16x16x32_bf16 v[80:83], v[222:225], v[214:217], v[80:83]
	v_mfma_f32_16x16x32_bf16 v[76:79], v[230:233], v[214:217], v[76:79]
	s_mov_b32 m0, s39
	v_lshl_add_u64 v[236:237], s[18:19], 0, v[164:165]
	s_barrier
	ds_read_b128 v[170:173], v177 offset:16384
	ds_read_b128 v[190:193], v177 offset:17408
	ds_read_b128 v[194:197], v177 offset:18432
	ds_read_b128 v[198:201], v177 offset:19456
	ds_read_b128 v[202:205], v177 offset:20480
	ds_read_b128 v[206:209], v177 offset:21504
	ds_read_b128 v[210:213], v177 offset:22528
	ds_read_b128 v[214:217], v177 offset:23552
	global_load_lds_dwordx4 v[236:237], off
	v_lshl_add_u64 v[238:239], s[18:19], 0, v[162:163]
	s_mov_b32 m0, s40
	s_nop 0
	global_load_lds_dwordx4 v[238:239], off
	s_barrier
	s_waitcnt lgkmcnt(7)
	v_mfma_f32_16x16x32_bf16 v[64:67], v[68:71], v[170:173], v[64:67]
	v_mfma_f32_16x16x32_bf16 v[60:63], v[84:87], v[170:173], v[60:63]
	s_waitcnt lgkmcnt(5)
	v_mfma_f32_16x16x32_bf16 v[48:51], v[68:71], v[194:197], v[48:51]
	v_mfma_f32_16x16x32_bf16 v[44:47], v[84:87], v[194:197], v[44:47]
	s_waitcnt lgkmcnt(3)
	v_mfma_f32_16x16x32_bf16 v[32:35], v[68:71], v[202:205], v[32:35]
	v_mfma_f32_16x16x32_bf16 v[28:31], v[84:87], v[202:205], v[28:31]
	s_waitcnt lgkmcnt(1)
	v_mfma_f32_16x16x32_bf16 v[16:19], v[68:71], v[210:213], v[16:19]
	v_mfma_f32_16x16x32_bf16 v[12:15], v[84:87], v[210:213], v[12:15]
	v_mfma_f32_16x16x32_bf16 v[64:67], v[72:75], v[190:193], v[64:67]
	v_mfma_f32_16x16x32_bf16 v[60:63], v[88:91], v[190:193], v[60:63]
	v_mfma_f32_16x16x32_bf16 v[48:51], v[72:75], v[198:201], v[48:51]
	v_mfma_f32_16x16x32_bf16 v[44:47], v[88:91], v[198:201], v[44:47]
	v_mfma_f32_16x16x32_bf16 v[32:35], v[72:75], v[206:209], v[32:35]
	v_mfma_f32_16x16x32_bf16 v[28:31], v[88:91], v[206:209], v[28:31]
	s_waitcnt lgkmcnt(0)
	v_mfma_f32_16x16x32_bf16 v[16:19], v[72:75], v[214:217], v[16:19]
	v_mfma_f32_16x16x32_bf16 v[12:15], v[88:91], v[214:217], v[12:15]
	s_barrier
; #define PG8_STAGE(bufoff, gbase, voff) do { _Pragma("unroll") for (int _i = 0; _i < 2; ++_i) \
;         __builtin_amdgcn_global_load_lds((const unsigned*)((const char*)(gbase) + (voff)[_i]), (LAS unsigned*)(lds + (bufoff) + ldsw + _i * 8192), 16, 0, 0); } while (0)
; #define PG8_LDA(dst, b, h) do { _Pragma("unroll") for (int m = 0; m < 4; ++m) _Pragma("unroll") for (int k = 0; k < 2; ++k) dst[m][k] = *(const LAS h8*)(lds + PG8_SA(b, h) + aoff + m * 2048 + k * 1024); } while (0)
; #define PG8_LDB(dst, b, h) do { _Pragma("unroll") for (int n = 0; n < 2; ++n) _Pragma("unroll") for (int k = 0; k < 2; ++k) dst[n][k] = *(const LAS h8*)(lds + PG8_SB(b, h) + boff + n * 2048 + k * 1024); } while (0)
; #define PG8_WAIT_V(n) asm volatile("s_waitcnt vmcnt(" #n ")" ::: "memory")
; #define PG8_WAIT_L(n) asm volatile("s_waitcnt lgkmcnt(" #n ")" ::: "memory")
; #define PG8_BAR __builtin_amdgcn_s_barrier()
; #define PG8_SCHED __builtin_amdgcn_sched_barrier(0)
; template <class Epi>
; __device__ __forceinline__ void gemm_phase(LAS unsigned char* lds, const Gemm g, const StaticOrder& S, const Epi& E, const int tid) {
;     ...
;             PG8_STAGE(PG8_SB(0, 1), b2 + hstepB, voffB);
;             PG8_WAIT_V(6); PG8_BAR; PG8_MMA(1, 1, At, B1); PG8_BAR;
;             PG8_LDB(B0, 1, 0); PG8_SCHED; PG8_LDA(At, 1, 0); PG8_STAGE(PG8_SA(0, 1), a2 + hstep, voffA);
;             PG8_WAIT_L(8); PG8_BAR; PG8_WAIT_L(0); PG8_MMA(0, 0, At, B0); PG8_BAR; PG8_SCHED;
;             PG8_LDB(B1, 1, 1); PG8_STAGE(PG8_SB(1, 0), b3, voffB);
;             PG8_BAR; PG8_WAIT_L(0); PG8_MMA(0, 1, At, B1); PG8_BAR;
;             PG8_LDA(At, 1, 1); PG8_STAGE(PG8_SA(1, 0), a3, voffA);
	s_add_u32 s56, s14, 0x80000
	s_addc_u32 s57, s15, 0
	s_add_i32 s55, s58, s38
	s_mov_b32 m0, s55
	s_nop 0
	global_load_lds_dwordx4 v2, s[56:57]
	s_add_i32 m0, s55, 0x2000
	s_nop 0
	global_load_lds_dwordx4 v0, s[56:57]
	s_waitcnt vmcnt(6)
	s_barrier
	v_mfma_f32_16x16x32_bf16 v[56:59], v[218:221], v[170:173], v[56:59]
	v_mfma_f32_16x16x32_bf16 v[52:55], v[226:229], v[170:173], v[52:55]
	v_mfma_f32_16x16x32_bf16 v[40:43], v[218:221], v[194:197], v[40:43]
	v_mfma_f32_16x16x32_bf16 v[36:39], v[226:229], v[194:197], v[36:39]
	v_mfma_f32_16x16x32_bf16 v[24:27], v[218:221], v[202:205], v[24:27]
	v_mfma_f32_16x16x32_bf16 v[20:23], v[226:229], v[202:205], v[20:23]
	v_mfma_f32_16x16x32_bf16 v[8:11], v[218:221], v[210:213], v[8:11]
	v_mfma_f32_16x16x32_bf16 v[4:7], v[226:229], v[210:213], v[4:7]
	v_mfma_f32_16x16x32_bf16 v[56:59], v[222:225], v[190:193], v[56:59]
	v_mfma_f32_16x16x32_bf16 v[52:55], v[230:233], v[190:193], v[52:55]
	v_mfma_f32_16x16x32_bf16 v[40:43], v[222:225], v[198:201], v[40:43]
	v_mfma_f32_16x16x32_bf16 v[36:39], v[230:233], v[198:201], v[36:39]
	v_mfma_f32_16x16x32_bf16 v[24:27], v[222:225], v[206:209], v[24:27]
	v_mfma_f32_16x16x32_bf16 v[20:23], v[230:233], v[206:209], v[20:23]
	v_mfma_f32_16x16x32_bf16 v[8:11], v[222:225], v[214:217], v[8:11]
	v_mfma_f32_16x16x32_bf16 v[4:7], v[230:233], v[214:217], v[4:7]
	s_add_i32 s55, 0, 0x18000
	v_add_u32_e32 v88, s55, v176
	s_barrier
	ds_read_b128 v[68:71], v88
	ds_read_b128 v[72:75], v88 offset:1024
	ds_read_b128 v[84:87], v88 offset:2048
	ds_read_b128 v[88:91], v88 offset:3072
	s_add_u32 s18, s18, 0x80000
	s_addc_u32 s19, s19, 0
	s_mov_b32 m0, s41
	ds_read_b128 v[170:173], v177 offset:32768
	ds_read_b128 v[190:193], v177 offset:33792
	ds_read_b128 v[194:197], v177 offset:34816
	ds_read_b128 v[198:201], v177 offset:35840
	ds_read_b128 v[202:205], v177 offset:36864
	ds_read_b128 v[206:209], v177 offset:37888
	ds_read_b128 v[210:213], v177 offset:38912
	ds_read_b128 v[214:217], v177 offset:39936
	global_load_lds_dwordx4 v164, s[18:19]
	s_mov_b32 m0, s42
	s_nop 0
	global_load_lds_dwordx4 v162, s[18:19]
	s_waitcnt lgkmcnt(8)
	s_barrier
	s_waitcnt lgkmcnt(7)
	v_mfma_f32_16x16x32_bf16 v[144:147], v[68:71], v[170:173], v[144:147]
	v_mfma_f32_16x16x32_bf16 v[140:143], v[84:87], v[170:173], v[140:143]
	s_waitcnt lgkmcnt(5)
	v_mfma_f32_16x16x32_bf16 v[128:131], v[68:71], v[194:197], v[128:131]
	v_mfma_f32_16x16x32_bf16 v[124:127], v[84:87], v[194:197], v[124:127]
	s_waitcnt lgkmcnt(3)
	v_mfma_f32_16x16x32_bf16 v[112:115], v[68:71], v[202:205], v[112:115]
	v_mfma_f32_16x16x32_bf16 v[108:111], v[84:87], v[202:205], v[108:111]
	s_waitcnt lgkmcnt(1)
	v_mfma_f32_16x16x32_bf16 v[96:99], v[68:71], v[210:213], v[96:99]
	v_mfma_f32_16x16x32_bf16 v[92:95], v[84:87], v[210:213], v[92:95]
	v_mfma_f32_16x16x32_bf16 v[144:147], v[72:75], v[190:193], v[144:147]
	v_mfma_f32_16x16x32_bf16 v[140:143], v[88:91], v[190:193], v[140:143]
	v_mfma_f32_16x16x32_bf16 v[128:131], v[72:75], v[198:201], v[128:131]
	v_mfma_f32_16x16x32_bf16 v[124:127], v[88:91], v[198:201], v[124:127]
	v_mfma_f32_16x16x32_bf16 v[112:115], v[72:75], v[206:209], v[112:115]
	v_mfma_f32_16x16x32_bf16 v[108:111], v[88:91], v[206:209], v[108:111]
	s_waitcnt lgkmcnt(0)
	v_mfma_f32_16x16x32_bf16 v[96:99], v[72:75], v[214:217], v[96:99]
	v_mfma_f32_16x16x32_bf16 v[92:95], v[88:91], v[214:217], v[92:95]
	s_barrier
	s_add_i32 s18, 0, 0x1c000
	s_add_i32 s19, s55, s38
	v_add_u32_e32 v178, s18, v176
	v_lshl_add_u64 v[174:175], v[174:175], 0, s[30:31]
	s_mov_b32 m0, s19
	ds_read_b128 v[218:221], v178
	ds_read_b128 v[222:225], v178 offset:1024
	ds_read_b128 v[226:229], v178 offset:2048
	ds_read_b128 v[230:233], v178 offset:3072
	global_load_lds_dwordx4 v[174:175], off
	v_lshl_add_u64 v[174:175], v[234:235], 0, s[30:31]
	s_add_i32 m0, s19, 0x2000
	s_nop 0
	global_load_lds_dwordx4 v[174:175], off
	s_barrier
	s_waitcnt lgkmcnt(3)
	v_mfma_f32_16x16x32_bf16 v[136:139], v[218:221], v[170:173], v[136:139]
	s_waitcnt lgkmcnt(1)
	v_mfma_f32_16x16x32_bf16 v[132:135], v[226:229], v[170:173], v[132:135]
	v_mfma_f32_16x16x32_bf16 v[120:123], v[218:221], v[194:197], v[120:123]
	v_mfma_f32_16x16x32_bf16 v[116:119], v[226:229], v[194:197], v[116:119]
	v_mfma_f32_16x16x32_bf16 v[104:107], v[218:221], v[202:205], v[104:107]
	v_mfma_f32_16x16x32_bf16 v[100:103], v[226:229], v[202:205], v[100:103]
	v_mfma_f32_16x16x32_bf16 v[80:83], v[218:221], v[210:213], v[80:83]
	v_mfma_f32_16x16x32_bf16 v[76:79], v[226:229], v[210:213], v[76:79]
	v_mfma_f32_16x16x32_bf16 v[136:139], v[222:225], v[190:193], v[136:139]
	s_waitcnt lgkmcnt(0)
	v_mfma_f32_16x16x32_bf16 v[132:135], v[230:233], v[190:193], v[132:135]
	v_mfma_f32_16x16x32_bf16 v[120:123], v[222:225], v[198:201], v[120:123]
	v_mfma_f32_16x16x32_bf16 v[116:119], v[230:233], v[198:201], v[116:119]
	v_mfma_f32_16x16x32_bf16 v[104:107], v[222:225], v[206:209], v[104:107]
	v_mfma_f32_16x16x32_bf16 v[100:103], v[230:233], v[206:209], v[100:103]
	v_mfma_f32_16x16x32_bf16 v[80:83], v[222:225], v[214:217], v[80:83]
	v_mfma_f32_16x16x32_bf16 v[76:79], v[230:233], v[214:217], v[76:79]
	s_mov_b32 m0, s43
	v_lshl_add_u64 v[174:175], v[236:237], 0, s[30:31]
	s_barrier
	ds_read_b128 v[170:173], v177 offset:49152
	ds_read_b128 v[190:193], v177 offset:50176
	ds_read_b128 v[194:197], v177 offset:51200
	ds_read_b128 v[198:201], v177 offset:52224
	ds_read_b128 v[202:205], v177 offset:53248
	ds_read_b128 v[206:209], v177 offset:54272
	ds_read_b128 v[210:213], v177 offset:55296
	ds_read_b128 v[214:217], v177 offset:56320
	global_load_lds_dwordx4 v[174:175], off
	v_lshl_add_u64 v[174:175], v[238:239], 0, s[30:31]
	s_mov_b32 m0, s46
	s_nop 0
	global_load_lds_dwordx4 v[174:175], off
	s_barrier
; #define PG8_STAGE(bufoff, gbase, voff) do { _Pragma("unroll") for (int _i = 0; _i < 2; ++_i) \
;         __builtin_amdgcn_global_load_lds((const unsigned*)((const char*)(gbase) + (voff)[_i]), (LAS unsigned*)(lds + (bufoff) + ldsw + _i * 8192), 16, 0, 0); } while (0)
; #define PG8_WAIT_V(n) asm volatile("s_waitcnt vmcnt(" #n ")" ::: "memory")
; #define PG8_WAIT_L(n) asm volatile("s_waitcnt lgkmcnt(" #n ")" ::: "memory")
; #define PG8_BAR __builtin_amdgcn_s_barrier()
; template <class Epi>
; __device__ __forceinline__ void gemm_phase(LAS unsigned char* lds, const Gemm g, const StaticOrder& S, const Epi& E, const int tid) {
;     ...
;             PG8_BAR; PG8_WAIT_L(0); PG8_MMA(1, 0, At, B0); PG8_BAR; PG8_SCHED;
;             PG8_STAGE(PG8_SB(1, 1), b3 + hstepB, voffB);
;             PG8_WAIT_V(6); PG8_BAR; PG8_MMA(1, 1, At, B1); PG8_BAR;
;     __device__ __forceinline__ void operator()(const f32x4 (&acc)[2][2][4][2], const pg8::Unit& u, int wr, int wc, int fr, int fq) const {
;         const int row0 = u.pm * 256 + wr * 64 + fr, col0 = u.pn * 256 + wc * 32 + 8 * fq;
;         const float* gp = gate + (size_t)((u.pm * 256) >> 12) * 6144 + col0;
;         f32x4 gv[2][2];
; #pragma unroll
;         for (int bj = 0; bj < 2; ++bj)
; #pragma unroll
;             for (int n = 0; n < 2; ++n) gv[bj][n] = *(const f32x4*)(gp + bj * 128 + 4 * n);
; #pragma unroll
;         for (int ai = 0; ai < 2; ++ai)
; #pragma unroll
;             for (int m = 0; m < 4; ++m) { const size_t ro = (size_t)(row0 + ai * 128 + m * 16) * DM + col0;
; #pragma unroll
;                 for (int bj = 0; bj < 2; ++bj) {
;                     f32x4 x0, x1;
;                     if (XF32) { x0 = *(const f32x4*)(xin + ro + bj * 128); x1 = *(const f32x4*)(xin + ro + bj * 128 + 4); }
;                     else { const h8 xh = *(const h8*)(H + ro + bj * 128); x0 = (f32x4){(float)xh[0], (float)xh[1], (float)xh[2], (float)xh[3]}; x1 = (f32x4){(float)xh[4], (float)xh[5], (float)xh[6], (float)xh[7]}; }
;                     const f32x4 y0 = x0 + gv[bj][0] * acc[ai][bj][m][0], y1 = x1 + gv[bj][1] * acc[ai][bj][m][1];
;                     h8 o; o[0] = (half_t)y0[0]; o[1] = (half_t)y0[1]; o[2] = (half_t)y0[2]; o[3] = (half_t)y0[3]; o[4] = (half_t)y1[0]; o[5] = (half_t)y1[1]; o[6] = (half_t)y1[2]; o[7] = (half_t)y1[3];
;                     *(h8*)(H + ro + bj * 128) = o; } }
	s_waitcnt lgkmcnt(7)
	v_mfma_f32_16x16x32_bf16 v[64:67], v[68:71], v[170:173], v[64:67]
	v_mfma_f32_16x16x32_bf16 v[60:63], v[84:87], v[170:173], v[60:63]
	s_waitcnt lgkmcnt(5)
	v_mfma_f32_16x16x32_bf16 v[48:51], v[68:71], v[194:197], v[48:51]
	v_mfma_f32_16x16x32_bf16 v[44:47], v[84:87], v[194:197], v[44:47]
	s_waitcnt lgkmcnt(3)
	v_mfma_f32_16x16x32_bf16 v[32:35], v[68:71], v[202:205], v[32:35]
	v_mfma_f32_16x16x32_bf16 v[28:31], v[84:87], v[202:205], v[28:31]
	s_waitcnt lgkmcnt(1)
	v_mfma_f32_16x16x32_bf16 v[16:19], v[68:71], v[210:213], v[16:19]
	v_mfma_f32_16x16x32_bf16 v[12:15], v[84:87], v[210:213], v[12:15]
	v_mfma_f32_16x16x32_bf16 v[64:67], v[72:75], v[190:193], v[64:67]
	v_mfma_f32_16x16x32_bf16 v[60:63], v[88:91], v[190:193], v[60:63]
	v_mfma_f32_16x16x32_bf16 v[48:51], v[72:75], v[198:201], v[48:51]
	v_mfma_f32_16x16x32_bf16 v[44:47], v[88:91], v[198:201], v[44:47]
	v_mfma_f32_16x16x32_bf16 v[32:35], v[72:75], v[206:209], v[32:35]
	v_mfma_f32_16x16x32_bf16 v[28:31], v[88:91], v[206:209], v[28:31]
	s_waitcnt lgkmcnt(0)
	v_mfma_f32_16x16x32_bf16 v[16:19], v[72:75], v[214:217], v[16:19]
	v_mfma_f32_16x16x32_bf16 v[12:15], v[88:91], v[214:217], v[12:15]
	s_barrier
	s_add_u32 s14, s14, 0x80080
	s_addc_u32 s15, s15, 0
	s_add_i32 s18, s18, s38
	s_mov_b32 m0, s18
	s_nop 0
	global_load_lds_dwordx4 v2, s[14:15]
	v_lshl_add_u64 v[68:69], s[14:15], 0, v[0:1]
	s_add_i32 m0, s18, 0x2000
	s_nop 0
	global_load_lds_dwordx4 v[68:69], off
	s_waitcnt vmcnt(6)
	s_barrier
	v_mfma_f32_16x16x32_bf16 v[56:59], v[218:221], v[170:173], v[56:59]
	v_mfma_f32_16x16x32_bf16 v[52:55], v[226:229], v[170:173], v[52:55]
	v_mfma_f32_16x16x32_bf16 v[40:43], v[218:221], v[194:197], v[40:43]
	v_mfma_f32_16x16x32_bf16 v[36:39], v[226:229], v[194:197], v[36:39]
	v_mfma_f32_16x16x32_bf16 v[24:27], v[218:221], v[202:205], v[24:27]
	v_mfma_f32_16x16x32_bf16 v[20:23], v[226:229], v[202:205], v[20:23]
	v_mfma_f32_16x16x32_bf16 v[8:11], v[218:221], v[210:213], v[8:11]
	v_mfma_f32_16x16x32_bf16 v[4:7], v[226:229], v[210:213], v[4:7]
	v_mfma_f32_16x16x32_bf16 v[56:59], v[222:225], v[190:193], v[56:59]
	v_mfma_f32_16x16x32_bf16 v[52:55], v[230:233], v[190:193], v[52:55]
	v_mfma_f32_16x16x32_bf16 v[40:43], v[222:225], v[198:201], v[40:43]
	v_mfma_f32_16x16x32_bf16 v[36:39], v[230:233], v[198:201], v[36:39]
	v_mfma_f32_16x16x32_bf16 v[24:27], v[222:225], v[206:209], v[24:27]
	v_mfma_f32_16x16x32_bf16 v[20:23], v[230:233], v[206:209], v[20:23]
	v_mfma_f32_16x16x32_bf16 v[8:11], v[222:225], v[214:217], v[8:11]
	v_mfma_f32_16x16x32_bf16 v[4:7], v[230:233], v[214:217], v[4:7]
	s_add_i32 s54, s54, 2
	s_add_u32 s12, s12, 0x100
	s_addc_u32 s13, s13, 0
	s_add_u32 s52, s52, 0x100
	s_addc_u32 s53, s53, 0
	s_cmp_gt_u32 s54, 29
	s_barrier
	s_cbranch_scc0 .LBB0_678
	s_ashr_i32 s1, s48, 4
	v_lshl_add_u32 v174, s48, 8, v179
	v_lshl_or_b32 v172, s49, 8, v157
	s_mul_hi_i32 s7, s1, 0x6000
	s_mulk_i32 s1, 0x6000
	v_ashrrev_i32_e32 v175, 31, v174
	s_add_u32 s12, s23, s1
	v_ashrrev_i32_e32 v173, 31, v172
	v_lshlrev_b64 v[170:171], 11, v[174:175]
	s_addc_u32 s13, s24, s7
	v_lshl_add_u64 v[170:171], v[170:171], 0, v[172:173]
	v_lshl_add_u64 v[72:73], v[172:173], 2, s[12:13]
	v_lshl_add_u64 v[198:199], v[170:171], 2, s[80:81]
	global_load_dwordx4 v[84:87], v[72:73], off offset:16
	global_load_dwordx4 v[88:91], v[72:73], off
	global_load_dwordx4 v[68:71], v[72:73], off offset:528
	s_nop 0
	global_load_dwordx4 v[72:75], v[72:73], off offset:512
	s_mov_b64 s[98:99], 0x0
	v_lshl_add_u64 v[248:249], v[198:199], 0, s[98:99]
	global_load_dwordx4 v[200:203], v[248:249], off offset:16
	global_load_dwordx4 v[204:207], v[248:249], off
	s_mov_b64 s[98:99], 0x0
	v_lshl_add_u64 v[248:249], v[198:199], 0, s[98:99]
	global_load_dwordx4 v[208:211], v[248:249], off offset:528
	global_load_dwordx4 v[212:215], v[248:249], off offset:512
	s_mov_b64 s[98:99], 0x20000
	v_lshl_add_u64 v[248:249], v[198:199], 0, s[98:99]
	global_load_dwordx4 v[216:219], v[248:249], off offset:16
	global_load_dwordx4 v[220:223], v[248:249], off
	s_mov_b64 s[98:99], 0x20000
	v_lshl_add_u64 v[248:249], v[198:199], 0, s[98:99]
	global_load_dwordx4 v[224:227], v[248:249], off offset:528
	global_load_dwordx4 v[228:231], v[248:249], off offset:512
	s_mov_b64 s[98:99], 0x40000
	v_lshl_add_u64 v[248:249], v[198:199], 0, s[98:99]
	global_load_dwordx4 v[232:235], v[248:249], off offset:16
	global_load_dwordx4 v[236:239], v[248:249], off
	s_mov_b64 s[98:99], 0x40000
	v_lshl_add_u64 v[248:249], v[198:199], 0, s[98:99]
	global_load_dwordx4 v[240:243], v[248:249], off offset:528
	global_load_dwordx4 v[244:247], v[248:249], off offset:512
	s_nop 0
	s_nop 1
	s_waitcnt vmcnt(10)
	v_mov_b32_e32 v190, v200
	v_mov_b32_e32 v191, v201
	v_mov_b32_e32 v192, v202
	v_mov_b32_e32 v193, v203
	s_nop 1
	v_mov_b32_e32 v194, v204
	v_mov_b32_e32 v195, v205
	v_mov_b32_e32 v196, v206
	v_mov_b32_e32 v197, v207
	s_mov_b64 s[98:99], 0x60000
	v_lshl_add_u64 v[248:249], v[198:199], 0, s[98:99]
	global_load_dwordx4 v[200:203], v[248:249], off offset:16
	global_load_dwordx4 v[204:207], v[248:249], off
	s_mov_b64 s[12:13], 0x40000
	s_and_b64 vcc, exec, s[4:5]
	s_mov_b32 s49, s0
	s_mov_b32 s48, s6
	s_mov_b64 s[14:15], s[10:11]
	s_nop 0
	v_pk_fma_f32 v[142:143], v[142:143], v[86:87], v[192:193]
	v_pk_fma_f32 v[146:147], v[146:147], v[90:91], v[196:197]
	v_pk_fma_f32 v[144:145], v[144:145], v[88:89], v[194:195]
	v_pk_fma_f32 v[190:191], v[140:141], v[84:85], v[190:191]
	v_cvt_pk_f16_f32 v143, v142, v143
	v_cvt_pk_f16_f32 v141, v146, v147
	v_cvt_pk_f16_f32 v142, v190, v191
	v_cvt_pk_f16_f32 v140, v144, v145
	v_lshl_add_u64 v[190:191], v[170:171], 1, s[16:17]
	global_store_dwordx4 v[190:191], v[140:143], off
	s_nop 1
	s_waitcnt vmcnt(10)
;     __device__ __forceinline__ void operator()(const f32x4 (&acc)[2][2][4][2], const pg8::Unit& u, int wr, int wc, int fr, int fq) const {
;     ...
;             for (int m = 0; m < 4; ++m) { const size_t ro = (size_t)(row0 + ai * 128 + m * 16) * DM + col0;
; #pragma unroll
;                 for (int bj = 0; bj < 2; ++bj) {
;                     f32x4 x0, x1;
;                     if (XF32) { x0 = *(const f32x4*)(xin + ro + bj * 128); x1 = *(const f32x4*)(xin + ro + bj * 128 + 4); }
;                     else { const h8 xh = *(const h8*)(H + ro + bj * 128); x0 = (f32x4){(float)xh[0], (float)xh[1], (float)xh[2], (float)xh[3]}; x1 = (f32x4){(float)xh[4], (float)xh[5], (float)xh[6], (float)xh[7]}; }
;                     const f32x4 y0 = x0 + gv[bj][0] * acc[ai][bj][m][0], y1 = x1 + gv[bj][1] * acc[ai][bj][m][1];
;                     h8 o; o[0] = (half_t)y0[0]; o[1] = (half_t)y0[1]; o[2] = (half_t)y0[2]; o[3] = (half_t)y0[3]; o[4] = (half_t)y1[0]; o[5] = (half_t)y1[1]; o[6] = (half_t)y1[2]; o[7] = (half_t)y1[3];
;                     *(h8*)(H + ro + bj * 128) = o; } }
	v_mov_b32_e32 v140, v208
	v_mov_b32_e32 v141, v209
	v_mov_b32_e32 v142, v210
	v_mov_b32_e32 v143, v211
	s_nop 0
	s_nop 1
	v_mov_b32_e32 v144, v212
	v_mov_b32_e32 v145, v213
	v_mov_b32_e32 v146, v214
	v_mov_b32_e32 v147, v215
	s_mov_b64 s[98:99], 0x60000
	v_lshl_add_u64 v[248:249], v[198:199], 0, s[98:99]
	global_load_dwordx4 v[208:211], v[248:249], off offset:528
	global_load_dwordx4 v[212:215], v[248:249], off offset:512
	s_nop 0
	v_pk_fma_f32 v[134:135], v[134:135], v[70:71], v[142:143]
	v_pk_fma_f32 v[138:139], v[138:139], v[74:75], v[146:147]
	v_pk_fma_f32 v[136:137], v[136:137], v[72:73], v[144:145]
	v_pk_fma_f32 v[140:141], v[132:133], v[68:69], v[140:141]
	v_cvt_pk_f16_f32 v135, v134, v135
	v_cvt_pk_f16_f32 v133, v138, v139
	v_cvt_pk_f16_f32 v134, v140, v141
	v_cvt_pk_f16_f32 v132, v136, v137
	global_store_dwordx4 v[190:191], v[132:135], off offset:256
	s_nop 1
	v_or_b32_e32 v132, 16, v174
	v_ashrrev_i32_e32 v133, 31, v132
	v_lshlrev_b64 v[132:133], 11, v[132:133]
	v_lshl_add_u64 v[140:141], v[132:133], 0, v[172:173]
	v_lshl_add_u64 v[142:143], v[140:141], 2, s[80:81]
	s_nop 1
	s_waitcnt vmcnt(10)
	v_mov_b32_e32 v132, v216
	v_mov_b32_e32 v133, v217
	v_mov_b32_e32 v134, v218
	v_mov_b32_e32 v135, v219
	s_nop 1
	v_mov_b32_e32 v136, v220
	v_mov_b32_e32 v137, v221
	v_mov_b32_e32 v138, v222
	v_mov_b32_e32 v139, v223
	s_mov_b64 s[98:99], 0x100000
	v_lshl_add_u64 v[248:249], v[198:199], 0, s[98:99]
	global_load_dwordx4 v[216:219], v[248:249], off offset:16
	global_load_dwordx4 v[220:223], v[248:249], off
	s_nop 0
	v_pk_fma_f32 v[126:127], v[126:127], v[86:87], v[134:135]
	v_pk_fma_f32 v[130:131], v[130:131], v[90:91], v[138:139]
	v_pk_fma_f32 v[128:129], v[128:129], v[88:89], v[136:137]
	v_pk_fma_f32 v[132:133], v[124:125], v[84:85], v[132:133]
	v_cvt_pk_f16_f32 v127, v126, v127
	v_cvt_pk_f16_f32 v125, v130, v131
	v_cvt_pk_f16_f32 v126, v132, v133
	v_cvt_pk_f16_f32 v124, v128, v129
	v_lshl_add_u64 v[132:133], v[140:141], 1, s[16:17]
	global_store_dwordx4 v[132:133], v[124:127], off
	s_nop 1
	s_waitcnt vmcnt(10)
	v_mov_b32_e32 v124, v224
	v_mov_b32_e32 v125, v225
	v_mov_b32_e32 v126, v226
	v_mov_b32_e32 v127, v227
	s_nop 0
	s_nop 1
	v_mov_b32_e32 v128, v228
	v_mov_b32_e32 v129, v229
	v_mov_b32_e32 v130, v230
	v_mov_b32_e32 v131, v231
	s_mov_b64 s[98:99], 0x100000
	v_lshl_add_u64 v[248:249], v[198:199], 0, s[98:99]
	global_load_dwordx4 v[224:227], v[248:249], off offset:528
	global_load_dwordx4 v[228:231], v[248:249], off offset:512
	s_nop 0
	v_pk_fma_f32 v[118:119], v[118:119], v[70:71], v[126:127]
	v_pk_fma_f32 v[122:123], v[122:123], v[74:75], v[130:131]
	v_pk_fma_f32 v[120:121], v[120:121], v[72:73], v[128:129]
	v_pk_fma_f32 v[124:125], v[116:117], v[68:69], v[124:125]
	v_cvt_pk_f16_f32 v119, v118, v119
	v_cvt_pk_f16_f32 v117, v122, v123
	v_cvt_pk_f16_f32 v118, v124, v125
	v_cvt_pk_f16_f32 v116, v120, v121
	global_store_dwordx4 v[132:133], v[116:119], off offset:256
	s_nop 1
	v_or_b32_e32 v116, 32, v174
	v_ashrrev_i32_e32 v117, 31, v116
	v_lshlrev_b64 v[116:117], 11, v[116:117]
	v_lshl_add_u64 v[124:125], v[116:117], 0, v[172:173]
	v_lshl_add_u64 v[126:127], v[124:125], 2, s[80:81]
	s_nop 1
	s_waitcnt vmcnt(10)
	v_mov_b32_e32 v116, v232
	v_mov_b32_e32 v117, v233
	v_mov_b32_e32 v118, v234
	v_mov_b32_e32 v119, v235
	s_nop 1
	v_mov_b32_e32 v120, v236
	v_mov_b32_e32 v121, v237
	v_mov_b32_e32 v122, v238
	v_mov_b32_e32 v123, v239
	s_mov_b64 s[98:99], 0x120000
	v_lshl_add_u64 v[248:249], v[198:199], 0, s[98:99]
	global_load_dwordx4 v[232:235], v[248:249], off offset:16
	global_load_dwordx4 v[236:239], v[248:249], off
	s_nop 0
	v_pk_fma_f32 v[110:111], v[110:111], v[86:87], v[118:119]
	v_pk_fma_f32 v[114:115], v[114:115], v[90:91], v[122:123]
	v_pk_fma_f32 v[112:113], v[112:113], v[88:89], v[120:121]
	v_pk_fma_f32 v[116:117], v[108:109], v[84:85], v[116:117]
	v_cvt_pk_f16_f32 v111, v110, v111
	v_cvt_pk_f16_f32 v109, v114, v115
	v_cvt_pk_f16_f32 v110, v116, v117
	v_cvt_pk_f16_f32 v108, v112, v113
	v_lshl_add_u64 v[116:117], v[124:125], 1, s[16:17]
	global_store_dwordx4 v[116:117], v[108:111], off
	s_nop 1
	s_waitcnt vmcnt(10)
	v_mov_b32_e32 v108, v240
	v_mov_b32_e32 v109, v241
	v_mov_b32_e32 v110, v242
	v_mov_b32_e32 v111, v243
	s_nop 0
	s_nop 1
	v_mov_b32_e32 v112, v244
	v_mov_b32_e32 v113, v245
	v_mov_b32_e32 v114, v246
	v_mov_b32_e32 v115, v247
	s_mov_b64 s[98:99], 0x120000
	v_lshl_add_u64 v[248:249], v[198:199], 0, s[98:99]
	global_load_dwordx4 v[240:243], v[248:249], off offset:528
	global_load_dwordx4 v[244:247], v[248:249], off offset:512
	s_nop 0
	v_pk_fma_f32 v[102:103], v[102:103], v[70:71], v[110:111]
	v_pk_fma_f32 v[106:107], v[106:107], v[74:75], v[114:115]
	v_pk_fma_f32 v[104:105], v[104:105], v[72:73], v[112:113]
	v_pk_fma_f32 v[108:109], v[100:101], v[68:69], v[108:109]
	v_cvt_pk_f16_f32 v103, v102, v103
	v_cvt_pk_f16_f32 v101, v106, v107
	v_cvt_pk_f16_f32 v102, v108, v109
	v_cvt_pk_f16_f32 v100, v104, v105
	global_store_dwordx4 v[116:117], v[100:103], off offset:256
	s_nop 1
	v_or_b32_e32 v100, 48, v174
	v_ashrrev_i32_e32 v101, 31, v100
	v_lshlrev_b64 v[100:101], 11, v[100:101]
	v_lshl_add_u64 v[108:109], v[100:101], 0, v[172:173]
	v_lshl_add_u64 v[110:111], v[108:109], 2, s[80:81]
	s_nop 1
	s_waitcnt vmcnt(10)
;     __device__ __forceinline__ void operator()(const f32x4 (&acc)[2][2][4][2], const pg8::Unit& u, int wr, int wc, int fr, int fq) const {
;     ...
;             for (int m = 0; m < 4; ++m) { const size_t ro = (size_t)(row0 + ai * 128 + m * 16) * DM + col0;
; #pragma unroll
;                 for (int bj = 0; bj < 2; ++bj) {
;                     f32x4 x0, x1;
;                     if (XF32) { x0 = *(const f32x4*)(xin + ro + bj * 128); x1 = *(const f32x4*)(xin + ro + bj * 128 + 4); }
;                     else { const h8 xh = *(const h8*)(H + ro + bj * 128); x0 = (f32x4){(float)xh[0], (float)xh[1], (float)xh[2], (float)xh[3]}; x1 = (f32x4){(float)xh[4], (float)xh[5], (float)xh[6], (float)xh[7]}; }
;                     const f32x4 y0 = x0 + gv[bj][0] * acc[ai][bj][m][0], y1 = x1 + gv[bj][1] * acc[ai][bj][m][1];
;                     h8 o; o[0] = (half_t)y0[0]; o[1] = (half_t)y0[1]; o[2] = (half_t)y0[2]; o[3] = (half_t)y0[3]; o[4] = (half_t)y1[0]; o[5] = (half_t)y1[1]; o[6] = (half_t)y1[2]; o[7] = (half_t)y1[3];
;                     *(h8*)(H + ro + bj * 128) = o; } }
	v_mov_b32_e32 v100, v200
	v_mov_b32_e32 v101, v201
	v_mov_b32_e32 v102, v202
	v_mov_b32_e32 v103, v203
	s_nop 1
	v_mov_b32_e32 v104, v204
	v_mov_b32_e32 v105, v205
	v_mov_b32_e32 v106, v206
	v_mov_b32_e32 v107, v207
	s_mov_b64 s[98:99], 0x140000
	v_lshl_add_u64 v[248:249], v[198:199], 0, s[98:99]
	global_load_dwordx4 v[200:203], v[248:249], off offset:16
	global_load_dwordx4 v[204:207], v[248:249], off
	s_nop 0
	v_pk_fma_f32 v[94:95], v[94:95], v[86:87], v[102:103]
	v_pk_fma_f32 v[98:99], v[98:99], v[90:91], v[106:107]
	v_pk_fma_f32 v[96:97], v[96:97], v[88:89], v[104:105]
	v_pk_fma_f32 v[100:101], v[92:93], v[84:85], v[100:101]
	v_cvt_pk_f16_f32 v95, v94, v95
	v_cvt_pk_f16_f32 v93, v98, v99
	v_cvt_pk_f16_f32 v94, v100, v101
	v_cvt_pk_f16_f32 v92, v96, v97
	v_lshl_add_u64 v[100:101], v[108:109], 1, s[16:17]
	global_store_dwordx4 v[100:101], v[92:95], off
	s_nop 1
	s_waitcnt vmcnt(10)
	v_mov_b32_e32 v92, v208
	v_mov_b32_e32 v93, v209
	v_mov_b32_e32 v94, v210
	v_mov_b32_e32 v95, v211
	s_nop 0
	s_nop 1
	v_mov_b32_e32 v96, v212
	v_mov_b32_e32 v97, v213
	v_mov_b32_e32 v98, v214
	v_mov_b32_e32 v99, v215
	s_mov_b64 s[98:99], 0x140000
	v_lshl_add_u64 v[248:249], v[198:199], 0, s[98:99]
	global_load_dwordx4 v[208:211], v[248:249], off offset:528
	global_load_dwordx4 v[212:215], v[248:249], off offset:512
	s_nop 0
	v_pk_fma_f32 v[78:79], v[78:79], v[70:71], v[94:95]
	v_pk_fma_f32 v[82:83], v[82:83], v[74:75], v[98:99]
	v_pk_fma_f32 v[80:81], v[80:81], v[72:73], v[96:97]
	v_pk_fma_f32 v[92:93], v[76:77], v[68:69], v[92:93]
	v_cvt_pk_f16_f32 v79, v78, v79
	v_cvt_pk_f16_f32 v77, v82, v83
	v_cvt_pk_f16_f32 v78, v92, v93
	v_cvt_pk_f16_f32 v76, v80, v81
	v_lshl_add_u64 v[92:93], v[170:171], 0, s[12:13]
	global_store_dwordx4 v[100:101], v[76:79], off offset:256
	v_lshl_add_u64 v[94:95], v[92:93], 2, s[80:81]
	s_nop 1
	s_waitcnt vmcnt(10)
	v_mov_b32_e32 v76, v216
	v_mov_b32_e32 v77, v217
	v_mov_b32_e32 v78, v218
	v_mov_b32_e32 v79, v219
	s_nop 1
	v_mov_b32_e32 v80, v220
	v_mov_b32_e32 v81, v221
	v_mov_b32_e32 v82, v222
	v_mov_b32_e32 v83, v223
	s_mov_b64 s[98:99], 0x160000
	v_lshl_add_u64 v[248:249], v[198:199], 0, s[98:99]
	global_load_dwordx4 v[216:219], v[248:249], off offset:16
	global_load_dwordx4 v[220:223], v[248:249], off
	s_mov_b64 s[12:13], 0x48000
	s_nop 0
	v_pk_fma_f32 v[62:63], v[62:63], v[86:87], v[78:79]
	v_pk_fma_f32 v[66:67], v[66:67], v[90:91], v[82:83]
	v_pk_fma_f32 v[64:65], v[64:65], v[88:89], v[80:81]
	v_pk_fma_f32 v[76:77], v[60:61], v[84:85], v[76:77]
	v_cvt_pk_f16_f32 v63, v62, v63
	v_cvt_pk_f16_f32 v61, v66, v67
	v_cvt_pk_f16_f32 v62, v76, v77
	v_cvt_pk_f16_f32 v60, v64, v65
	v_lshl_add_u64 v[76:77], v[92:93], 1, s[16:17]
	global_store_dwordx4 v[76:77], v[60:63], off
	s_nop 1
	s_waitcnt vmcnt(10)
	v_mov_b32_e32 v60, v224
	v_mov_b32_e32 v61, v225
	v_mov_b32_e32 v62, v226
	v_mov_b32_e32 v63, v227
	s_nop 0
	s_nop 1
	v_mov_b32_e32 v64, v228
	v_mov_b32_e32 v65, v229
	v_mov_b32_e32 v66, v230
	v_mov_b32_e32 v67, v231
	s_mov_b64 s[98:99], 0x160000
	v_lshl_add_u64 v[248:249], v[198:199], 0, s[98:99]
	global_load_dwordx4 v[224:227], v[248:249], off offset:528
	global_load_dwordx4 v[228:231], v[248:249], off offset:512
	s_nop 0
	v_pk_fma_f32 v[54:55], v[54:55], v[70:71], v[62:63]
	v_pk_fma_f32 v[58:59], v[58:59], v[74:75], v[66:67]
	v_pk_fma_f32 v[56:57], v[56:57], v[72:73], v[64:65]
	v_pk_fma_f32 v[60:61], v[52:53], v[68:69], v[60:61]
	v_cvt_pk_f16_f32 v55, v54, v55
	v_cvt_pk_f16_f32 v53, v58, v59
	v_cvt_pk_f16_f32 v54, v60, v61
	v_cvt_pk_f16_f32 v52, v56, v57
	v_lshl_add_u64 v[60:61], v[170:171], 0, s[12:13]
	global_store_dwordx4 v[76:77], v[52:55], off offset:256
	v_lshl_add_u64 v[62:63], v[60:61], 2, s[80:81]
	s_nop 1
	s_waitcnt vmcnt(10)
	v_mov_b32_e32 v52, v232
	v_mov_b32_e32 v53, v233
	v_mov_b32_e32 v54, v234
	v_mov_b32_e32 v55, v235
	s_nop 1
	v_mov_b32_e32 v56, v236
	v_mov_b32_e32 v57, v237
	v_mov_b32_e32 v58, v238
	v_mov_b32_e32 v59, v239
	s_mov_b64 s[12:13], 0x50000
	s_nop 0
	v_pk_fma_f32 v[46:47], v[46:47], v[86:87], v[54:55]
	v_pk_fma_f32 v[50:51], v[50:51], v[90:91], v[58:59]
	v_pk_fma_f32 v[48:49], v[48:49], v[88:89], v[56:57]
	v_pk_fma_f32 v[52:53], v[44:45], v[84:85], v[52:53]
	v_cvt_pk_f16_f32 v47, v46, v47
	v_cvt_pk_f16_f32 v45, v50, v51
	v_cvt_pk_f16_f32 v46, v52, v53
	v_cvt_pk_f16_f32 v44, v48, v49
	v_lshl_add_u64 v[52:53], v[60:61], 1, s[16:17]
	global_store_dwordx4 v[52:53], v[44:47], off
	s_nop 1
	s_waitcnt vmcnt(8)
; #define PG8_WAIT_V(n) asm volatile("s_waitcnt vmcnt(" #n ")" ::: "memory")
; #define PG8_BAR __builtin_amdgcn_s_barrier()
; template <class Epi>
; __device__ __forceinline__ void gemm_phase(LAS unsigned char* lds, const Gemm g, const StaticOrder& S, const Epi& E, const int tid) {
;     ...
;         if (!has_next) break;
; #pragma unroll
;         for (int a = 0; a < 2; ++a)
; #pragma unroll
;             for (int b = 0; b < 2; ++b)
; #pragma unroll
;                 for (int m = 0; m < 4; ++m)
; #pragma unroll
;                     for (int n = 0; n < 2; ++n) acc[a][b][m][n] = (f32x4){0.f, 0.f, 0.f, 0.f};
;         cur = nxt; cA = nA; cB = nB; ++ui;
;     }
;     PG8_WAIT_V(0);
;     if (wr == 0) PG8_BAR;
;     PG8_BAR;
;     __device__ __forceinline__ void operator()(const f32x4 (&acc)[2][2][4][2], const pg8::Unit& u, int wr, int wc, int fr, int fq) const {
;     ...
;             for (int m = 0; m < 4; ++m) { const size_t ro = (size_t)(row0 + ai * 128 + m * 16) * DM + col0;
; #pragma unroll
;                 for (int bj = 0; bj < 2; ++bj) {
;                     f32x4 x0, x1;
;                     if (XF32) { x0 = *(const f32x4*)(xin + ro + bj * 128); x1 = *(const f32x4*)(xin + ro + bj * 128 + 4); }
;                     else { const h8 xh = *(const h8*)(H + ro + bj * 128); x0 = (f32x4){(float)xh[0], (float)xh[1], (float)xh[2], (float)xh[3]}; x1 = (f32x4){(float)xh[4], (float)xh[5], (float)xh[6], (float)xh[7]}; }
;                     const f32x4 y0 = x0 + gv[bj][0] * acc[ai][bj][m][0], y1 = x1 + gv[bj][1] * acc[ai][bj][m][1];
;                     h8 o; o[0] = (half_t)y0[0]; o[1] = (half_t)y0[1]; o[2] = (half_t)y0[2]; o[3] = (half_t)y0[3]; o[4] = (half_t)y1[0]; o[5] = (half_t)y1[1]; o[6] = (half_t)y1[2]; o[7] = (half_t)y1[3];
;                     *(h8*)(H + ro + bj * 128) = o; } }
	v_mov_b32_e32 v44, v240
	v_mov_b32_e32 v45, v241
	v_mov_b32_e32 v46, v242
	v_mov_b32_e32 v47, v243
	s_nop 0
	s_nop 1
	v_mov_b32_e32 v48, v244
	v_mov_b32_e32 v49, v245
	v_mov_b32_e32 v50, v246
	v_mov_b32_e32 v51, v247
	s_nop 0
	v_pk_fma_f32 v[38:39], v[38:39], v[70:71], v[46:47]
	v_pk_fma_f32 v[42:43], v[42:43], v[74:75], v[50:51]
	v_pk_fma_f32 v[40:41], v[40:41], v[72:73], v[48:49]
	v_pk_fma_f32 v[44:45], v[36:37], v[68:69], v[44:45]
	v_cvt_pk_f16_f32 v39, v38, v39
	v_cvt_pk_f16_f32 v37, v42, v43
	v_cvt_pk_f16_f32 v38, v44, v45
	v_cvt_pk_f16_f32 v36, v40, v41
	v_lshl_add_u64 v[44:45], v[170:171], 0, s[12:13]
	global_store_dwordx4 v[52:53], v[36:39], off offset:256
	v_lshl_add_u64 v[46:47], v[44:45], 2, s[80:81]
	s_nop 1
	s_waitcnt vmcnt(6)
	v_mov_b32_e32 v36, v200
	v_mov_b32_e32 v37, v201
	v_mov_b32_e32 v38, v202
	v_mov_b32_e32 v39, v203
	s_nop 1
	v_mov_b32_e32 v40, v204
	v_mov_b32_e32 v41, v205
	v_mov_b32_e32 v42, v206
	v_mov_b32_e32 v43, v207
	s_mov_b64 s[12:13], 0x58000
	s_nop 0
	v_pk_fma_f32 v[30:31], v[30:31], v[86:87], v[38:39]
	v_pk_fma_f32 v[34:35], v[34:35], v[90:91], v[42:43]
	v_pk_fma_f32 v[32:33], v[32:33], v[88:89], v[40:41]
	v_pk_fma_f32 v[36:37], v[28:29], v[84:85], v[36:37]
	v_cvt_pk_f16_f32 v31, v30, v31
	v_cvt_pk_f16_f32 v29, v34, v35
	v_cvt_pk_f16_f32 v30, v36, v37
	v_cvt_pk_f16_f32 v28, v32, v33
	v_lshl_add_u64 v[36:37], v[44:45], 1, s[16:17]
	global_store_dwordx4 v[36:37], v[28:31], off
	s_nop 1
	s_waitcnt vmcnt(4)
	v_mov_b32_e32 v28, v208
	v_mov_b32_e32 v29, v209
	v_mov_b32_e32 v30, v210
	v_mov_b32_e32 v31, v211
	s_nop 0
	s_nop 1
	v_mov_b32_e32 v32, v212
	v_mov_b32_e32 v33, v213
	v_mov_b32_e32 v34, v214
	v_mov_b32_e32 v35, v215
	s_nop 0
	v_pk_fma_f32 v[22:23], v[22:23], v[70:71], v[30:31]
	v_pk_fma_f32 v[26:27], v[26:27], v[74:75], v[34:35]
	v_pk_fma_f32 v[24:25], v[24:25], v[72:73], v[32:33]
	v_pk_fma_f32 v[28:29], v[20:21], v[68:69], v[28:29]
	v_cvt_pk_f16_f32 v23, v22, v23
	v_cvt_pk_f16_f32 v21, v26, v27
	v_cvt_pk_f16_f32 v22, v28, v29
	v_cvt_pk_f16_f32 v20, v24, v25
	v_lshl_add_u64 v[28:29], v[170:171], 0, s[12:13]
	global_store_dwordx4 v[36:37], v[20:23], off offset:256
	v_lshl_add_u64 v[30:31], v[28:29], 2, s[80:81]
	s_nop 1
	s_waitcnt vmcnt(2)
	v_mov_b32_e32 v20, v216
	v_mov_b32_e32 v21, v217
	v_mov_b32_e32 v22, v218
	v_mov_b32_e32 v23, v219
	s_nop 1
	v_mov_b32_e32 v24, v220
	v_mov_b32_e32 v25, v221
	v_mov_b32_e32 v26, v222
	v_mov_b32_e32 v27, v223
	s_mov_b64 s[12:13], s[8:9]
	s_nop 0
	v_pk_fma_f32 v[14:15], v[14:15], v[86:87], v[22:23]
	v_pk_fma_f32 v[18:19], v[18:19], v[90:91], v[26:27]
	v_pk_fma_f32 v[16:17], v[16:17], v[88:89], v[24:25]
	v_pk_fma_f32 v[20:21], v[12:13], v[84:85], v[20:21]
	v_cvt_pk_f16_f32 v15, v14, v15
	v_cvt_pk_f16_f32 v13, v18, v19
	v_cvt_pk_f16_f32 v14, v20, v21
	v_cvt_pk_f16_f32 v12, v16, v17
	v_lshl_add_u64 v[20:21], v[28:29], 1, s[16:17]
	global_store_dwordx4 v[20:21], v[12:15], off
	s_nop 1
	s_waitcnt vmcnt(0)
	v_mov_b32_e32 v12, v224
	v_mov_b32_e32 v13, v225
	v_mov_b32_e32 v14, v226
	v_mov_b32_e32 v15, v227
	s_nop 0
	s_nop 1
	v_mov_b32_e32 v16, v228
	v_mov_b32_e32 v17, v229
	v_mov_b32_e32 v18, v230
	v_mov_b32_e32 v19, v231
	s_nop 0
	v_pk_fma_f32 v[6:7], v[6:7], v[70:71], v[14:15]
	v_pk_fma_f32 v[10:11], v[10:11], v[74:75], v[18:19]
	v_pk_fma_f32 v[8:9], v[8:9], v[72:73], v[16:17]
	v_pk_fma_f32 v[12:13], v[4:5], v[68:69], v[12:13]
	v_cvt_pk_f16_f32 v7, v6, v7
	v_cvt_pk_f16_f32 v5, v10, v11
	v_cvt_pk_f16_f32 v6, v12, v13
	v_cvt_pk_f16_f32 v4, v8, v9
	global_store_dwordx4 v[20:21], v[4:7], off offset:256
	s_cbranch_vccz .LBB0_671
	s_waitcnt vmcnt(0)
	v_readlane_b32 s42, v251, 7
	v_readlane_b32 s46, v251, 9
	v_readlane_b32 s48, v251, 13
	s_cmpk_gt_u32 s25, 0xff
	v_readlane_b32 s43, v251, 8
	v_readlane_b32 s47, v251, 10
	v_readlane_b32 s49, v251, 14
	s_cbranch_scc1 .LBB0_682
	s_barrier
